# weight conversion loops (7 of 11): unrolled by two tiles with a second register set, the loads of tile t+2 issued right after the stores of tile t (two tiles of loads in flight)
# speedup vs baseline: 1.0054x; 1.0003x over previous
; __device__ __forceinline__ bf16_t f2bf(float f) { unsigned u = __float_as_uint(f); u += 0x7FFFu + ((u >> 16) & 1u); return (bf16_t)(u >> 16); }
;     ...
;     for (int t_ = first; t_ < ntile * ((REP & 1) + 1); t_ += gridDim.x) { const int t = t_ % ntile;
;         const int r0 = (t / nkt) * 64, k0 = (t % nkt) * 64;
;         __syncthreads();
; #pragma unroll
;         for (int i = 0; i < 8; ++i) { const int kk = i * 8 + w; tile[kk * 65 + lane] = src(k0 + kk, r0 + lane); }
;         __syncthreads();
; #pragma unroll
;         for (int i = 0; i < 8; ++i) { const int j = i * 8 + w; Bt[(size_t)(r0 + j) * ld + k0 + lane] = f2bf(tile[lane * 65 + j]); }
;     }
; __device__ void convert_phase(unsigned char* smem, const Params& p, int l) {
;     ...
;       conv_tiles(tile, wt + W_UP1, 5632, 1024, 0, [=](int k, int r) { const int col = (r >> 5) * 16 + (r & 15); return gn[k] * (((r >> 4) & 1) ? wu[(size_t)k * DFF + col] : wg[(size_t)k * DFF + col]); }); }
.LBB0_307:
	s_mov_b32 s98, s11
	s_mul_hi_i32 s8, s98, 0x2e8ba2e9
	s_lshr_b32 s9, s8, 31
	s_ashr_i32 s8, s8, 8
	s_add_i32 s8, s8, s9
	s_mulk_i32 s8, 0x580
	s_sub_i32 s8, s98, s8
	s_sext_i32_i16 s9, s8
	s_bfe_u32 s9, s9, 0x4001b
	s_add_i32 s9, s8, s9
	s_sext_i32_i16 s16, s9
	s_and_b32 s9, s9, 0xfff0
	s_lshl_b32 s16, s16, 2
	s_sub_i32 s8, s8, s9
	s_and_b32 s9, s16, 0xffffffc0
	v_or_b32_e32 v16, s9, v4
	s_sext_i32_i16 s8, s8
	v_ashrrev_i32_e32 v17, 1, v16
	s_lshl_b32 s8, s8, 6
	v_and_or_b32 v18, v17, -16, v6
	v_add_u32_e32 v16, s8, v5
	v_ashrrev_i32_e32 v19, 31, v18
	v_ashrrev_i32_e32 v17, 31, v16
	v_lshl_add_u64 v[18:19], v[18:19], 2, v[0:1]
	v_add_u32_e32 v22, s8, v8
	v_add_u32_e32 v23, s8, v9
	v_add_u32_e32 v24, s8, v10
	v_add_u32_e32 v26, s8, v11
	v_add_u32_e32 v28, s8, v12
	v_add_u32_e32 v30, s8, v13
	v_add_u32_e32 v32, s8, v14
	v_lshl_add_u64 v[20:21], v[16:17], 2, s[6:7]
	v_mad_i64_i32 v[16:17], s[16:17], v16, s33, v[18:19]
	global_load_dword v34, v[20:21], off
	global_load_dword v35, v[20:21], off offset:32
	global_load_dword v36, v[20:21], off offset:64
	global_load_dword v37, v[20:21], off offset:96
	global_load_dword v38, v[20:21], off offset:128
	global_load_dword v39, v[20:21], off offset:160
	global_load_dword v40, v[20:21], off offset:192
	global_load_dword v41, v[20:21], off offset:224
	v_mad_i64_i32 v[20:21], s[16:17], v22, s33, v[18:19]
	v_mad_i64_i32 v[22:23], s[16:17], v23, s33, v[18:19]
	v_mad_i64_i32 v[24:25], s[16:17], v24, s33, v[18:19]
	v_mad_i64_i32 v[26:27], s[16:17], v26, s33, v[18:19]
	v_mad_i64_i32 v[28:29], s[16:17], v28, s33, v[18:19]
	v_mad_i64_i32 v[30:31], s[16:17], v30, s33, v[18:19]
	v_mad_i64_i32 v[18:19], s[16:17], v32, s33, v[18:19]
	global_load_dword v42, v[16:17], off
	global_load_dword v43, v[20:21], off
	global_load_dword v44, v[22:23], off
	global_load_dword v45, v[24:25], off
	global_load_dword v46, v[26:27], off
	global_load_dword v47, v[28:29], off
	global_load_dword v48, v[30:31], off
	global_load_dword v49, v[18:19], off
	v_add_u32_e32 v16, s9, v5
	v_add_u32_e32 v18, s9, v8
	v_add_u32_e32 v20, s9, v9
	v_add_u32_e32 v22, s9, v10
	v_add_u32_e32 v24, s9, v11
	v_add_u32_e32 v26, s9, v12
	v_add_u32_e32 v28, s9, v13
	v_add_u32_e32 v30, s9, v14
	s_ashr_i32 s9, s8, 31
	v_ashrrev_i32_e32 v17, 31, v16
	v_ashrrev_i32_e32 v19, 31, v18
	v_ashrrev_i32_e32 v21, 31, v20
	v_ashrrev_i32_e32 v23, 31, v22
	v_ashrrev_i32_e32 v25, 31, v24
	v_ashrrev_i32_e32 v27, 31, v26
	v_ashrrev_i32_e32 v29, 31, v28
	v_ashrrev_i32_e32 v31, 31, v30
	v_lshl_add_u64 v[32:33], s[8:9], 1, v[2:3]
	v_lshlrev_b64 v[16:17], 11, v[16:17]
	v_lshlrev_b64 v[18:19], 11, v[18:19]
	v_lshlrev_b64 v[20:21], 11, v[20:21]
	v_lshlrev_b64 v[22:23], 11, v[22:23]
	v_lshlrev_b64 v[24:25], 11, v[24:25]
	v_lshlrev_b64 v[26:27], 11, v[26:27]
	v_lshlrev_b64 v[28:29], 11, v[28:29]
	v_lshlrev_b64 v[30:31], 11, v[30:31]
	v_lshl_add_u64 v[16:17], v[32:33], 0, v[16:17]
	v_lshl_add_u64 v[18:19], v[32:33], 0, v[18:19]
	v_lshl_add_u64 v[20:21], v[32:33], 0, v[20:21]
	v_lshl_add_u64 v[22:23], v[32:33], 0, v[22:23]
	v_lshl_add_u64 v[24:25], v[32:33], 0, v[24:25]
	v_lshl_add_u64 v[26:27], v[32:33], 0, v[26:27]
	v_lshl_add_u64 v[28:29], v[32:33], 0, v[28:29]
	v_lshl_add_u64 v[30:31], v[32:33], 0, v[30:31]
	s_add_i32 s98, s11, s5
	s_cmp_lt_i32 s98, 0x580
	s_cbranch_scc0 .Lcv307_p1skip
	s_mul_hi_i32 s8, s98, 0x2e8ba2e9
	s_lshr_b32 s9, s8, 31
	s_ashr_i32 s8, s8, 8
	s_add_i32 s8, s8, s9
	s_mulk_i32 s8, 0x580
	s_sub_i32 s8, s98, s8
	s_sext_i32_i16 s9, s8
	s_bfe_u32 s9, s9, 0x4001b
	s_add_i32 s9, s8, s9
	s_sext_i32_i16 s16, s9
	s_and_b32 s9, s9, 0xfff0
	s_lshl_b32 s16, s16, 2
	s_sub_i32 s8, s8, s9
	s_and_b32 s9, s16, 0xffffffc0
	v_or_b32_e32 v56, s9, v4
	s_sext_i32_i16 s8, s8
	v_ashrrev_i32_e32 v57, 1, v56
	s_lshl_b32 s8, s8, 6
	v_and_or_b32 v58, v57, -16, v6
	v_add_u32_e32 v56, s8, v5
	v_ashrrev_i32_e32 v59, 31, v58
	v_ashrrev_i32_e32 v57, 31, v56
	v_lshl_add_u64 v[58:59], v[58:59], 2, v[0:1]
	v_add_u32_e32 v62, s8, v8
	v_add_u32_e32 v63, s8, v9
	v_add_u32_e32 v64, s8, v10
	v_add_u32_e32 v66, s8, v11
	v_add_u32_e32 v68, s8, v12
	v_add_u32_e32 v70, s8, v13
	v_add_u32_e32 v72, s8, v14
	v_lshl_add_u64 v[60:61], v[56:57], 2, s[6:7]
	v_mad_i64_i32 v[56:57], s[16:17], v56, s33, v[58:59]
	global_load_dword v74, v[60:61], off
	global_load_dword v75, v[60:61], off offset:32
	global_load_dword v76, v[60:61], off offset:64
	global_load_dword v77, v[60:61], off offset:96
	global_load_dword v78, v[60:61], off offset:128
	global_load_dword v79, v[60:61], off offset:160
	global_load_dword v80, v[60:61], off offset:192
	global_load_dword v81, v[60:61], off offset:224
	v_mad_i64_i32 v[60:61], s[16:17], v62, s33, v[58:59]
	v_mad_i64_i32 v[62:63], s[16:17], v63, s33, v[58:59]
	v_mad_i64_i32 v[64:65], s[16:17], v64, s33, v[58:59]
	v_mad_i64_i32 v[66:67], s[16:17], v66, s33, v[58:59]
	v_mad_i64_i32 v[68:69], s[16:17], v68, s33, v[58:59]
	v_mad_i64_i32 v[70:71], s[16:17], v70, s33, v[58:59]
	v_mad_i64_i32 v[58:59], s[16:17], v72, s33, v[58:59]
	global_load_dword v82, v[56:57], off
	global_load_dword v83, v[60:61], off
	global_load_dword v84, v[62:63], off
	global_load_dword v85, v[64:65], off
	global_load_dword v86, v[66:67], off
	global_load_dword v87, v[68:69], off
	global_load_dword v88, v[70:71], off
	global_load_dword v89, v[58:59], off
	v_add_u32_e32 v56, s9, v5
	v_add_u32_e32 v58, s9, v8
	v_add_u32_e32 v60, s9, v9
	v_add_u32_e32 v62, s9, v10
	v_add_u32_e32 v64, s9, v11
	v_add_u32_e32 v66, s9, v12
	v_add_u32_e32 v68, s9, v13
	v_add_u32_e32 v70, s9, v14
	s_ashr_i32 s9, s8, 31
	v_ashrrev_i32_e32 v57, 31, v56
	v_ashrrev_i32_e32 v59, 31, v58
	v_ashrrev_i32_e32 v61, 31, v60
	v_ashrrev_i32_e32 v63, 31, v62
	v_ashrrev_i32_e32 v65, 31, v64
	v_ashrrev_i32_e32 v67, 31, v66
	v_ashrrev_i32_e32 v69, 31, v68
	v_ashrrev_i32_e32 v71, 31, v70
	v_lshl_add_u64 v[72:73], s[8:9], 1, v[2:3]
	v_lshlrev_b64 v[56:57], 11, v[56:57]
	v_lshlrev_b64 v[58:59], 11, v[58:59]
	v_lshlrev_b64 v[60:61], 11, v[60:61]
	v_lshlrev_b64 v[62:63], 11, v[62:63]
	v_lshlrev_b64 v[64:65], 11, v[64:65]
	v_lshlrev_b64 v[66:67], 11, v[66:67]
	v_lshlrev_b64 v[68:69], 11, v[68:69]
	v_lshlrev_b64 v[70:71], 11, v[70:71]
	v_lshl_add_u64 v[56:57], v[72:73], 0, v[56:57]
	v_lshl_add_u64 v[58:59], v[72:73], 0, v[58:59]
	v_lshl_add_u64 v[60:61], v[72:73], 0, v[60:61]
	v_lshl_add_u64 v[62:63], v[72:73], 0, v[62:63]
	v_lshl_add_u64 v[64:65], v[72:73], 0, v[64:65]
	v_lshl_add_u64 v[66:67], v[72:73], 0, v[66:67]
	v_lshl_add_u64 v[68:69], v[72:73], 0, v[68:69]
	v_lshl_add_u64 v[70:71], v[72:73], 0, v[70:71]
	s_waitcnt vmcnt(16)
	s_branch .Lcv307_top

; __device__ __forceinline__ bf16_t f2bf(float f) { unsigned u = __float_as_uint(f); u += 0x7FFFu + ((u >> 16) & 1u); return (bf16_t)(u >> 16); }
;     ...
;     for (int t_ = first; t_ < ntile * ((REP & 1) + 1); t_ += gridDim.x) { const int t = t_ % ntile;
;         const int r0 = (t / nkt) * 64, k0 = (t % nkt) * 64;
;         __syncthreads();
; #pragma unroll
;         for (int i = 0; i < 8; ++i) { const int kk = i * 8 + w; tile[kk * 65 + lane] = src(k0 + kk, r0 + lane); }
;         __syncthreads();
; #pragma unroll
;         for (int i = 0; i < 8; ++i) { const int j = i * 8 + w; Bt[(size_t)(r0 + j) * ld + k0 + lane] = f2bf(tile[lane * 65 + j]); }
; __device__ void convert_phase(unsigned char* smem, const Params& p, int l) {
;     ...
;       conv_tiles(tile, wt + W_UP1, 5632, 1024, 0, [=](int k, int r) { const int col = (r >> 5) * 16 + (r & 15); return gn[k] * (((r >> 4) & 1) ? wu[(size_t)k * DFF + col] : wg[(size_t)k * DFF + col]); }); }
.Lcv307_top:
	s_barrier
	s_waitcnt vmcnt(31)
	v_mul_f32_e32 v32, v34, v42
	s_waitcnt vmcnt(30)
	v_mul_f32_e32 v33, v35, v43
	s_waitcnt vmcnt(29)
	v_mul_f32_e32 v34, v36, v44
	s_waitcnt vmcnt(28)
	v_mul_f32_e32 v35, v37, v45
	s_waitcnt vmcnt(27)
	v_mul_f32_e32 v36, v38, v46
	s_waitcnt vmcnt(26)
	v_mul_f32_e32 v37, v39, v47
	s_waitcnt vmcnt(25)
	v_mul_f32_e32 v38, v40, v48
	s_waitcnt vmcnt(24)
	v_mul_f32_e32 v39, v41, v49
	ds_write_b32 v15, v32
	ds_write_b32 v15, v33 offset:2080
	ds_write_b32 v15, v34 offset:4160
	ds_write_b32 v15, v35 offset:6240
	ds_write_b32 v15, v36 offset:8320
	ds_write_b32 v15, v37 offset:10400
	ds_write_b32 v15, v38 offset:12480
	ds_write_b32 v15, v39 offset:14560
	s_waitcnt lgkmcnt(0)
	s_barrier
	ds_read2_b32 v[32:33], v7 offset1:8
	ds_read2_b32 v[34:35], v7 offset0:16 offset1:24
	ds_read2_b32 v[36:37], v7 offset0:32 offset1:40
	ds_read2_b32 v[38:39], v7 offset0:48 offset1:56
	s_waitcnt lgkmcnt(3)
	v_bfe_u32 v40, v32, 16, 1
	v_bfe_u32 v41, v33, 16, 1
	s_waitcnt lgkmcnt(2)
	v_bfe_u32 v42, v34, 16, 1
	v_bfe_u32 v43, v35, 16, 1
	s_waitcnt lgkmcnt(1)
	v_bfe_u32 v44, v36, 16, 1
	v_bfe_u32 v45, v37, 16, 1
	s_waitcnt lgkmcnt(0)
	v_bfe_u32 v46, v38, 16, 1
	v_bfe_u32 v47, v39, 16, 1
	v_add3_u32 v32, v32, v40, s88
	v_add3_u32 v33, v33, v41, s88
	v_add3_u32 v34, v34, v42, s88
	v_add3_u32 v35, v35, v43, s88
	v_add3_u32 v36, v36, v44, s88
	v_add3_u32 v37, v37, v45, s88
	v_add3_u32 v38, v38, v46, s88
	v_add3_u32 v39, v39, v47, s88
	global_store_short_d16_hi v[16:17], v32, off
	global_store_short_d16_hi v[18:19], v33, off
	global_store_short_d16_hi v[20:21], v34, off
	global_store_short_d16_hi v[22:23], v35, off
	global_store_short_d16_hi v[24:25], v36, off
	global_store_short_d16_hi v[26:27], v37, off
	global_store_short_d16_hi v[28:29], v38, off
	global_store_short_d16_hi v[30:31], v39, off
	s_lshl_b32 s98, s5, 1
	s_add_i32 s98, s98, s11
	s_cmp_lt_i32 s98, 0x580
	s_cbranch_scc0 .Lcv307_s0
	s_mul_hi_i32 s8, s98, 0x2e8ba2e9
	s_lshr_b32 s9, s8, 31
	s_ashr_i32 s8, s8, 8
	s_add_i32 s8, s8, s9
	s_mulk_i32 s8, 0x580
	s_sub_i32 s8, s98, s8
	s_sext_i32_i16 s9, s8
	s_bfe_u32 s9, s9, 0x4001b
	s_add_i32 s9, s8, s9
	s_sext_i32_i16 s16, s9
	s_and_b32 s9, s9, 0xfff0
	s_lshl_b32 s16, s16, 2
	s_sub_i32 s8, s8, s9
	s_and_b32 s9, s16, 0xffffffc0
	v_or_b32_e32 v16, s9, v4
	s_sext_i32_i16 s8, s8
	v_ashrrev_i32_e32 v17, 1, v16
	s_lshl_b32 s8, s8, 6
	v_and_or_b32 v18, v17, -16, v6
	v_add_u32_e32 v16, s8, v5
	v_ashrrev_i32_e32 v19, 31, v18
	v_ashrrev_i32_e32 v17, 31, v16
	v_lshl_add_u64 v[18:19], v[18:19], 2, v[0:1]
	v_add_u32_e32 v22, s8, v8
	v_add_u32_e32 v23, s8, v9
	v_add_u32_e32 v24, s8, v10
	v_add_u32_e32 v26, s8, v11
	v_add_u32_e32 v28, s8, v12
	v_add_u32_e32 v30, s8, v13
	v_add_u32_e32 v32, s8, v14
	v_lshl_add_u64 v[20:21], v[16:17], 2, s[6:7]
	v_mad_i64_i32 v[16:17], s[16:17], v16, s33, v[18:19]
	global_load_dword v34, v[20:21], off
	global_load_dword v35, v[20:21], off offset:32
	global_load_dword v36, v[20:21], off offset:64
	global_load_dword v37, v[20:21], off offset:96
	global_load_dword v38, v[20:21], off offset:128
	global_load_dword v39, v[20:21], off offset:160
	global_load_dword v40, v[20:21], off offset:192
	global_load_dword v41, v[20:21], off offset:224
	v_mad_i64_i32 v[20:21], s[16:17], v22, s33, v[18:19]
	v_mad_i64_i32 v[22:23], s[16:17], v23, s33, v[18:19]
	v_mad_i64_i32 v[24:25], s[16:17], v24, s33, v[18:19]
	v_mad_i64_i32 v[26:27], s[16:17], v26, s33, v[18:19]
	v_mad_i64_i32 v[28:29], s[16:17], v28, s33, v[18:19]
	v_mad_i64_i32 v[30:31], s[16:17], v30, s33, v[18:19]
	v_mad_i64_i32 v[18:19], s[16:17], v32, s33, v[18:19]
	global_load_dword v42, v[16:17], off
	global_load_dword v43, v[20:21], off
	global_load_dword v44, v[22:23], off
	global_load_dword v45, v[24:25], off
	global_load_dword v46, v[26:27], off
	global_load_dword v47, v[28:29], off
	global_load_dword v48, v[30:31], off
	global_load_dword v49, v[18:19], off
	v_add_u32_e32 v16, s9, v5
	v_add_u32_e32 v18, s9, v8
	v_add_u32_e32 v20, s9, v9
	v_add_u32_e32 v22, s9, v10
	v_add_u32_e32 v24, s9, v11
	v_add_u32_e32 v26, s9, v12
	v_add_u32_e32 v28, s9, v13
	v_add_u32_e32 v30, s9, v14
	s_ashr_i32 s9, s8, 31
	v_ashrrev_i32_e32 v17, 31, v16
	v_ashrrev_i32_e32 v19, 31, v18
	v_ashrrev_i32_e32 v21, 31, v20
	v_ashrrev_i32_e32 v23, 31, v22
	v_ashrrev_i32_e32 v25, 31, v24
	v_ashrrev_i32_e32 v27, 31, v26
	v_ashrrev_i32_e32 v29, 31, v28
	v_ashrrev_i32_e32 v31, 31, v30
	v_lshl_add_u64 v[32:33], s[8:9], 1, v[2:3]
	v_lshlrev_b64 v[16:17], 11, v[16:17]
	v_lshlrev_b64 v[18:19], 11, v[18:19]
	v_lshlrev_b64 v[20:21], 11, v[20:21]
	v_lshlrev_b64 v[22:23], 11, v[22:23]
	v_lshlrev_b64 v[24:25], 11, v[24:25]
	v_lshlrev_b64 v[26:27], 11, v[26:27]
	v_lshlrev_b64 v[28:29], 11, v[28:29]
	v_lshlrev_b64 v[30:31], 11, v[30:31]
	v_lshl_add_u64 v[16:17], v[32:33], 0, v[16:17]
	v_lshl_add_u64 v[18:19], v[32:33], 0, v[18:19]
	v_lshl_add_u64 v[20:21], v[32:33], 0, v[20:21]
	v_lshl_add_u64 v[22:23], v[32:33], 0, v[22:23]
	v_lshl_add_u64 v[24:25], v[32:33], 0, v[24:25]
	v_lshl_add_u64 v[26:27], v[32:33], 0, v[26:27]
	v_lshl_add_u64 v[28:29], v[32:33], 0, v[28:29]
	v_lshl_add_u64 v[30:31], v[32:33], 0, v[30:31]
	s_branch .Lcv307_n0

; __device__ __forceinline__ bf16_t f2bf(float f) { unsigned u = __float_as_uint(f); u += 0x7FFFu + ((u >> 16) & 1u); return (bf16_t)(u >> 16); }
;     ...
;     for (int t_ = first; t_ < ntile * ((REP & 1) + 1); t_ += gridDim.x) { const int t = t_ % ntile;
;         const int r0 = (t / nkt) * 64, k0 = (t % nkt) * 64;
;         __syncthreads();
; #pragma unroll
;         for (int i = 0; i < 8; ++i) { const int kk = i * 8 + w; tile[kk * 65 + lane] = src(k0 + kk, r0 + lane); }
;         __syncthreads();
; #pragma unroll
;         for (int i = 0; i < 8; ++i) { const int j = i * 8 + w; Bt[(size_t)(r0 + j) * ld + k0 + lane] = f2bf(tile[lane * 65 + j]); }
; __device__ void convert_phase(unsigned char* smem, const Params& p, int l) {
;     ...
;       conv_tiles(tile, wt + W_UP1, 5632, 1024, 0, [=](int k, int r) { const int col = (r >> 5) * 16 + (r & 15); return gn[k] * (((r >> 4) & 1) ? wu[(size_t)k * DFF + col] : wg[(size_t)k * DFF + col]); }); }
.Lcv307_n0:
	s_add_i32 s11, s11, s5
	s_cmp_lt_i32 s11, 0x580
	s_cbranch_scc0 .LBB0_308
	s_barrier
	s_waitcnt vmcnt(31)
	v_mul_f32_e32 v72, v74, v82
	s_waitcnt vmcnt(30)
	v_mul_f32_e32 v73, v75, v83
	s_waitcnt vmcnt(29)
	v_mul_f32_e32 v74, v76, v84
	s_waitcnt vmcnt(28)
	v_mul_f32_e32 v75, v77, v85
	s_waitcnt vmcnt(27)
	v_mul_f32_e32 v76, v78, v86
	s_waitcnt vmcnt(26)
	v_mul_f32_e32 v77, v79, v87
	s_waitcnt vmcnt(25)
	v_mul_f32_e32 v78, v80, v88
	s_waitcnt vmcnt(24)
	v_mul_f32_e32 v79, v81, v89
	ds_write_b32 v15, v72
	ds_write_b32 v15, v73 offset:2080
	ds_write_b32 v15, v74 offset:4160
	ds_write_b32 v15, v75 offset:6240
	ds_write_b32 v15, v76 offset:8320
	ds_write_b32 v15, v77 offset:10400
	ds_write_b32 v15, v78 offset:12480
	ds_write_b32 v15, v79 offset:14560
	s_waitcnt lgkmcnt(0)
	s_barrier
	ds_read2_b32 v[72:73], v7 offset1:8
	ds_read2_b32 v[74:75], v7 offset0:16 offset1:24
	ds_read2_b32 v[76:77], v7 offset0:32 offset1:40
	ds_read2_b32 v[78:79], v7 offset0:48 offset1:56
	s_waitcnt lgkmcnt(3)
	v_bfe_u32 v80, v72, 16, 1
	v_bfe_u32 v81, v73, 16, 1
	s_waitcnt lgkmcnt(2)
	v_bfe_u32 v82, v74, 16, 1
	v_bfe_u32 v83, v75, 16, 1
	s_waitcnt lgkmcnt(1)
	v_bfe_u32 v84, v76, 16, 1
	v_bfe_u32 v85, v77, 16, 1
	s_waitcnt lgkmcnt(0)
	v_bfe_u32 v86, v78, 16, 1
	v_bfe_u32 v87, v79, 16, 1
	v_add3_u32 v72, v72, v80, s88
	v_add3_u32 v73, v73, v81, s88
	v_add3_u32 v74, v74, v82, s88
	v_add3_u32 v75, v75, v83, s88
	v_add3_u32 v76, v76, v84, s88
	v_add3_u32 v77, v77, v85, s88
	v_add3_u32 v78, v78, v86, s88
	v_add3_u32 v79, v79, v87, s88
	global_store_short_d16_hi v[56:57], v72, off
	global_store_short_d16_hi v[58:59], v73, off
	global_store_short_d16_hi v[60:61], v74, off
	global_store_short_d16_hi v[62:63], v75, off
	global_store_short_d16_hi v[64:65], v76, off
	global_store_short_d16_hi v[66:67], v77, off
	global_store_short_d16_hi v[68:69], v78, off
	global_store_short_d16_hi v[70:71], v79, off
	s_lshl_b32 s98, s5, 1
	s_add_i32 s98, s98, s11
	s_cmp_lt_i32 s98, 0x580
	s_cbranch_scc0 .Lcv307_s1
	s_mul_hi_i32 s8, s98, 0x2e8ba2e9
	s_lshr_b32 s9, s8, 31
	s_ashr_i32 s8, s8, 8
	s_add_i32 s8, s8, s9
	s_mulk_i32 s8, 0x580
	s_sub_i32 s8, s98, s8
	s_sext_i32_i16 s9, s8
	s_bfe_u32 s9, s9, 0x4001b
	s_add_i32 s9, s8, s9
	s_sext_i32_i16 s16, s9
	s_and_b32 s9, s9, 0xfff0
	s_lshl_b32 s16, s16, 2
	s_sub_i32 s8, s8, s9
	s_and_b32 s9, s16, 0xffffffc0
	v_or_b32_e32 v56, s9, v4
	s_sext_i32_i16 s8, s8
	v_ashrrev_i32_e32 v57, 1, v56
	s_lshl_b32 s8, s8, 6
	v_and_or_b32 v58, v57, -16, v6
	v_add_u32_e32 v56, s8, v5
	v_ashrrev_i32_e32 v59, 31, v58
	v_ashrrev_i32_e32 v57, 31, v56
	v_lshl_add_u64 v[58:59], v[58:59], 2, v[0:1]
	v_add_u32_e32 v62, s8, v8
	v_add_u32_e32 v63, s8, v9
	v_add_u32_e32 v64, s8, v10
	v_add_u32_e32 v66, s8, v11
	v_add_u32_e32 v68, s8, v12
	v_add_u32_e32 v70, s8, v13
	v_add_u32_e32 v72, s8, v14
	v_lshl_add_u64 v[60:61], v[56:57], 2, s[6:7]
	v_mad_i64_i32 v[56:57], s[16:17], v56, s33, v[58:59]
	global_load_dword v74, v[60:61], off
	global_load_dword v75, v[60:61], off offset:32
	global_load_dword v76, v[60:61], off offset:64
	global_load_dword v77, v[60:61], off offset:96
	global_load_dword v78, v[60:61], off offset:128
	global_load_dword v79, v[60:61], off offset:160
	global_load_dword v80, v[60:61], off offset:192
	global_load_dword v81, v[60:61], off offset:224
	v_mad_i64_i32 v[60:61], s[16:17], v62, s33, v[58:59]
	v_mad_i64_i32 v[62:63], s[16:17], v63, s33, v[58:59]
	v_mad_i64_i32 v[64:65], s[16:17], v64, s33, v[58:59]
	v_mad_i64_i32 v[66:67], s[16:17], v66, s33, v[58:59]
	v_mad_i64_i32 v[68:69], s[16:17], v68, s33, v[58:59]
	v_mad_i64_i32 v[70:71], s[16:17], v70, s33, v[58:59]
	v_mad_i64_i32 v[58:59], s[16:17], v72, s33, v[58:59]
	global_load_dword v82, v[56:57], off
	global_load_dword v83, v[60:61], off
	global_load_dword v84, v[62:63], off
	global_load_dword v85, v[64:65], off
	global_load_dword v86, v[66:67], off
	global_load_dword v87, v[68:69], off
	global_load_dword v88, v[70:71], off
	global_load_dword v89, v[58:59], off
	v_add_u32_e32 v56, s9, v5
	v_add_u32_e32 v58, s9, v8
	v_add_u32_e32 v60, s9, v9
	v_add_u32_e32 v62, s9, v10
	v_add_u32_e32 v64, s9, v11
	v_add_u32_e32 v66, s9, v12
	v_add_u32_e32 v68, s9, v13
	v_add_u32_e32 v70, s9, v14
	s_ashr_i32 s9, s8, 31
	v_ashrrev_i32_e32 v57, 31, v56
	v_ashrrev_i32_e32 v59, 31, v58
	v_ashrrev_i32_e32 v61, 31, v60
	v_ashrrev_i32_e32 v63, 31, v62
	v_ashrrev_i32_e32 v65, 31, v64
	v_ashrrev_i32_e32 v67, 31, v66
	v_ashrrev_i32_e32 v69, 31, v68
	v_ashrrev_i32_e32 v71, 31, v70
	v_lshl_add_u64 v[72:73], s[8:9], 1, v[2:3]
	v_lshlrev_b64 v[56:57], 11, v[56:57]
	v_lshlrev_b64 v[58:59], 11, v[58:59]
	v_lshlrev_b64 v[60:61], 11, v[60:61]
	v_lshlrev_b64 v[62:63], 11, v[62:63]
	v_lshlrev_b64 v[64:65], 11, v[64:65]
	v_lshlrev_b64 v[66:67], 11, v[66:67]
	v_lshlrev_b64 v[68:69], 11, v[68:69]
	v_lshlrev_b64 v[70:71], 11, v[70:71]
	v_lshl_add_u64 v[56:57], v[72:73], 0, v[56:57]
	v_lshl_add_u64 v[58:59], v[72:73], 0, v[58:59]
	v_lshl_add_u64 v[60:61], v[72:73], 0, v[60:61]
	v_lshl_add_u64 v[62:63], v[72:73], 0, v[62:63]
	v_lshl_add_u64 v[64:65], v[72:73], 0, v[64:65]
	v_lshl_add_u64 v[66:67], v[72:73], 0, v[66:67]
	v_lshl_add_u64 v[68:69], v[72:73], 0, v[68:69]
	v_lshl_add_u64 v[70:71], v[72:73], 0, v[70:71]
	s_branch .Lcv307_n1

;     ...
;     for (int t_ = first; t_ < ntile * ((REP & 1) + 1); t_ += gridDim.x) { const int t = t_ % ntile;
.Lcv307_n1:
	s_add_i32 s11, s11, s5
	s_cmp_lt_i32 s11, 0x580
	s_cbranch_scc1 .Lcv307_top

; __device__ __forceinline__ bf16_t f2bf(float f) { unsigned u = __float_as_uint(f); u += 0x7FFFu + ((u >> 16) & 1u); return (bf16_t)(u >> 16); }
;     ...
;     for (int t_ = first; t_ < ntile * ((REP & 1) + 1); t_ += gridDim.x) { const int t = t_ % ntile;
;         const int r0 = (t / nkt) * 64, k0 = (t % nkt) * 64;
;         __syncthreads();
; #pragma unroll
;         for (int i = 0; i < 8; ++i) { const int kk = i * 8 + w; tile[kk * 65 + lane] = src(k0 + kk, r0 + lane); }
;         __syncthreads();
; #pragma unroll
;         for (int i = 0; i < 8; ++i) { const int j = i * 8 + w; Bt[(size_t)(r0 + j) * ld + k0 + lane] = f2bf(tile[lane * 65 + j]); }
;     }
; __device__ void convert_phase(unsigned char* smem, const Params& p, int l) {
;     ...
;     { const float* wd = ((const float*)ldp(4)) + uo; conv_tiles(tile, wt + W_DN1, 1024, 2816, 37, [=](int k, int r) { return wd[(size_t)k * DM + r]; }); }
.LBB0_310:
	s_mov_b32 s98, s11
	s_mul_hi_i32 s8, s98, 0x2e8ba2e9
	s_lshr_b32 s9, s8, 31
	s_ashr_i32 s8, s8, 7
	s_add_i32 s8, s8, s9
	s_mulk_i32 s8, 0x2c0
	s_sub_i32 s8, s98, s8
	s_sext_i32_i16 s9, s8
	s_mulk_i32 s9, 0xba3
	s_lshr_b32 s16, s9, 31
	s_ashr_i32 s9, s9, 17
	s_add_i32 s9, s9, s16
	s_sext_i32_i16 s16, s9
	s_mul_i32 s9, s9, 44
	s_sub_i32 s8, s8, s9
	s_sext_i32_i16 s8, s8
	s_lshl_b32 s16, s16, 6
	s_lshl_b32 s8, s8, 6
	v_or_b32_e32 v14, s16, v2
	v_add_u32_e32 v16, s8, v3
	v_ashrrev_i32_e32 v15, 31, v14
	v_add_u32_e32 v18, s8, v5
	v_add_u32_e32 v20, s8, v6
	v_add_u32_e32 v22, s8, v7
	v_add_u32_e32 v24, s8, v8
	v_add_u32_e32 v26, s8, v9
	v_add_u32_e32 v28, s8, v10
	v_add_u32_e32 v30, s8, v11
	v_ashrrev_i32_e32 v17, 31, v16
	v_lshl_add_u64 v[14:15], v[14:15], 2, s[6:7]
	v_ashrrev_i32_e32 v19, 31, v18
	v_ashrrev_i32_e32 v21, 31, v20
	v_ashrrev_i32_e32 v23, 31, v22
	v_ashrrev_i32_e32 v25, 31, v24
	v_ashrrev_i32_e32 v27, 31, v26
	v_ashrrev_i32_e32 v29, 31, v28
	v_ashrrev_i32_e32 v31, 31, v30
	v_lshlrev_b64 v[16:17], 12, v[16:17]
	v_lshlrev_b64 v[18:19], 12, v[18:19]
	v_lshlrev_b64 v[20:21], 12, v[20:21]
	v_lshlrev_b64 v[22:23], 12, v[22:23]
	v_lshlrev_b64 v[24:25], 12, v[24:25]
	v_lshlrev_b64 v[26:27], 12, v[26:27]
	v_lshlrev_b64 v[28:29], 12, v[28:29]
	v_lshlrev_b64 v[30:31], 12, v[30:31]
	v_lshl_add_u64 v[16:17], v[14:15], 0, v[16:17]
	v_lshl_add_u64 v[18:19], v[14:15], 0, v[18:19]
	v_lshl_add_u64 v[20:21], v[14:15], 0, v[20:21]
	v_lshl_add_u64 v[22:23], v[14:15], 0, v[22:23]
	v_lshl_add_u64 v[24:25], v[14:15], 0, v[24:25]
	v_lshl_add_u64 v[26:27], v[14:15], 0, v[26:27]
	v_lshl_add_u64 v[28:29], v[14:15], 0, v[28:29]
	v_lshl_add_u64 v[14:15], v[14:15], 0, v[30:31]
	global_load_dword v13, v[16:17], off
	global_load_dword v30, v[18:19], off
	global_load_dword v31, v[20:21], off
	global_load_dword v32, v[22:23], off
	global_load_dword v33, v[24:25], off
	global_load_dword v34, v[26:27], off
	global_load_dword v35, v[28:29], off
	global_load_dword v36, v[14:15], off
	s_ashr_i32 s9, s8, 31
	v_add_u32_e32 v16, s16, v3
	v_add_u32_e32 v18, s16, v5
	v_add_u32_e32 v20, s16, v6
	v_add_u32_e32 v22, s16, v7
	v_add_u32_e32 v24, s16, v8
	v_add_u32_e32 v26, s16, v9
	v_add_u32_e32 v28, s16, v10
	v_add_u32_e32 v37, s16, v11
	v_lshl_add_u64 v[14:15], s[8:9], 1, v[0:1]
	v_mad_i64_i32 v[16:17], s[8:9], v16, s54, v[14:15]
	v_mad_i64_i32 v[18:19], s[8:9], v18, s54, v[14:15]
	v_mad_i64_i32 v[20:21], s[8:9], v20, s54, v[14:15]
	v_mad_i64_i32 v[22:23], s[8:9], v22, s54, v[14:15]
	v_mad_i64_i32 v[24:25], s[8:9], v24, s54, v[14:15]
	v_mad_i64_i32 v[26:27], s[8:9], v26, s54, v[14:15]
	v_mad_i64_i32 v[28:29], s[8:9], v28, s54, v[14:15]
	v_mad_i64_i32 v[14:15], s[8:9], v37, s54, v[14:15]
	s_add_i32 s98, s11, s5
	s_cmp_lt_i32 s98, 0x2c0
	s_cbranch_scc0 .Lcv310_p1skip
	s_mul_hi_i32 s8, s98, 0x2e8ba2e9
	s_lshr_b32 s9, s8, 31
	s_ashr_i32 s8, s8, 7
	s_add_i32 s8, s8, s9
	s_mulk_i32 s8, 0x2c0
	s_sub_i32 s8, s98, s8
	s_sext_i32_i16 s9, s8
	s_mulk_i32 s9, 0xba3
	s_lshr_b32 s16, s9, 31
	s_ashr_i32 s9, s9, 17
	s_add_i32 s9, s9, s16
	s_sext_i32_i16 s16, s9
	s_mul_i32 s9, s9, 44
	s_sub_i32 s8, s8, s9
	s_sext_i32_i16 s8, s8
	s_lshl_b32 s16, s16, 6
	s_lshl_b32 s8, s8, 6
	v_or_b32_e32 v54, s16, v2
	v_add_u32_e32 v56, s8, v3
	v_ashrrev_i32_e32 v55, 31, v54
	v_add_u32_e32 v58, s8, v5
	v_add_u32_e32 v60, s8, v6
	v_add_u32_e32 v62, s8, v7
	v_add_u32_e32 v64, s8, v8
	v_add_u32_e32 v66, s8, v9
	v_add_u32_e32 v68, s8, v10
	v_add_u32_e32 v70, s8, v11
	v_ashrrev_i32_e32 v57, 31, v56
	v_lshl_add_u64 v[54:55], v[54:55], 2, s[6:7]
	v_ashrrev_i32_e32 v59, 31, v58
	v_ashrrev_i32_e32 v61, 31, v60
	v_ashrrev_i32_e32 v63, 31, v62
	v_ashrrev_i32_e32 v65, 31, v64
	v_ashrrev_i32_e32 v67, 31, v66
	v_ashrrev_i32_e32 v69, 31, v68
	v_ashrrev_i32_e32 v71, 31, v70
	v_lshlrev_b64 v[56:57], 12, v[56:57]
	v_lshlrev_b64 v[58:59], 12, v[58:59]
	v_lshlrev_b64 v[60:61], 12, v[60:61]
	v_lshlrev_b64 v[62:63], 12, v[62:63]
	v_lshlrev_b64 v[64:65], 12, v[64:65]
	v_lshlrev_b64 v[66:67], 12, v[66:67]
	v_lshlrev_b64 v[68:69], 12, v[68:69]
	v_lshlrev_b64 v[70:71], 12, v[70:71]
	v_lshl_add_u64 v[56:57], v[54:55], 0, v[56:57]
	v_lshl_add_u64 v[58:59], v[54:55], 0, v[58:59]
	v_lshl_add_u64 v[60:61], v[54:55], 0, v[60:61]
	v_lshl_add_u64 v[62:63], v[54:55], 0, v[62:63]
	v_lshl_add_u64 v[64:65], v[54:55], 0, v[64:65]
	v_lshl_add_u64 v[66:67], v[54:55], 0, v[66:67]
	v_lshl_add_u64 v[68:69], v[54:55], 0, v[68:69]
	v_lshl_add_u64 v[54:55], v[54:55], 0, v[70:71]
	global_load_dword v53, v[56:57], off
	global_load_dword v70, v[58:59], off
	global_load_dword v71, v[60:61], off
	global_load_dword v72, v[62:63], off
	global_load_dword v73, v[64:65], off
	global_load_dword v74, v[66:67], off
	global_load_dword v75, v[68:69], off
	global_load_dword v76, v[54:55], off
	s_ashr_i32 s9, s8, 31
	v_add_u32_e32 v56, s16, v3
	v_add_u32_e32 v58, s16, v5
	v_add_u32_e32 v60, s16, v6
	v_add_u32_e32 v62, s16, v7
	v_add_u32_e32 v64, s16, v8
	v_add_u32_e32 v66, s16, v9
	v_add_u32_e32 v68, s16, v10
	v_add_u32_e32 v77, s16, v11
	v_lshl_add_u64 v[54:55], s[8:9], 1, v[0:1]
	v_mad_i64_i32 v[56:57], s[8:9], v56, s54, v[54:55]
	v_mad_i64_i32 v[58:59], s[8:9], v58, s54, v[54:55]
	v_mad_i64_i32 v[60:61], s[8:9], v60, s54, v[54:55]
	v_mad_i64_i32 v[62:63], s[8:9], v62, s54, v[54:55]
	v_mad_i64_i32 v[64:65], s[8:9], v64, s54, v[54:55]
	v_mad_i64_i32 v[66:67], s[8:9], v66, s54, v[54:55]
	v_mad_i64_i32 v[68:69], s[8:9], v68, s54, v[54:55]
	v_mad_i64_i32 v[54:55], s[8:9], v77, s54, v[54:55]
	s_waitcnt vmcnt(8)
	s_branch .Lcv310_top

; __device__ __forceinline__ bf16_t f2bf(float f) { unsigned u = __float_as_uint(f); u += 0x7FFFu + ((u >> 16) & 1u); return (bf16_t)(u >> 16); }
;     ...
;     for (int t_ = first; t_ < ntile * ((REP & 1) + 1); t_ += gridDim.x) { const int t = t_ % ntile;
;         const int r0 = (t / nkt) * 64, k0 = (t % nkt) * 64;
;         __syncthreads();
; #pragma unroll
;         for (int i = 0; i < 8; ++i) { const int kk = i * 8 + w; tile[kk * 65 + lane] = src(k0 + kk, r0 + lane); }
;         __syncthreads();
; #pragma unroll
;         for (int i = 0; i < 8; ++i) { const int j = i * 8 + w; Bt[(size_t)(r0 + j) * ld + k0 + lane] = f2bf(tile[lane * 65 + j]); }
; __device__ void convert_phase(unsigned char* smem, const Params& p, int l) {
;     ...
;     { const float* wd = ((const float*)ldp(4)) + uo; conv_tiles(tile, wt + W_DN1, 1024, 2816, 37, [=](int k, int r) { return wd[(size_t)k * DM + r]; }); }
.Lcv310_top:
	s_barrier
	s_waitcnt vmcnt(23)
	ds_write_b32 v12, v13
	s_waitcnt vmcnt(22)
	ds_write_b32 v12, v30 offset:2080
	s_waitcnt vmcnt(21)
	ds_write_b32 v12, v31 offset:4160
	s_waitcnt vmcnt(20)
	ds_write_b32 v12, v32 offset:6240
	s_waitcnt vmcnt(19)
	ds_write_b32 v12, v33 offset:8320
	s_waitcnt vmcnt(18)
	ds_write_b32 v12, v34 offset:10400
	s_waitcnt vmcnt(17)
	ds_write_b32 v12, v35 offset:12480
	s_waitcnt vmcnt(16)
	ds_write_b32 v12, v36 offset:14560
	s_waitcnt lgkmcnt(0)
	s_barrier
	ds_read2_b32 v[30:31], v4 offset1:8
	ds_read2_b32 v[32:33], v4 offset0:16 offset1:24
	ds_read2_b32 v[34:35], v4 offset0:32 offset1:40
	ds_read2_b32 v[36:37], v4 offset0:48 offset1:56
	s_waitcnt lgkmcnt(3)
	v_bfe_u32 v13, v30, 16, 1
	v_bfe_u32 v38, v31, 16, 1
	s_waitcnt lgkmcnt(2)
	v_bfe_u32 v39, v32, 16, 1
	v_bfe_u32 v40, v33, 16, 1
	s_waitcnt lgkmcnt(1)
	v_bfe_u32 v41, v34, 16, 1
	v_bfe_u32 v42, v35, 16, 1
	s_waitcnt lgkmcnt(0)
	v_bfe_u32 v43, v36, 16, 1
	v_bfe_u32 v44, v37, 16, 1
	v_add3_u32 v13, v30, v13, s88
	v_add3_u32 v30, v31, v38, s88
	v_add3_u32 v31, v32, v39, s88
	v_add3_u32 v32, v33, v40, s88
	v_add3_u32 v33, v34, v41, s88
	v_add3_u32 v34, v35, v42, s88
	v_add3_u32 v35, v36, v43, s88
	v_add3_u32 v36, v37, v44, s88
	global_store_short_d16_hi v[16:17], v13, off
	global_store_short_d16_hi v[18:19], v30, off
	global_store_short_d16_hi v[20:21], v31, off
	global_store_short_d16_hi v[22:23], v32, off
	global_store_short_d16_hi v[24:25], v33, off
	global_store_short_d16_hi v[26:27], v34, off
	global_store_short_d16_hi v[28:29], v35, off
	global_store_short_d16_hi v[14:15], v36, off
	s_lshl_b32 s98, s5, 1
	s_add_i32 s98, s98, s11
	s_cmp_lt_i32 s98, 0x2c0
	s_cbranch_scc0 .Lcv310_s0
	s_mul_hi_i32 s8, s98, 0x2e8ba2e9
	s_lshr_b32 s9, s8, 31
	s_ashr_i32 s8, s8, 7
	s_add_i32 s8, s8, s9
	s_mulk_i32 s8, 0x2c0
	s_sub_i32 s8, s98, s8
	s_sext_i32_i16 s9, s8
	s_mulk_i32 s9, 0xba3
	s_lshr_b32 s16, s9, 31
	s_ashr_i32 s9, s9, 17
	s_add_i32 s9, s9, s16
	s_sext_i32_i16 s16, s9
	s_mul_i32 s9, s9, 44
	s_sub_i32 s8, s8, s9
	s_sext_i32_i16 s8, s8
	s_lshl_b32 s16, s16, 6
	s_lshl_b32 s8, s8, 6
	v_or_b32_e32 v14, s16, v2
	v_add_u32_e32 v16, s8, v3
	v_ashrrev_i32_e32 v15, 31, v14
	v_add_u32_e32 v18, s8, v5
	v_add_u32_e32 v20, s8, v6
	v_add_u32_e32 v22, s8, v7
	v_add_u32_e32 v24, s8, v8
	v_add_u32_e32 v26, s8, v9
	v_add_u32_e32 v28, s8, v10
	v_add_u32_e32 v30, s8, v11
	v_ashrrev_i32_e32 v17, 31, v16
	v_lshl_add_u64 v[14:15], v[14:15], 2, s[6:7]
	v_ashrrev_i32_e32 v19, 31, v18
	v_ashrrev_i32_e32 v21, 31, v20
	v_ashrrev_i32_e32 v23, 31, v22
	v_ashrrev_i32_e32 v25, 31, v24
	v_ashrrev_i32_e32 v27, 31, v26
	v_ashrrev_i32_e32 v29, 31, v28
	v_ashrrev_i32_e32 v31, 31, v30
	v_lshlrev_b64 v[16:17], 12, v[16:17]
	v_lshlrev_b64 v[18:19], 12, v[18:19]
	v_lshlrev_b64 v[20:21], 12, v[20:21]
	v_lshlrev_b64 v[22:23], 12, v[22:23]
	v_lshlrev_b64 v[24:25], 12, v[24:25]
	v_lshlrev_b64 v[26:27], 12, v[26:27]
	v_lshlrev_b64 v[28:29], 12, v[28:29]
	v_lshlrev_b64 v[30:31], 12, v[30:31]
	v_lshl_add_u64 v[16:17], v[14:15], 0, v[16:17]
	v_lshl_add_u64 v[18:19], v[14:15], 0, v[18:19]
	v_lshl_add_u64 v[20:21], v[14:15], 0, v[20:21]
	v_lshl_add_u64 v[22:23], v[14:15], 0, v[22:23]
	v_lshl_add_u64 v[24:25], v[14:15], 0, v[24:25]
	v_lshl_add_u64 v[26:27], v[14:15], 0, v[26:27]
	v_lshl_add_u64 v[28:29], v[14:15], 0, v[28:29]
	v_lshl_add_u64 v[14:15], v[14:15], 0, v[30:31]
	global_load_dword v13, v[16:17], off
	global_load_dword v30, v[18:19], off
	global_load_dword v31, v[20:21], off
	global_load_dword v32, v[22:23], off
	global_load_dword v33, v[24:25], off
	global_load_dword v34, v[26:27], off
	global_load_dword v35, v[28:29], off
	global_load_dword v36, v[14:15], off
	s_ashr_i32 s9, s8, 31
	v_add_u32_e32 v16, s16, v3
	v_add_u32_e32 v18, s16, v5
	v_add_u32_e32 v20, s16, v6
	v_add_u32_e32 v22, s16, v7
	v_add_u32_e32 v24, s16, v8
	v_add_u32_e32 v26, s16, v9
	v_add_u32_e32 v28, s16, v10
	v_add_u32_e32 v37, s16, v11
	v_lshl_add_u64 v[14:15], s[8:9], 1, v[0:1]
	v_mad_i64_i32 v[16:17], s[8:9], v16, s54, v[14:15]
	v_mad_i64_i32 v[18:19], s[8:9], v18, s54, v[14:15]
	v_mad_i64_i32 v[20:21], s[8:9], v20, s54, v[14:15]
	v_mad_i64_i32 v[22:23], s[8:9], v22, s54, v[14:15]
	v_mad_i64_i32 v[24:25], s[8:9], v24, s54, v[14:15]
	v_mad_i64_i32 v[26:27], s[8:9], v26, s54, v[14:15]
	v_mad_i64_i32 v[28:29], s[8:9], v28, s54, v[14:15]
	v_mad_i64_i32 v[14:15], s[8:9], v37, s54, v[14:15]
	s_branch .Lcv310_n0

; __device__ __forceinline__ bf16_t f2bf(float f) { unsigned u = __float_as_uint(f); u += 0x7FFFu + ((u >> 16) & 1u); return (bf16_t)(u >> 16); }
;     ...
;     for (int t_ = first; t_ < ntile * ((REP & 1) + 1); t_ += gridDim.x) { const int t = t_ % ntile;
;         const int r0 = (t / nkt) * 64, k0 = (t % nkt) * 64;
;         __syncthreads();
; #pragma unroll
;         for (int i = 0; i < 8; ++i) { const int kk = i * 8 + w; tile[kk * 65 + lane] = src(k0 + kk, r0 + lane); }
;         __syncthreads();
; #pragma unroll
;         for (int i = 0; i < 8; ++i) { const int j = i * 8 + w; Bt[(size_t)(r0 + j) * ld + k0 + lane] = f2bf(tile[lane * 65 + j]); }
; __device__ void convert_phase(unsigned char* smem, const Params& p, int l) {
;     ...
;     { const float* wd = ((const float*)ldp(4)) + uo; conv_tiles(tile, wt + W_DN1, 1024, 2816, 37, [=](int k, int r) { return wd[(size_t)k * DM + r]; }); }
.Lcv310_n0:
	s_add_i32 s11, s11, s5
	s_cmp_lt_i32 s11, 0x2c0
	s_cbranch_scc0 .LBB0_311
	s_barrier
	s_waitcnt vmcnt(23)
	ds_write_b32 v12, v53
	s_waitcnt vmcnt(22)
	ds_write_b32 v12, v70 offset:2080
	s_waitcnt vmcnt(21)
	ds_write_b32 v12, v71 offset:4160
	s_waitcnt vmcnt(20)
	ds_write_b32 v12, v72 offset:6240
	s_waitcnt vmcnt(19)
	ds_write_b32 v12, v73 offset:8320
	s_waitcnt vmcnt(18)
	ds_write_b32 v12, v74 offset:10400
	s_waitcnt vmcnt(17)
	ds_write_b32 v12, v75 offset:12480
	s_waitcnt vmcnt(16)
	ds_write_b32 v12, v76 offset:14560
	s_waitcnt lgkmcnt(0)
	s_barrier
	ds_read2_b32 v[70:71], v4 offset1:8
	ds_read2_b32 v[72:73], v4 offset0:16 offset1:24
	ds_read2_b32 v[74:75], v4 offset0:32 offset1:40
	ds_read2_b32 v[76:77], v4 offset0:48 offset1:56
	s_waitcnt lgkmcnt(3)
	v_bfe_u32 v53, v70, 16, 1
	v_bfe_u32 v78, v71, 16, 1
	s_waitcnt lgkmcnt(2)
	v_bfe_u32 v79, v72, 16, 1
	v_bfe_u32 v80, v73, 16, 1
	s_waitcnt lgkmcnt(1)
	v_bfe_u32 v81, v74, 16, 1
	v_bfe_u32 v82, v75, 16, 1
	s_waitcnt lgkmcnt(0)
	v_bfe_u32 v83, v76, 16, 1
	v_bfe_u32 v84, v77, 16, 1
	v_add3_u32 v53, v70, v53, s88
	v_add3_u32 v70, v71, v78, s88
	v_add3_u32 v71, v72, v79, s88
	v_add3_u32 v72, v73, v80, s88
	v_add3_u32 v73, v74, v81, s88
	v_add3_u32 v74, v75, v82, s88
	v_add3_u32 v75, v76, v83, s88
	v_add3_u32 v76, v77, v84, s88
	global_store_short_d16_hi v[56:57], v53, off
	global_store_short_d16_hi v[58:59], v70, off
	global_store_short_d16_hi v[60:61], v71, off
	global_store_short_d16_hi v[62:63], v72, off
	global_store_short_d16_hi v[64:65], v73, off
	global_store_short_d16_hi v[66:67], v74, off
	global_store_short_d16_hi v[68:69], v75, off
	global_store_short_d16_hi v[54:55], v76, off
	s_lshl_b32 s98, s5, 1
	s_add_i32 s98, s98, s11
	s_cmp_lt_i32 s98, 0x2c0
	s_cbranch_scc0 .Lcv310_s1
	s_mul_hi_i32 s8, s98, 0x2e8ba2e9
	s_lshr_b32 s9, s8, 31
	s_ashr_i32 s8, s8, 7
	s_add_i32 s8, s8, s9
	s_mulk_i32 s8, 0x2c0
	s_sub_i32 s8, s98, s8
	s_sext_i32_i16 s9, s8
	s_mulk_i32 s9, 0xba3
	s_lshr_b32 s16, s9, 31
	s_ashr_i32 s9, s9, 17
	s_add_i32 s9, s9, s16
	s_sext_i32_i16 s16, s9
	s_mul_i32 s9, s9, 44
	s_sub_i32 s8, s8, s9
	s_sext_i32_i16 s8, s8
	s_lshl_b32 s16, s16, 6
	s_lshl_b32 s8, s8, 6
	v_or_b32_e32 v54, s16, v2
	v_add_u32_e32 v56, s8, v3
	v_ashrrev_i32_e32 v55, 31, v54
	v_add_u32_e32 v58, s8, v5
	v_add_u32_e32 v60, s8, v6
	v_add_u32_e32 v62, s8, v7
	v_add_u32_e32 v64, s8, v8
	v_add_u32_e32 v66, s8, v9
	v_add_u32_e32 v68, s8, v10
	v_add_u32_e32 v70, s8, v11
	v_ashrrev_i32_e32 v57, 31, v56
	v_lshl_add_u64 v[54:55], v[54:55], 2, s[6:7]
	v_ashrrev_i32_e32 v59, 31, v58
	v_ashrrev_i32_e32 v61, 31, v60
	v_ashrrev_i32_e32 v63, 31, v62
	v_ashrrev_i32_e32 v65, 31, v64
	v_ashrrev_i32_e32 v67, 31, v66
	v_ashrrev_i32_e32 v69, 31, v68
	v_ashrrev_i32_e32 v71, 31, v70
	v_lshlrev_b64 v[56:57], 12, v[56:57]
	v_lshlrev_b64 v[58:59], 12, v[58:59]
	v_lshlrev_b64 v[60:61], 12, v[60:61]
	v_lshlrev_b64 v[62:63], 12, v[62:63]
	v_lshlrev_b64 v[64:65], 12, v[64:65]
	v_lshlrev_b64 v[66:67], 12, v[66:67]
	v_lshlrev_b64 v[68:69], 12, v[68:69]
	v_lshlrev_b64 v[70:71], 12, v[70:71]
	v_lshl_add_u64 v[56:57], v[54:55], 0, v[56:57]
	v_lshl_add_u64 v[58:59], v[54:55], 0, v[58:59]
	v_lshl_add_u64 v[60:61], v[54:55], 0, v[60:61]
	v_lshl_add_u64 v[62:63], v[54:55], 0, v[62:63]
	v_lshl_add_u64 v[64:65], v[54:55], 0, v[64:65]
	v_lshl_add_u64 v[66:67], v[54:55], 0, v[66:67]
	v_lshl_add_u64 v[68:69], v[54:55], 0, v[68:69]
	v_lshl_add_u64 v[54:55], v[54:55], 0, v[70:71]
	global_load_dword v53, v[56:57], off
	global_load_dword v70, v[58:59], off
	global_load_dword v71, v[60:61], off
	global_load_dword v72, v[62:63], off
	global_load_dword v73, v[64:65], off
	global_load_dword v74, v[66:67], off
	global_load_dword v75, v[68:69], off
	global_load_dword v76, v[54:55], off
	s_ashr_i32 s9, s8, 31
	v_add_u32_e32 v56, s16, v3
	v_add_u32_e32 v58, s16, v5
	v_add_u32_e32 v60, s16, v6
	v_add_u32_e32 v62, s16, v7
	v_add_u32_e32 v64, s16, v8
	v_add_u32_e32 v66, s16, v9
	v_add_u32_e32 v68, s16, v10
	v_add_u32_e32 v77, s16, v11
	v_lshl_add_u64 v[54:55], s[8:9], 1, v[0:1]
	v_mad_i64_i32 v[56:57], s[8:9], v56, s54, v[54:55]
	v_mad_i64_i32 v[58:59], s[8:9], v58, s54, v[54:55]
	v_mad_i64_i32 v[60:61], s[8:9], v60, s54, v[54:55]
	v_mad_i64_i32 v[62:63], s[8:9], v62, s54, v[54:55]
	v_mad_i64_i32 v[64:65], s[8:9], v64, s54, v[54:55]
	v_mad_i64_i32 v[66:67], s[8:9], v66, s54, v[54:55]
	v_mad_i64_i32 v[68:69], s[8:9], v68, s54, v[54:55]
	v_mad_i64_i32 v[54:55], s[8:9], v77, s54, v[54:55]
	s_branch .Lcv310_n1

;     ...
;     for (int t_ = first; t_ < ntile * ((REP & 1) + 1); t_ += gridDim.x) { const int t = t_ % ntile;
.Lcv310_n1:
	s_add_i32 s11, s11, s5
	s_cmp_lt_i32 s11, 0x2c0
	s_cbranch_scc1 .Lcv310_top

; __device__ __forceinline__ bf16_t f2bf(float f) { unsigned u = __float_as_uint(f); u += 0x7FFFu + ((u >> 16) & 1u); return (bf16_t)(u >> 16); }
;     ...
;     for (int t_ = first; t_ < ntile * ((REP & 1) + 1); t_ += gridDim.x) { const int t = t_ % ntile;
;         const int r0 = (t / nkt) * 64, k0 = (t % nkt) * 64;
;         __syncthreads();
; #pragma unroll
;         for (int i = 0; i < 8; ++i) { const int kk = i * 8 + w; tile[kk * 65 + lane] = src(k0 + kk, r0 + lane); }
;         __syncthreads();
; #pragma unroll
;         for (int i = 0; i < 8; ++i) { const int j = i * 8 + w; Bt[(size_t)(r0 + j) * ld + k0 + lane] = f2bf(tile[lane * 65 + j]); }
;     }
; __device__ void convert_phase(unsigned char* smem, const Params& p, int l) {
;     ...
;       conv_tiles(tile, wt + W_HYRG, 2560, 1024, 71, [=](int k, int r) { const int col = r < HYC ? r : r + QKVC; return gn[k] * wi[(size_t)k * INC + col]; });
.LBB0_313:
	s_mov_b32 s98, s18
	s_mul_hi_i32 s10, s98, 0x66666667
	s_lshr_b32 s19, s10, 31
	s_ashr_i32 s10, s10, 8
	s_add_i32 s10, s10, s19
	s_mulk_i32 s10, 0x280
	s_sub_i32 s10, s98, s10
	s_sext_i32_i16 s19, s10
	s_bfe_u32 s19, s19, 0x4001b
	s_add_i32 s19, s10, s19
	s_sext_i32_i16 s20, s19
	s_and_b32 s19, s19, 0xfff0
	s_lshl_b32 s20, s20, 2
	s_sub_i32 s10, s10, s19
	s_and_b32 s19, s20, 0xffffffc0
	s_movk_i32 s11, 0x600
	v_or_b32_e32 v13, s19, v2
	s_sext_i32_i16 s10, s10
	v_add_u32_e32 v15, 0x1200, v13
	v_cmp_gt_i32_e32 vcc, s11, v13
	s_lshl_b32 s10, s10, 6
	v_add_u32_e32 v14, s10, v3
	v_cndmask_b32_e32 v16, v15, v13, vcc
	v_ashrrev_i32_e32 v17, 31, v16
	v_ashrrev_i32_e32 v15, 31, v14
	v_lshl_add_u64 v[16:17], v[16:17], 2, s[6:7]
	v_add_u32_e32 v20, s10, v5
	v_add_u32_e32 v21, s10, v6
	v_add_u32_e32 v22, s10, v7
	v_add_u32_e32 v24, s10, v8
	v_add_u32_e32 v26, s10, v9
	v_add_u32_e32 v28, s10, v10
	v_add_u32_e32 v30, s10, v11
	v_lshl_add_u64 v[18:19], v[14:15], 2, s[8:9]
	v_mad_i64_i32 v[14:15], s[20:21], v14, s94, v[16:17]
	global_load_dword v13, v[18:19], off
	global_load_dword v32, v[18:19], off offset:32
	global_load_dword v33, v[18:19], off offset:64
	global_load_dword v34, v[18:19], off offset:96
	global_load_dword v35, v[18:19], off offset:128
	global_load_dword v36, v[18:19], off offset:160
	global_load_dword v37, v[18:19], off offset:192
	global_load_dword v38, v[18:19], off offset:224
	v_mad_i64_i32 v[18:19], s[20:21], v20, s94, v[16:17]
	v_mad_i64_i32 v[20:21], s[20:21], v21, s94, v[16:17]
	v_mad_i64_i32 v[22:23], s[20:21], v22, s94, v[16:17]
	v_mad_i64_i32 v[24:25], s[20:21], v24, s94, v[16:17]
	v_mad_i64_i32 v[26:27], s[20:21], v26, s94, v[16:17]
	v_mad_i64_i32 v[28:29], s[20:21], v28, s94, v[16:17]
	v_mad_i64_i32 v[16:17], s[20:21], v30, s94, v[16:17]
	global_load_dword v39, v[14:15], off
	global_load_dword v40, v[18:19], off
	global_load_dword v41, v[20:21], off
	global_load_dword v42, v[22:23], off
	global_load_dword v43, v[24:25], off
	global_load_dword v44, v[26:27], off
	global_load_dword v45, v[28:29], off
	global_load_dword v46, v[16:17], off
	v_add_u32_e32 v14, s19, v3
	v_add_u32_e32 v16, s19, v5
	v_add_u32_e32 v18, s19, v6
	v_add_u32_e32 v20, s19, v7
	v_add_u32_e32 v22, s19, v8
	v_add_u32_e32 v24, s19, v9
	v_add_u32_e32 v26, s19, v10
	v_add_u32_e32 v28, s19, v11
	s_ashr_i32 s11, s10, 31
	v_ashrrev_i32_e32 v15, 31, v14
	v_ashrrev_i32_e32 v17, 31, v16
	v_ashrrev_i32_e32 v19, 31, v18
	v_ashrrev_i32_e32 v21, 31, v20
	v_ashrrev_i32_e32 v23, 31, v22
	v_ashrrev_i32_e32 v25, 31, v24
	v_ashrrev_i32_e32 v27, 31, v26
	v_ashrrev_i32_e32 v29, 31, v28
	v_lshl_add_u64 v[30:31], s[10:11], 1, v[0:1]
	v_lshlrev_b64 v[14:15], 11, v[14:15]
	v_lshlrev_b64 v[16:17], 11, v[16:17]
	v_lshlrev_b64 v[18:19], 11, v[18:19]
	v_lshlrev_b64 v[20:21], 11, v[20:21]
	v_lshlrev_b64 v[22:23], 11, v[22:23]
	v_lshlrev_b64 v[24:25], 11, v[24:25]
	v_lshlrev_b64 v[26:27], 11, v[26:27]
	v_lshlrev_b64 v[28:29], 11, v[28:29]
	v_lshl_add_u64 v[14:15], v[30:31], 0, v[14:15]
	v_lshl_add_u64 v[16:17], v[30:31], 0, v[16:17]
	v_lshl_add_u64 v[18:19], v[30:31], 0, v[18:19]
	v_lshl_add_u64 v[20:21], v[30:31], 0, v[20:21]
	v_lshl_add_u64 v[22:23], v[30:31], 0, v[22:23]
	v_lshl_add_u64 v[24:25], v[30:31], 0, v[24:25]
	v_lshl_add_u64 v[26:27], v[30:31], 0, v[26:27]
	v_lshl_add_u64 v[28:29], v[30:31], 0, v[28:29]
	s_add_i32 s98, s18, s5
	s_cmp_lt_i32 s98, 0x280
	s_cbranch_scc0 .Lcv313_p1skip
	s_mul_hi_i32 s10, s98, 0x66666667
	s_lshr_b32 s19, s10, 31
	s_ashr_i32 s10, s10, 8
	s_add_i32 s10, s10, s19
	s_mulk_i32 s10, 0x280
	s_sub_i32 s10, s98, s10
	s_sext_i32_i16 s19, s10
	s_bfe_u32 s19, s19, 0x4001b
	s_add_i32 s19, s10, s19
	s_sext_i32_i16 s20, s19
	s_and_b32 s19, s19, 0xfff0
	s_lshl_b32 s20, s20, 2
	s_sub_i32 s10, s10, s19
	s_and_b32 s19, s20, 0xffffffc0
	s_movk_i32 s11, 0x600
	v_or_b32_e32 v53, s19, v2
	s_sext_i32_i16 s10, s10
	v_add_u32_e32 v55, 0x1200, v53
	v_cmp_gt_i32_e32 vcc, s11, v53
	s_lshl_b32 s10, s10, 6
	v_add_u32_e32 v54, s10, v3
	v_cndmask_b32_e32 v56, v55, v53, vcc
	v_ashrrev_i32_e32 v57, 31, v56
	v_ashrrev_i32_e32 v55, 31, v54
	v_lshl_add_u64 v[56:57], v[56:57], 2, s[6:7]
	v_add_u32_e32 v60, s10, v5
	v_add_u32_e32 v61, s10, v6
	v_add_u32_e32 v62, s10, v7
	v_add_u32_e32 v64, s10, v8
	v_add_u32_e32 v66, s10, v9
	v_add_u32_e32 v68, s10, v10
	v_add_u32_e32 v70, s10, v11
	v_lshl_add_u64 v[58:59], v[54:55], 2, s[8:9]
	v_mad_i64_i32 v[54:55], s[20:21], v54, s94, v[56:57]
	global_load_dword v53, v[58:59], off
	global_load_dword v72, v[58:59], off offset:32
	global_load_dword v73, v[58:59], off offset:64
	global_load_dword v74, v[58:59], off offset:96
	global_load_dword v75, v[58:59], off offset:128
	global_load_dword v76, v[58:59], off offset:160
	global_load_dword v77, v[58:59], off offset:192
	global_load_dword v78, v[58:59], off offset:224
	v_mad_i64_i32 v[58:59], s[20:21], v60, s94, v[56:57]
	v_mad_i64_i32 v[60:61], s[20:21], v61, s94, v[56:57]
	v_mad_i64_i32 v[62:63], s[20:21], v62, s94, v[56:57]
	v_mad_i64_i32 v[64:65], s[20:21], v64, s94, v[56:57]
	v_mad_i64_i32 v[66:67], s[20:21], v66, s94, v[56:57]
	v_mad_i64_i32 v[68:69], s[20:21], v68, s94, v[56:57]
	v_mad_i64_i32 v[56:57], s[20:21], v70, s94, v[56:57]
	global_load_dword v79, v[54:55], off
	global_load_dword v80, v[58:59], off
	global_load_dword v81, v[60:61], off
	global_load_dword v82, v[62:63], off
	global_load_dword v83, v[64:65], off
	global_load_dword v84, v[66:67], off
	global_load_dword v85, v[68:69], off
	global_load_dword v86, v[56:57], off
	v_add_u32_e32 v54, s19, v3
	v_add_u32_e32 v56, s19, v5
	v_add_u32_e32 v58, s19, v6
	v_add_u32_e32 v60, s19, v7
	v_add_u32_e32 v62, s19, v8
	v_add_u32_e32 v64, s19, v9
	v_add_u32_e32 v66, s19, v10
	v_add_u32_e32 v68, s19, v11
	s_ashr_i32 s11, s10, 31
	v_ashrrev_i32_e32 v55, 31, v54
	v_ashrrev_i32_e32 v57, 31, v56
	v_ashrrev_i32_e32 v59, 31, v58
	v_ashrrev_i32_e32 v61, 31, v60
	v_ashrrev_i32_e32 v63, 31, v62
	v_ashrrev_i32_e32 v65, 31, v64
	v_ashrrev_i32_e32 v67, 31, v66
	v_ashrrev_i32_e32 v69, 31, v68
	v_lshl_add_u64 v[70:71], s[10:11], 1, v[0:1]
	v_lshlrev_b64 v[54:55], 11, v[54:55]
	v_lshlrev_b64 v[56:57], 11, v[56:57]
	v_lshlrev_b64 v[58:59], 11, v[58:59]
	v_lshlrev_b64 v[60:61], 11, v[60:61]
	v_lshlrev_b64 v[62:63], 11, v[62:63]
	v_lshlrev_b64 v[64:65], 11, v[64:65]
	v_lshlrev_b64 v[66:67], 11, v[66:67]
	v_lshlrev_b64 v[68:69], 11, v[68:69]
	v_lshl_add_u64 v[54:55], v[70:71], 0, v[54:55]
	v_lshl_add_u64 v[56:57], v[70:71], 0, v[56:57]
	v_lshl_add_u64 v[58:59], v[70:71], 0, v[58:59]
	v_lshl_add_u64 v[60:61], v[70:71], 0, v[60:61]
	v_lshl_add_u64 v[62:63], v[70:71], 0, v[62:63]
	v_lshl_add_u64 v[64:65], v[70:71], 0, v[64:65]
	v_lshl_add_u64 v[66:67], v[70:71], 0, v[66:67]
	v_lshl_add_u64 v[68:69], v[70:71], 0, v[68:69]
	s_waitcnt vmcnt(16)
	s_branch .Lcv313_top

; __device__ __forceinline__ bf16_t f2bf(float f) { unsigned u = __float_as_uint(f); u += 0x7FFFu + ((u >> 16) & 1u); return (bf16_t)(u >> 16); }
;     ...
;     for (int t_ = first; t_ < ntile * ((REP & 1) + 1); t_ += gridDim.x) { const int t = t_ % ntile;
;         const int r0 = (t / nkt) * 64, k0 = (t % nkt) * 64;
;         __syncthreads();
; #pragma unroll
;         for (int i = 0; i < 8; ++i) { const int kk = i * 8 + w; tile[kk * 65 + lane] = src(k0 + kk, r0 + lane); }
;         __syncthreads();
; #pragma unroll
;         for (int i = 0; i < 8; ++i) { const int j = i * 8 + w; Bt[(size_t)(r0 + j) * ld + k0 + lane] = f2bf(tile[lane * 65 + j]); }
; __device__ void convert_phase(unsigned char* smem, const Params& p, int l) {
;     ...
;       conv_tiles(tile, wt + W_HYRG, 2560, 1024, 71, [=](int k, int r) { const int col = r < HYC ? r : r + QKVC; return gn[k] * wi[(size_t)k * INC + col]; });
.Lcv313_top:
	s_barrier
	s_waitcnt vmcnt(31)
	v_mul_f32_e32 v13, v13, v39
	s_waitcnt vmcnt(30)
	v_mul_f32_e32 v30, v32, v40
	s_waitcnt vmcnt(29)
	v_mul_f32_e32 v31, v33, v41
	s_waitcnt vmcnt(28)
	v_mul_f32_e32 v32, v34, v42
	s_waitcnt vmcnt(27)
	v_mul_f32_e32 v33, v35, v43
	s_waitcnt vmcnt(26)
	v_mul_f32_e32 v34, v36, v44
	s_waitcnt vmcnt(25)
	v_mul_f32_e32 v35, v37, v45
	s_waitcnt vmcnt(24)
	v_mul_f32_e32 v36, v38, v46
	ds_write_b32 v12, v13
	ds_write_b32 v12, v30 offset:2080
	ds_write_b32 v12, v31 offset:4160
	ds_write_b32 v12, v32 offset:6240
	ds_write_b32 v12, v33 offset:8320
	ds_write_b32 v12, v34 offset:10400
	ds_write_b32 v12, v35 offset:12480
	ds_write_b32 v12, v36 offset:14560
	s_waitcnt lgkmcnt(0)
	s_barrier
	ds_read2_b32 v[30:31], v4 offset1:8
	ds_read2_b32 v[32:33], v4 offset0:16 offset1:24
	ds_read2_b32 v[34:35], v4 offset0:32 offset1:40
	ds_read2_b32 v[36:37], v4 offset0:48 offset1:56
	s_waitcnt lgkmcnt(3)
	v_bfe_u32 v13, v30, 16, 1
	v_bfe_u32 v38, v31, 16, 1
	s_waitcnt lgkmcnt(2)
	v_bfe_u32 v39, v32, 16, 1
	v_bfe_u32 v40, v33, 16, 1
	s_waitcnt lgkmcnt(1)
	v_bfe_u32 v41, v34, 16, 1
	v_bfe_u32 v42, v35, 16, 1
	s_waitcnt lgkmcnt(0)
	v_bfe_u32 v43, v36, 16, 1
	v_bfe_u32 v44, v37, 16, 1
	v_add3_u32 v13, v30, v13, s88
	v_add3_u32 v30, v31, v38, s88
	v_add3_u32 v31, v32, v39, s88
	v_add3_u32 v32, v33, v40, s88
	v_add3_u32 v33, v34, v41, s88
	v_add3_u32 v34, v35, v42, s88
	v_add3_u32 v35, v36, v43, s88
	v_add3_u32 v36, v37, v44, s88
	global_store_short_d16_hi v[14:15], v13, off
	global_store_short_d16_hi v[16:17], v30, off
	global_store_short_d16_hi v[18:19], v31, off
	global_store_short_d16_hi v[20:21], v32, off
	global_store_short_d16_hi v[22:23], v33, off
	global_store_short_d16_hi v[24:25], v34, off
	global_store_short_d16_hi v[26:27], v35, off
	global_store_short_d16_hi v[28:29], v36, off
	s_lshl_b32 s98, s5, 1
	s_add_i32 s98, s98, s18
	s_cmp_lt_i32 s98, 0x280
	s_cbranch_scc0 .Lcv313_s0
	s_mul_hi_i32 s10, s98, 0x66666667
	s_lshr_b32 s19, s10, 31
	s_ashr_i32 s10, s10, 8
	s_add_i32 s10, s10, s19
	s_mulk_i32 s10, 0x280
	s_sub_i32 s10, s98, s10
	s_sext_i32_i16 s19, s10
	s_bfe_u32 s19, s19, 0x4001b
	s_add_i32 s19, s10, s19
	s_sext_i32_i16 s20, s19
	s_and_b32 s19, s19, 0xfff0
	s_lshl_b32 s20, s20, 2
	s_sub_i32 s10, s10, s19
	s_and_b32 s19, s20, 0xffffffc0
	s_movk_i32 s11, 0x600
	v_or_b32_e32 v13, s19, v2
	s_sext_i32_i16 s10, s10
	v_add_u32_e32 v15, 0x1200, v13
	v_cmp_gt_i32_e32 vcc, s11, v13
	s_lshl_b32 s10, s10, 6
	v_add_u32_e32 v14, s10, v3
	v_cndmask_b32_e32 v16, v15, v13, vcc
	v_ashrrev_i32_e32 v17, 31, v16
	v_ashrrev_i32_e32 v15, 31, v14
	v_lshl_add_u64 v[16:17], v[16:17], 2, s[6:7]
	v_add_u32_e32 v20, s10, v5
	v_add_u32_e32 v21, s10, v6
	v_add_u32_e32 v22, s10, v7
	v_add_u32_e32 v24, s10, v8
	v_add_u32_e32 v26, s10, v9
	v_add_u32_e32 v28, s10, v10
	v_add_u32_e32 v30, s10, v11
	v_lshl_add_u64 v[18:19], v[14:15], 2, s[8:9]
	v_mad_i64_i32 v[14:15], s[20:21], v14, s94, v[16:17]
	global_load_dword v13, v[18:19], off
	global_load_dword v32, v[18:19], off offset:32
	global_load_dword v33, v[18:19], off offset:64
	global_load_dword v34, v[18:19], off offset:96
	global_load_dword v35, v[18:19], off offset:128
	global_load_dword v36, v[18:19], off offset:160
	global_load_dword v37, v[18:19], off offset:192
	global_load_dword v38, v[18:19], off offset:224
	v_mad_i64_i32 v[18:19], s[20:21], v20, s94, v[16:17]
	v_mad_i64_i32 v[20:21], s[20:21], v21, s94, v[16:17]
	v_mad_i64_i32 v[22:23], s[20:21], v22, s94, v[16:17]
	v_mad_i64_i32 v[24:25], s[20:21], v24, s94, v[16:17]
	v_mad_i64_i32 v[26:27], s[20:21], v26, s94, v[16:17]
	v_mad_i64_i32 v[28:29], s[20:21], v28, s94, v[16:17]
	v_mad_i64_i32 v[16:17], s[20:21], v30, s94, v[16:17]
	global_load_dword v39, v[14:15], off
	global_load_dword v40, v[18:19], off
	global_load_dword v41, v[20:21], off
	global_load_dword v42, v[22:23], off
	global_load_dword v43, v[24:25], off
	global_load_dword v44, v[26:27], off
	global_load_dword v45, v[28:29], off
	global_load_dword v46, v[16:17], off
	v_add_u32_e32 v14, s19, v3
	v_add_u32_e32 v16, s19, v5
	v_add_u32_e32 v18, s19, v6
	v_add_u32_e32 v20, s19, v7
	v_add_u32_e32 v22, s19, v8
	v_add_u32_e32 v24, s19, v9
	v_add_u32_e32 v26, s19, v10
	v_add_u32_e32 v28, s19, v11
	s_ashr_i32 s11, s10, 31
	v_ashrrev_i32_e32 v15, 31, v14
	v_ashrrev_i32_e32 v17, 31, v16
	v_ashrrev_i32_e32 v19, 31, v18
	v_ashrrev_i32_e32 v21, 31, v20
	v_ashrrev_i32_e32 v23, 31, v22
	v_ashrrev_i32_e32 v25, 31, v24
	v_ashrrev_i32_e32 v27, 31, v26
	v_ashrrev_i32_e32 v29, 31, v28
	v_lshl_add_u64 v[30:31], s[10:11], 1, v[0:1]
	v_lshlrev_b64 v[14:15], 11, v[14:15]
	v_lshlrev_b64 v[16:17], 11, v[16:17]
	v_lshlrev_b64 v[18:19], 11, v[18:19]
	v_lshlrev_b64 v[20:21], 11, v[20:21]
	v_lshlrev_b64 v[22:23], 11, v[22:23]
	v_lshlrev_b64 v[24:25], 11, v[24:25]
	v_lshlrev_b64 v[26:27], 11, v[26:27]
	v_lshlrev_b64 v[28:29], 11, v[28:29]
	v_lshl_add_u64 v[14:15], v[30:31], 0, v[14:15]
	v_lshl_add_u64 v[16:17], v[30:31], 0, v[16:17]
	v_lshl_add_u64 v[18:19], v[30:31], 0, v[18:19]
	v_lshl_add_u64 v[20:21], v[30:31], 0, v[20:21]
	v_lshl_add_u64 v[22:23], v[30:31], 0, v[22:23]
	v_lshl_add_u64 v[24:25], v[30:31], 0, v[24:25]
	v_lshl_add_u64 v[26:27], v[30:31], 0, v[26:27]
	v_lshl_add_u64 v[28:29], v[30:31], 0, v[28:29]
	s_branch .Lcv313_n0

; __device__ __forceinline__ bf16_t f2bf(float f) { unsigned u = __float_as_uint(f); u += 0x7FFFu + ((u >> 16) & 1u); return (bf16_t)(u >> 16); }
;     ...
;     for (int t_ = first; t_ < ntile * ((REP & 1) + 1); t_ += gridDim.x) { const int t = t_ % ntile;
;         const int r0 = (t / nkt) * 64, k0 = (t % nkt) * 64;
;         __syncthreads();
; #pragma unroll
;         for (int i = 0; i < 8; ++i) { const int kk = i * 8 + w; tile[kk * 65 + lane] = src(k0 + kk, r0 + lane); }
;         __syncthreads();
; #pragma unroll
;         for (int i = 0; i < 8; ++i) { const int j = i * 8 + w; Bt[(size_t)(r0 + j) * ld + k0 + lane] = f2bf(tile[lane * 65 + j]); }
; __device__ void convert_phase(unsigned char* smem, const Params& p, int l) {
;     ...
;       conv_tiles(tile, wt + W_HYRG, 2560, 1024, 71, [=](int k, int r) { const int col = r < HYC ? r : r + QKVC; return gn[k] * wi[(size_t)k * INC + col]; });
.Lcv313_n0:
	s_add_i32 s18, s18, s5
	s_cmp_lt_i32 s18, 0x280
	s_cbranch_scc0 .LBB0_314
	s_barrier
	s_waitcnt vmcnt(31)
	v_mul_f32_e32 v53, v53, v79
	s_waitcnt vmcnt(30)
	v_mul_f32_e32 v70, v72, v80
	s_waitcnt vmcnt(29)
	v_mul_f32_e32 v71, v73, v81
	s_waitcnt vmcnt(28)
	v_mul_f32_e32 v72, v74, v82
	s_waitcnt vmcnt(27)
	v_mul_f32_e32 v73, v75, v83
	s_waitcnt vmcnt(26)
	v_mul_f32_e32 v74, v76, v84
	s_waitcnt vmcnt(25)
	v_mul_f32_e32 v75, v77, v85
	s_waitcnt vmcnt(24)
	v_mul_f32_e32 v76, v78, v86
	ds_write_b32 v12, v53
	ds_write_b32 v12, v70 offset:2080
	ds_write_b32 v12, v71 offset:4160
	ds_write_b32 v12, v72 offset:6240
	ds_write_b32 v12, v73 offset:8320
	ds_write_b32 v12, v74 offset:10400
	ds_write_b32 v12, v75 offset:12480
	ds_write_b32 v12, v76 offset:14560
	s_waitcnt lgkmcnt(0)
	s_barrier
	ds_read2_b32 v[70:71], v4 offset1:8
	ds_read2_b32 v[72:73], v4 offset0:16 offset1:24
	ds_read2_b32 v[74:75], v4 offset0:32 offset1:40
	ds_read2_b32 v[76:77], v4 offset0:48 offset1:56
	s_waitcnt lgkmcnt(3)
	v_bfe_u32 v53, v70, 16, 1
	v_bfe_u32 v78, v71, 16, 1
	s_waitcnt lgkmcnt(2)
	v_bfe_u32 v79, v72, 16, 1
	v_bfe_u32 v80, v73, 16, 1
	s_waitcnt lgkmcnt(1)
	v_bfe_u32 v81, v74, 16, 1
	v_bfe_u32 v82, v75, 16, 1
	s_waitcnt lgkmcnt(0)
	v_bfe_u32 v83, v76, 16, 1
	v_bfe_u32 v84, v77, 16, 1
	v_add3_u32 v53, v70, v53, s88
	v_add3_u32 v70, v71, v78, s88
	v_add3_u32 v71, v72, v79, s88
	v_add3_u32 v72, v73, v80, s88
	v_add3_u32 v73, v74, v81, s88
	v_add3_u32 v74, v75, v82, s88
	v_add3_u32 v75, v76, v83, s88
	v_add3_u32 v76, v77, v84, s88
	global_store_short_d16_hi v[54:55], v53, off
	global_store_short_d16_hi v[56:57], v70, off
	global_store_short_d16_hi v[58:59], v71, off
	global_store_short_d16_hi v[60:61], v72, off
	global_store_short_d16_hi v[62:63], v73, off
	global_store_short_d16_hi v[64:65], v74, off
	global_store_short_d16_hi v[66:67], v75, off
	global_store_short_d16_hi v[68:69], v76, off
	s_lshl_b32 s98, s5, 1
	s_add_i32 s98, s98, s18
	s_cmp_lt_i32 s98, 0x280
	s_cbranch_scc0 .Lcv313_s1
	s_mul_hi_i32 s10, s98, 0x66666667
	s_lshr_b32 s19, s10, 31
	s_ashr_i32 s10, s10, 8
	s_add_i32 s10, s10, s19
	s_mulk_i32 s10, 0x280
	s_sub_i32 s10, s98, s10
	s_sext_i32_i16 s19, s10
	s_bfe_u32 s19, s19, 0x4001b
	s_add_i32 s19, s10, s19
	s_sext_i32_i16 s20, s19
	s_and_b32 s19, s19, 0xfff0
	s_lshl_b32 s20, s20, 2
	s_sub_i32 s10, s10, s19
	s_and_b32 s19, s20, 0xffffffc0
	s_movk_i32 s11, 0x600
	v_or_b32_e32 v53, s19, v2
	s_sext_i32_i16 s10, s10
	v_add_u32_e32 v55, 0x1200, v53
	v_cmp_gt_i32_e32 vcc, s11, v53
	s_lshl_b32 s10, s10, 6
	v_add_u32_e32 v54, s10, v3
	v_cndmask_b32_e32 v56, v55, v53, vcc
	v_ashrrev_i32_e32 v57, 31, v56
	v_ashrrev_i32_e32 v55, 31, v54
	v_lshl_add_u64 v[56:57], v[56:57], 2, s[6:7]
	v_add_u32_e32 v60, s10, v5
	v_add_u32_e32 v61, s10, v6
	v_add_u32_e32 v62, s10, v7
	v_add_u32_e32 v64, s10, v8
	v_add_u32_e32 v66, s10, v9
	v_add_u32_e32 v68, s10, v10
	v_add_u32_e32 v70, s10, v11
	v_lshl_add_u64 v[58:59], v[54:55], 2, s[8:9]
	v_mad_i64_i32 v[54:55], s[20:21], v54, s94, v[56:57]
	global_load_dword v53, v[58:59], off
	global_load_dword v72, v[58:59], off offset:32
	global_load_dword v73, v[58:59], off offset:64
	global_load_dword v74, v[58:59], off offset:96
	global_load_dword v75, v[58:59], off offset:128
	global_load_dword v76, v[58:59], off offset:160
	global_load_dword v77, v[58:59], off offset:192
	global_load_dword v78, v[58:59], off offset:224
	v_mad_i64_i32 v[58:59], s[20:21], v60, s94, v[56:57]
	v_mad_i64_i32 v[60:61], s[20:21], v61, s94, v[56:57]
	v_mad_i64_i32 v[62:63], s[20:21], v62, s94, v[56:57]
	v_mad_i64_i32 v[64:65], s[20:21], v64, s94, v[56:57]
	v_mad_i64_i32 v[66:67], s[20:21], v66, s94, v[56:57]
	v_mad_i64_i32 v[68:69], s[20:21], v68, s94, v[56:57]
	v_mad_i64_i32 v[56:57], s[20:21], v70, s94, v[56:57]
	global_load_dword v79, v[54:55], off
	global_load_dword v80, v[58:59], off
	global_load_dword v81, v[60:61], off
	global_load_dword v82, v[62:63], off
	global_load_dword v83, v[64:65], off
	global_load_dword v84, v[66:67], off
	global_load_dword v85, v[68:69], off
	global_load_dword v86, v[56:57], off
	v_add_u32_e32 v54, s19, v3
	v_add_u32_e32 v56, s19, v5
	v_add_u32_e32 v58, s19, v6
	v_add_u32_e32 v60, s19, v7
	v_add_u32_e32 v62, s19, v8
	v_add_u32_e32 v64, s19, v9
	v_add_u32_e32 v66, s19, v10
	v_add_u32_e32 v68, s19, v11
	s_ashr_i32 s11, s10, 31
	v_ashrrev_i32_e32 v55, 31, v54
	v_ashrrev_i32_e32 v57, 31, v56
	v_ashrrev_i32_e32 v59, 31, v58
	v_ashrrev_i32_e32 v61, 31, v60
	v_ashrrev_i32_e32 v63, 31, v62
	v_ashrrev_i32_e32 v65, 31, v64
	v_ashrrev_i32_e32 v67, 31, v66
	v_ashrrev_i32_e32 v69, 31, v68
	v_lshl_add_u64 v[70:71], s[10:11], 1, v[0:1]
	v_lshlrev_b64 v[54:55], 11, v[54:55]
	v_lshlrev_b64 v[56:57], 11, v[56:57]
	v_lshlrev_b64 v[58:59], 11, v[58:59]
	v_lshlrev_b64 v[60:61], 11, v[60:61]
	v_lshlrev_b64 v[62:63], 11, v[62:63]
	v_lshlrev_b64 v[64:65], 11, v[64:65]
	v_lshlrev_b64 v[66:67], 11, v[66:67]
	v_lshlrev_b64 v[68:69], 11, v[68:69]
	v_lshl_add_u64 v[54:55], v[70:71], 0, v[54:55]
	v_lshl_add_u64 v[56:57], v[70:71], 0, v[56:57]
	v_lshl_add_u64 v[58:59], v[70:71], 0, v[58:59]
	v_lshl_add_u64 v[60:61], v[70:71], 0, v[60:61]
	v_lshl_add_u64 v[62:63], v[70:71], 0, v[62:63]
	v_lshl_add_u64 v[64:65], v[70:71], 0, v[64:65]
	v_lshl_add_u64 v[66:67], v[70:71], 0, v[66:67]
	v_lshl_add_u64 v[68:69], v[70:71], 0, v[68:69]
	s_branch .Lcv313_n1

;     ...
;     for (int t_ = first; t_ < ntile * ((REP & 1) + 1); t_ += gridDim.x) { const int t = t_ % ntile;
.Lcv313_n1:
	s_add_i32 s18, s18, s5
	s_cmp_lt_i32 s18, 0x280
	s_cbranch_scc1 .Lcv313_top

; __device__ __forceinline__ bf16_t f2bf(float f) { unsigned u = __float_as_uint(f); u += 0x7FFFu + ((u >> 16) & 1u); return (bf16_t)(u >> 16); }
;     ...
;     for (int t_ = first; t_ < ntile * ((REP & 1) + 1); t_ += gridDim.x) { const int t = t_ % ntile;
;         const int r0 = (t / nkt) * 64, k0 = (t % nkt) * 64;
;         __syncthreads();
; #pragma unroll
;         for (int i = 0; i < 8; ++i) { const int kk = i * 8 + w; tile[kk * 65 + lane] = src(k0 + kk, r0 + lane); }
;         __syncthreads();
; #pragma unroll
;         for (int i = 0; i < 8; ++i) { const int j = i * 8 + w; Bt[(size_t)(r0 + j) * ld + k0 + lane] = f2bf(tile[lane * 65 + j]); }
;     }
; __device__ void convert_phase(unsigned char* smem, const Params& p, int l) {
;     ...
;       conv_tiles(tile, wt + W_QKV, 4608, 1024, 113, [=](int k, int r) { return gn[k] * wi[(size_t)k * INC + HYC + r]; }); }
.LBB0_316:
	s_mov_b32 s98, s18
	s_mul_hi_i32 s10, s98, 0x38e38e39
	s_lshr_b32 s11, s10, 31
	s_ashr_i32 s10, s10, 8
	s_add_i32 s10, s10, s11
	s_mulk_i32 s10, 0x480
	s_sub_i32 s10, s98, s10
	s_sext_i32_i16 s11, s10
	s_bfe_u32 s11, s11, 0x4001b
	s_add_i32 s11, s10, s11
	s_sext_i32_i16 s19, s11
	s_and_b32 s11, s11, 0xfff0
	s_lshl_b32 s19, s19, 2
	s_sub_i32 s10, s10, s11
	s_and_b32 s11, s19, 0xffffffc0
	s_sext_i32_i16 s10, s10
	s_lshl_b32 s10, s10, 6
	v_or_b32_e32 v16, s11, v2
	v_mov_b64_e32 v[14:15], s[6:7]
	v_ashrrev_i32_e32 v17, 31, v16
	v_add_u32_e32 v18, s10, v3
	v_add_u32_e32 v13, s10, v5
	v_add_u32_e32 v24, s10, v6
	v_add_u32_e32 v26, s10, v7
	v_add_u32_e32 v28, s10, v8
	v_add_u32_e32 v30, s10, v9
	v_add_u32_e32 v32, s10, v10
	v_add_u32_e32 v34, s10, v11
	v_mad_i64_i32 v[20:21], s[20:21], v18, s94, v[14:15]
	v_lshlrev_b64 v[16:17], 2, v[16:17]
	v_mad_i64_i32 v[22:23], s[20:21], v13, s94, v[14:15]
	v_mad_i64_i32 v[24:25], s[20:21], v24, s94, v[14:15]
	v_mad_i64_i32 v[26:27], s[20:21], v26, s94, v[14:15]
	v_mad_i64_i32 v[28:29], s[20:21], v28, s94, v[14:15]
	v_mad_i64_i32 v[30:31], s[20:21], v30, s94, v[14:15]
	v_mad_i64_i32 v[32:33], s[20:21], v32, s94, v[14:15]
	v_mad_i64_i32 v[14:15], s[20:21], v34, s94, v[14:15]
	v_lshl_add_u64 v[20:21], v[20:21], 0, v[16:17]
	v_lshl_add_u64 v[22:23], v[22:23], 0, v[16:17]
	v_lshl_add_u64 v[24:25], v[24:25], 0, v[16:17]
	v_lshl_add_u64 v[26:27], v[26:27], 0, v[16:17]
	v_lshl_add_u64 v[28:29], v[28:29], 0, v[16:17]
	v_lshl_add_u64 v[30:31], v[30:31], 0, v[16:17]
	v_lshl_add_u64 v[32:33], v[32:33], 0, v[16:17]
	v_lshl_add_u64 v[14:15], v[14:15], 0, v[16:17]
	v_add_co_u32_e32 v16, vcc, s78, v20
	v_ashrrev_i32_e32 v19, 31, v18
	s_nop 0
	v_addc_co_u32_e32 v17, vcc, 0, v21, vcc
	v_add_co_u32_e32 v20, vcc, s78, v22
	v_lshl_add_u64 v[18:19], v[18:19], 2, s[8:9]
	s_nop 0
	v_addc_co_u32_e32 v21, vcc, 0, v23, vcc
	v_add_co_u32_e32 v22, vcc, s78, v24
	s_nop 1
	v_addc_co_u32_e32 v23, vcc, 0, v25, vcc
	v_add_co_u32_e32 v24, vcc, s78, v26
	s_nop 0
	v_addc_co_u32_e32 v25, vcc, 0, v27, vcc
	v_add_co_u32_e32 v26, vcc, s78, v28
	s_nop 1
	v_addc_co_u32_e32 v27, vcc, 0, v29, vcc
	v_add_co_u32_e32 v28, vcc, s78, v30
	s_nop 0
	v_addc_co_u32_e32 v29, vcc, 0, v31, vcc
	v_add_co_u32_e32 v30, vcc, s78, v32
	s_nop 1
	v_addc_co_u32_e32 v31, vcc, 0, v33, vcc
	v_add_co_u32_e32 v14, vcc, s78, v14
	global_load_dword v13, v[18:19], off
	global_load_dword v32, v[18:19], off offset:32
	global_load_dword v33, v[18:19], off offset:64
	global_load_dword v34, v[18:19], off offset:96
	global_load_dword v35, v[18:19], off offset:128
	global_load_dword v36, v[18:19], off offset:160
	global_load_dword v37, v[18:19], off offset:192
	global_load_dword v38, v[18:19], off offset:224
	v_addc_co_u32_e32 v15, vcc, 0, v15, vcc
	global_load_dword v39, v[16:17], off offset:2048
	global_load_dword v40, v[20:21], off offset:2048
	global_load_dword v41, v[22:23], off offset:2048
	global_load_dword v42, v[24:25], off offset:2048
	global_load_dword v43, v[26:27], off offset:2048
	global_load_dword v44, v[28:29], off offset:2048
	global_load_dword v45, v[30:31], off offset:2048
	global_load_dword v46, v[14:15], off offset:2048
	v_add_u32_e32 v14, s11, v3
	v_add_u32_e32 v16, s11, v5
	v_add_u32_e32 v18, s11, v6
	v_add_u32_e32 v20, s11, v7
	v_add_u32_e32 v22, s11, v8
	v_add_u32_e32 v24, s11, v9
	v_add_u32_e32 v26, s11, v10
	v_add_u32_e32 v28, s11, v11
	s_ashr_i32 s11, s10, 31
	v_ashrrev_i32_e32 v15, 31, v14
	v_ashrrev_i32_e32 v17, 31, v16
	v_ashrrev_i32_e32 v19, 31, v18
	v_ashrrev_i32_e32 v21, 31, v20
	v_ashrrev_i32_e32 v23, 31, v22
	v_ashrrev_i32_e32 v25, 31, v24
	v_ashrrev_i32_e32 v27, 31, v26
	v_ashrrev_i32_e32 v29, 31, v28
	v_lshl_add_u64 v[30:31], s[10:11], 1, v[0:1]
	v_lshlrev_b64 v[14:15], 11, v[14:15]
	v_lshlrev_b64 v[16:17], 11, v[16:17]
	v_lshlrev_b64 v[18:19], 11, v[18:19]
	v_lshlrev_b64 v[20:21], 11, v[20:21]
	v_lshlrev_b64 v[22:23], 11, v[22:23]
	v_lshlrev_b64 v[24:25], 11, v[24:25]
	v_lshlrev_b64 v[26:27], 11, v[26:27]
	v_lshlrev_b64 v[28:29], 11, v[28:29]
	v_lshl_add_u64 v[14:15], v[30:31], 0, v[14:15]
	v_lshl_add_u64 v[16:17], v[30:31], 0, v[16:17]
	v_lshl_add_u64 v[18:19], v[30:31], 0, v[18:19]
	v_lshl_add_u64 v[20:21], v[30:31], 0, v[20:21]
	v_lshl_add_u64 v[22:23], v[30:31], 0, v[22:23]
	v_lshl_add_u64 v[24:25], v[30:31], 0, v[24:25]
	v_lshl_add_u64 v[26:27], v[30:31], 0, v[26:27]
	v_lshl_add_u64 v[28:29], v[30:31], 0, v[28:29]
	s_add_i32 s98, s18, s5
	s_cmp_lt_i32 s98, 0x480
	s_cbranch_scc0 .Lcv316_p1skip
; __device__ __forceinline__ bf16_t f2bf(float f) { unsigned u = __float_as_uint(f); u += 0x7FFFu + ((u >> 16) & 1u); return (bf16_t)(u >> 16); }
;     ...
;     for (int t_ = first; t_ < ntile * ((REP & 1) + 1); t_ += gridDim.x) { const int t = t_ % ntile;
;         const int r0 = (t / nkt) * 64, k0 = (t % nkt) * 64;
;         __syncthreads();
; #pragma unroll
;         for (int i = 0; i < 8; ++i) { const int kk = i * 8 + w; tile[kk * 65 + lane] = src(k0 + kk, r0 + lane); }
;         __syncthreads();
; #pragma unroll
;         for (int i = 0; i < 8; ++i) { const int j = i * 8 + w; Bt[(size_t)(r0 + j) * ld + k0 + lane] = f2bf(tile[lane * 65 + j]); }
;     }
; __device__ void convert_phase(unsigned char* smem, const Params& p, int l) {
;     ...
;       conv_tiles(tile, wt + W_QKV, 4608, 1024, 113, [=](int k, int r) { return gn[k] * wi[(size_t)k * INC + HYC + r]; }); }
	s_mul_hi_i32 s10, s98, 0x38e38e39
	s_lshr_b32 s11, s10, 31
	s_ashr_i32 s10, s10, 8
	s_add_i32 s10, s10, s11
	s_mulk_i32 s10, 0x480
	s_sub_i32 s10, s98, s10
	s_sext_i32_i16 s11, s10
	s_bfe_u32 s11, s11, 0x4001b
	s_add_i32 s11, s10, s11
	s_sext_i32_i16 s19, s11
	s_and_b32 s11, s11, 0xfff0
	s_lshl_b32 s19, s19, 2
	s_sub_i32 s10, s10, s11
	s_and_b32 s11, s19, 0xffffffc0
	s_sext_i32_i16 s10, s10
	s_lshl_b32 s10, s10, 6
	v_or_b32_e32 v56, s11, v2
	v_mov_b64_e32 v[54:55], s[6:7]
	v_ashrrev_i32_e32 v57, 31, v56
	v_add_u32_e32 v58, s10, v3
	v_add_u32_e32 v53, s10, v5
	v_add_u32_e32 v64, s10, v6
	v_add_u32_e32 v66, s10, v7
	v_add_u32_e32 v68, s10, v8
	v_add_u32_e32 v70, s10, v9
	v_add_u32_e32 v72, s10, v10
	v_add_u32_e32 v74, s10, v11
	v_mad_i64_i32 v[60:61], s[20:21], v58, s94, v[54:55]
	v_lshlrev_b64 v[56:57], 2, v[56:57]
	v_mad_i64_i32 v[62:63], s[20:21], v53, s94, v[54:55]
	v_mad_i64_i32 v[64:65], s[20:21], v64, s94, v[54:55]
	v_mad_i64_i32 v[66:67], s[20:21], v66, s94, v[54:55]
	v_mad_i64_i32 v[68:69], s[20:21], v68, s94, v[54:55]
	v_mad_i64_i32 v[70:71], s[20:21], v70, s94, v[54:55]
	v_mad_i64_i32 v[72:73], s[20:21], v72, s94, v[54:55]
	v_mad_i64_i32 v[54:55], s[20:21], v74, s94, v[54:55]
	v_lshl_add_u64 v[60:61], v[60:61], 0, v[56:57]
	v_lshl_add_u64 v[62:63], v[62:63], 0, v[56:57]
	v_lshl_add_u64 v[64:65], v[64:65], 0, v[56:57]
	v_lshl_add_u64 v[66:67], v[66:67], 0, v[56:57]
	v_lshl_add_u64 v[68:69], v[68:69], 0, v[56:57]
	v_lshl_add_u64 v[70:71], v[70:71], 0, v[56:57]
	v_lshl_add_u64 v[72:73], v[72:73], 0, v[56:57]
	v_lshl_add_u64 v[54:55], v[54:55], 0, v[56:57]
	v_add_co_u32_e32 v56, vcc, s78, v60
	v_ashrrev_i32_e32 v59, 31, v58
	s_nop 0
	v_addc_co_u32_e32 v57, vcc, 0, v61, vcc
	v_add_co_u32_e32 v60, vcc, s78, v62
	v_lshl_add_u64 v[58:59], v[58:59], 2, s[8:9]
	s_nop 0
	v_addc_co_u32_e32 v61, vcc, 0, v63, vcc
	v_add_co_u32_e32 v62, vcc, s78, v64
	s_nop 1
	v_addc_co_u32_e32 v63, vcc, 0, v65, vcc
	v_add_co_u32_e32 v64, vcc, s78, v66
	s_nop 0
	v_addc_co_u32_e32 v65, vcc, 0, v67, vcc
	v_add_co_u32_e32 v66, vcc, s78, v68
	s_nop 1
	v_addc_co_u32_e32 v67, vcc, 0, v69, vcc
	v_add_co_u32_e32 v68, vcc, s78, v70
	s_nop 0
	v_addc_co_u32_e32 v69, vcc, 0, v71, vcc
	v_add_co_u32_e32 v70, vcc, s78, v72
	s_nop 1
	v_addc_co_u32_e32 v71, vcc, 0, v73, vcc
	v_add_co_u32_e32 v54, vcc, s78, v54
	global_load_dword v53, v[58:59], off
	global_load_dword v72, v[58:59], off offset:32
	global_load_dword v73, v[58:59], off offset:64
	global_load_dword v74, v[58:59], off offset:96
	global_load_dword v75, v[58:59], off offset:128
	global_load_dword v76, v[58:59], off offset:160
	global_load_dword v77, v[58:59], off offset:192
	global_load_dword v78, v[58:59], off offset:224
	v_addc_co_u32_e32 v55, vcc, 0, v55, vcc
	global_load_dword v79, v[56:57], off offset:2048
	global_load_dword v80, v[60:61], off offset:2048
	global_load_dword v81, v[62:63], off offset:2048
	global_load_dword v82, v[64:65], off offset:2048
	global_load_dword v83, v[66:67], off offset:2048
	global_load_dword v84, v[68:69], off offset:2048
	global_load_dword v85, v[70:71], off offset:2048
	global_load_dword v86, v[54:55], off offset:2048
	v_add_u32_e32 v54, s11, v3
	v_add_u32_e32 v56, s11, v5
	v_add_u32_e32 v58, s11, v6
	v_add_u32_e32 v60, s11, v7
	v_add_u32_e32 v62, s11, v8
	v_add_u32_e32 v64, s11, v9
	v_add_u32_e32 v66, s11, v10
	v_add_u32_e32 v68, s11, v11
	s_ashr_i32 s11, s10, 31
	v_ashrrev_i32_e32 v55, 31, v54
	v_ashrrev_i32_e32 v57, 31, v56
	v_ashrrev_i32_e32 v59, 31, v58
	v_ashrrev_i32_e32 v61, 31, v60
	v_ashrrev_i32_e32 v63, 31, v62
	v_ashrrev_i32_e32 v65, 31, v64
	v_ashrrev_i32_e32 v67, 31, v66
	v_ashrrev_i32_e32 v69, 31, v68
	v_lshl_add_u64 v[70:71], s[10:11], 1, v[0:1]
	v_lshlrev_b64 v[54:55], 11, v[54:55]
	v_lshlrev_b64 v[56:57], 11, v[56:57]
	v_lshlrev_b64 v[58:59], 11, v[58:59]
	v_lshlrev_b64 v[60:61], 11, v[60:61]
	v_lshlrev_b64 v[62:63], 11, v[62:63]
	v_lshlrev_b64 v[64:65], 11, v[64:65]
	v_lshlrev_b64 v[66:67], 11, v[66:67]
	v_lshlrev_b64 v[68:69], 11, v[68:69]
	v_lshl_add_u64 v[54:55], v[70:71], 0, v[54:55]
	v_lshl_add_u64 v[56:57], v[70:71], 0, v[56:57]
	v_lshl_add_u64 v[58:59], v[70:71], 0, v[58:59]
	v_lshl_add_u64 v[60:61], v[70:71], 0, v[60:61]
	v_lshl_add_u64 v[62:63], v[70:71], 0, v[62:63]
	v_lshl_add_u64 v[64:65], v[70:71], 0, v[64:65]
	v_lshl_add_u64 v[66:67], v[70:71], 0, v[66:67]
	v_lshl_add_u64 v[68:69], v[70:71], 0, v[68:69]
	s_waitcnt vmcnt(16)
	s_branch .Lcv316_top

; __device__ __forceinline__ bf16_t f2bf(float f) { unsigned u = __float_as_uint(f); u += 0x7FFFu + ((u >> 16) & 1u); return (bf16_t)(u >> 16); }
;     ...
;     for (int t_ = first; t_ < ntile * ((REP & 1) + 1); t_ += gridDim.x) { const int t = t_ % ntile;
;         const int r0 = (t / nkt) * 64, k0 = (t % nkt) * 64;
;         __syncthreads();
; #pragma unroll
;         for (int i = 0; i < 8; ++i) { const int kk = i * 8 + w; tile[kk * 65 + lane] = src(k0 + kk, r0 + lane); }
;         __syncthreads();
; #pragma unroll
;         for (int i = 0; i < 8; ++i) { const int j = i * 8 + w; Bt[(size_t)(r0 + j) * ld + k0 + lane] = f2bf(tile[lane * 65 + j]); }
; __device__ void convert_phase(unsigned char* smem, const Params& p, int l) {
;     ...
;       conv_tiles(tile, wt + W_QKV, 4608, 1024, 113, [=](int k, int r) { return gn[k] * wi[(size_t)k * INC + HYC + r]; }); }
.Lcv316_top:
	s_barrier
	s_waitcnt vmcnt(31)
	v_mul_f32_e32 v13, v13, v39
	s_waitcnt vmcnt(30)
	v_mul_f32_e32 v30, v32, v40
	s_waitcnt vmcnt(29)
	v_mul_f32_e32 v31, v33, v41
	s_waitcnt vmcnt(28)
	v_mul_f32_e32 v32, v34, v42
	s_waitcnt vmcnt(27)
	v_mul_f32_e32 v33, v35, v43
	s_waitcnt vmcnt(26)
	v_mul_f32_e32 v34, v36, v44
	s_waitcnt vmcnt(25)
	v_mul_f32_e32 v35, v37, v45
	s_waitcnt vmcnt(24)
	v_mul_f32_e32 v36, v38, v46
	ds_write_b32 v12, v13
	ds_write_b32 v12, v30 offset:2080
	ds_write_b32 v12, v31 offset:4160
	ds_write_b32 v12, v32 offset:6240
	ds_write_b32 v12, v33 offset:8320
	ds_write_b32 v12, v34 offset:10400
	ds_write_b32 v12, v35 offset:12480
	ds_write_b32 v12, v36 offset:14560
	s_waitcnt lgkmcnt(0)
	s_barrier
	ds_read2_b32 v[30:31], v4 offset1:8
	ds_read2_b32 v[32:33], v4 offset0:16 offset1:24
	ds_read2_b32 v[34:35], v4 offset0:32 offset1:40
	ds_read2_b32 v[36:37], v4 offset0:48 offset1:56
	s_waitcnt lgkmcnt(3)
	v_bfe_u32 v13, v30, 16, 1
	v_bfe_u32 v38, v31, 16, 1
	s_waitcnt lgkmcnt(2)
	v_bfe_u32 v39, v32, 16, 1
	v_bfe_u32 v40, v33, 16, 1
	s_waitcnt lgkmcnt(1)
	v_bfe_u32 v41, v34, 16, 1
	v_bfe_u32 v42, v35, 16, 1
	s_waitcnt lgkmcnt(0)
	v_bfe_u32 v43, v36, 16, 1
	v_bfe_u32 v44, v37, 16, 1
	v_add3_u32 v13, v30, v13, s88
	v_add3_u32 v30, v31, v38, s88
	v_add3_u32 v31, v32, v39, s88
	v_add3_u32 v32, v33, v40, s88
	v_add3_u32 v33, v34, v41, s88
	v_add3_u32 v34, v35, v42, s88
	v_add3_u32 v35, v36, v43, s88
	v_add3_u32 v36, v37, v44, s88
	global_store_short_d16_hi v[14:15], v13, off
	global_store_short_d16_hi v[16:17], v30, off
	global_store_short_d16_hi v[18:19], v31, off
	global_store_short_d16_hi v[20:21], v32, off
	global_store_short_d16_hi v[22:23], v33, off
	global_store_short_d16_hi v[24:25], v34, off
	global_store_short_d16_hi v[26:27], v35, off
	global_store_short_d16_hi v[28:29], v36, off
	s_lshl_b32 s98, s5, 1
	s_add_i32 s98, s98, s18
	s_cmp_lt_i32 s98, 0x480
	s_cbranch_scc0 .Lcv316_s0
	s_mul_hi_i32 s10, s98, 0x38e38e39
	s_lshr_b32 s11, s10, 31
	s_ashr_i32 s10, s10, 8
	s_add_i32 s10, s10, s11
	s_mulk_i32 s10, 0x480
	s_sub_i32 s10, s98, s10
	s_sext_i32_i16 s11, s10
	s_bfe_u32 s11, s11, 0x4001b
	s_add_i32 s11, s10, s11
	s_sext_i32_i16 s19, s11
	s_and_b32 s11, s11, 0xfff0
	s_lshl_b32 s19, s19, 2
	s_sub_i32 s10, s10, s11
	s_and_b32 s11, s19, 0xffffffc0
	s_sext_i32_i16 s10, s10
	s_lshl_b32 s10, s10, 6
	v_or_b32_e32 v16, s11, v2
	v_mov_b64_e32 v[14:15], s[6:7]
	v_ashrrev_i32_e32 v17, 31, v16
	v_add_u32_e32 v18, s10, v3
	v_add_u32_e32 v13, s10, v5
	v_add_u32_e32 v24, s10, v6
	v_add_u32_e32 v26, s10, v7
	v_add_u32_e32 v28, s10, v8
	v_add_u32_e32 v30, s10, v9
	v_add_u32_e32 v32, s10, v10
	v_add_u32_e32 v34, s10, v11
	v_mad_i64_i32 v[20:21], s[20:21], v18, s94, v[14:15]
	v_lshlrev_b64 v[16:17], 2, v[16:17]
	v_mad_i64_i32 v[22:23], s[20:21], v13, s94, v[14:15]
	v_mad_i64_i32 v[24:25], s[20:21], v24, s94, v[14:15]
	v_mad_i64_i32 v[26:27], s[20:21], v26, s94, v[14:15]
	v_mad_i64_i32 v[28:29], s[20:21], v28, s94, v[14:15]
	v_mad_i64_i32 v[30:31], s[20:21], v30, s94, v[14:15]
	v_mad_i64_i32 v[32:33], s[20:21], v32, s94, v[14:15]
	v_mad_i64_i32 v[14:15], s[20:21], v34, s94, v[14:15]
	v_lshl_add_u64 v[20:21], v[20:21], 0, v[16:17]
	v_lshl_add_u64 v[22:23], v[22:23], 0, v[16:17]
	v_lshl_add_u64 v[24:25], v[24:25], 0, v[16:17]
	v_lshl_add_u64 v[26:27], v[26:27], 0, v[16:17]
	v_lshl_add_u64 v[28:29], v[28:29], 0, v[16:17]
	v_lshl_add_u64 v[30:31], v[30:31], 0, v[16:17]
	v_lshl_add_u64 v[32:33], v[32:33], 0, v[16:17]
	v_lshl_add_u64 v[14:15], v[14:15], 0, v[16:17]
	v_add_co_u32_e32 v16, vcc, s78, v20
	v_ashrrev_i32_e32 v19, 31, v18
	s_nop 0
	v_addc_co_u32_e32 v17, vcc, 0, v21, vcc
	v_add_co_u32_e32 v20, vcc, s78, v22
	v_lshl_add_u64 v[18:19], v[18:19], 2, s[8:9]
	s_nop 0
	v_addc_co_u32_e32 v21, vcc, 0, v23, vcc
	v_add_co_u32_e32 v22, vcc, s78, v24
	s_nop 1
	v_addc_co_u32_e32 v23, vcc, 0, v25, vcc
	v_add_co_u32_e32 v24, vcc, s78, v26
	s_nop 0
	v_addc_co_u32_e32 v25, vcc, 0, v27, vcc
	v_add_co_u32_e32 v26, vcc, s78, v28
	s_nop 1
	v_addc_co_u32_e32 v27, vcc, 0, v29, vcc
	v_add_co_u32_e32 v28, vcc, s78, v30
	s_nop 0
	v_addc_co_u32_e32 v29, vcc, 0, v31, vcc
	v_add_co_u32_e32 v30, vcc, s78, v32
	s_nop 1
	v_addc_co_u32_e32 v31, vcc, 0, v33, vcc
	v_add_co_u32_e32 v14, vcc, s78, v14
	global_load_dword v13, v[18:19], off
	global_load_dword v32, v[18:19], off offset:32
	global_load_dword v33, v[18:19], off offset:64
	global_load_dword v34, v[18:19], off offset:96
	global_load_dword v35, v[18:19], off offset:128
	global_load_dword v36, v[18:19], off offset:160
	global_load_dword v37, v[18:19], off offset:192
	global_load_dword v38, v[18:19], off offset:224
	v_addc_co_u32_e32 v15, vcc, 0, v15, vcc
	global_load_dword v39, v[16:17], off offset:2048
	global_load_dword v40, v[20:21], off offset:2048
	global_load_dword v41, v[22:23], off offset:2048
	global_load_dword v42, v[24:25], off offset:2048
	global_load_dword v43, v[26:27], off offset:2048
	global_load_dword v44, v[28:29], off offset:2048
	global_load_dword v45, v[30:31], off offset:2048
	global_load_dword v46, v[14:15], off offset:2048
	v_add_u32_e32 v14, s11, v3
	v_add_u32_e32 v16, s11, v5
	v_add_u32_e32 v18, s11, v6
	v_add_u32_e32 v20, s11, v7
	v_add_u32_e32 v22, s11, v8
	v_add_u32_e32 v24, s11, v9
	v_add_u32_e32 v26, s11, v10
	v_add_u32_e32 v28, s11, v11
	s_ashr_i32 s11, s10, 31
	v_ashrrev_i32_e32 v15, 31, v14
	v_ashrrev_i32_e32 v17, 31, v16
	v_ashrrev_i32_e32 v19, 31, v18
	v_ashrrev_i32_e32 v21, 31, v20
	v_ashrrev_i32_e32 v23, 31, v22
	v_ashrrev_i32_e32 v25, 31, v24
	v_ashrrev_i32_e32 v27, 31, v26
	v_ashrrev_i32_e32 v29, 31, v28
	v_lshl_add_u64 v[30:31], s[10:11], 1, v[0:1]
	v_lshlrev_b64 v[14:15], 11, v[14:15]
	v_lshlrev_b64 v[16:17], 11, v[16:17]
	v_lshlrev_b64 v[18:19], 11, v[18:19]
	v_lshlrev_b64 v[20:21], 11, v[20:21]
	v_lshlrev_b64 v[22:23], 11, v[22:23]
	v_lshlrev_b64 v[24:25], 11, v[24:25]
	v_lshlrev_b64 v[26:27], 11, v[26:27]
	v_lshlrev_b64 v[28:29], 11, v[28:29]
	v_lshl_add_u64 v[14:15], v[30:31], 0, v[14:15]
	v_lshl_add_u64 v[16:17], v[30:31], 0, v[16:17]
	v_lshl_add_u64 v[18:19], v[30:31], 0, v[18:19]
	v_lshl_add_u64 v[20:21], v[30:31], 0, v[20:21]
	v_lshl_add_u64 v[22:23], v[30:31], 0, v[22:23]
	v_lshl_add_u64 v[24:25], v[30:31], 0, v[24:25]
	v_lshl_add_u64 v[26:27], v[30:31], 0, v[26:27]
	v_lshl_add_u64 v[28:29], v[30:31], 0, v[28:29]
	s_branch .Lcv316_n0

; __device__ __forceinline__ bf16_t f2bf(float f) { unsigned u = __float_as_uint(f); u += 0x7FFFu + ((u >> 16) & 1u); return (bf16_t)(u >> 16); }
;     ...
;     for (int t_ = first; t_ < ntile * ((REP & 1) + 1); t_ += gridDim.x) { const int t = t_ % ntile;
;         const int r0 = (t / nkt) * 64, k0 = (t % nkt) * 64;
;         __syncthreads();
; #pragma unroll
;         for (int i = 0; i < 8; ++i) { const int kk = i * 8 + w; tile[kk * 65 + lane] = src(k0 + kk, r0 + lane); }
;         __syncthreads();
; #pragma unroll
;         for (int i = 0; i < 8; ++i) { const int j = i * 8 + w; Bt[(size_t)(r0 + j) * ld + k0 + lane] = f2bf(tile[lane * 65 + j]); }
; __device__ void convert_phase(unsigned char* smem, const Params& p, int l) {
;     ...
;       conv_tiles(tile, wt + W_QKV, 4608, 1024, 113, [=](int k, int r) { return gn[k] * wi[(size_t)k * INC + HYC + r]; }); }
.Lcv316_n0:
	s_add_i32 s18, s18, s5
	s_cmp_lt_i32 s18, 0x480
	s_cbranch_scc0 .LBB0_317
	s_barrier
	s_waitcnt vmcnt(31)
	v_mul_f32_e32 v53, v53, v79
	s_waitcnt vmcnt(30)
	v_mul_f32_e32 v70, v72, v80
	s_waitcnt vmcnt(29)
	v_mul_f32_e32 v71, v73, v81
	s_waitcnt vmcnt(28)
	v_mul_f32_e32 v72, v74, v82
	s_waitcnt vmcnt(27)
	v_mul_f32_e32 v73, v75, v83
	s_waitcnt vmcnt(26)
	v_mul_f32_e32 v74, v76, v84
	s_waitcnt vmcnt(25)
	v_mul_f32_e32 v75, v77, v85
	s_waitcnt vmcnt(24)
	v_mul_f32_e32 v76, v78, v86
	ds_write_b32 v12, v53
	ds_write_b32 v12, v70 offset:2080
	ds_write_b32 v12, v71 offset:4160
	ds_write_b32 v12, v72 offset:6240
	ds_write_b32 v12, v73 offset:8320
	ds_write_b32 v12, v74 offset:10400
	ds_write_b32 v12, v75 offset:12480
	ds_write_b32 v12, v76 offset:14560
	s_waitcnt lgkmcnt(0)
	s_barrier
	ds_read2_b32 v[70:71], v4 offset1:8
	ds_read2_b32 v[72:73], v4 offset0:16 offset1:24
	ds_read2_b32 v[74:75], v4 offset0:32 offset1:40
	ds_read2_b32 v[76:77], v4 offset0:48 offset1:56
	s_waitcnt lgkmcnt(3)
	v_bfe_u32 v53, v70, 16, 1
	v_bfe_u32 v78, v71, 16, 1
	s_waitcnt lgkmcnt(2)
	v_bfe_u32 v79, v72, 16, 1
	v_bfe_u32 v80, v73, 16, 1
	s_waitcnt lgkmcnt(1)
	v_bfe_u32 v81, v74, 16, 1
	v_bfe_u32 v82, v75, 16, 1
	s_waitcnt lgkmcnt(0)
	v_bfe_u32 v83, v76, 16, 1
	v_bfe_u32 v84, v77, 16, 1
	v_add3_u32 v53, v70, v53, s88
	v_add3_u32 v70, v71, v78, s88
	v_add3_u32 v71, v72, v79, s88
	v_add3_u32 v72, v73, v80, s88
	v_add3_u32 v73, v74, v81, s88
	v_add3_u32 v74, v75, v82, s88
	v_add3_u32 v75, v76, v83, s88
	v_add3_u32 v76, v77, v84, s88
	global_store_short_d16_hi v[54:55], v53, off
	global_store_short_d16_hi v[56:57], v70, off
	global_store_short_d16_hi v[58:59], v71, off
	global_store_short_d16_hi v[60:61], v72, off
	global_store_short_d16_hi v[62:63], v73, off
	global_store_short_d16_hi v[64:65], v74, off
	global_store_short_d16_hi v[66:67], v75, off
	global_store_short_d16_hi v[68:69], v76, off
	s_lshl_b32 s98, s5, 1
	s_add_i32 s98, s98, s18
	s_cmp_lt_i32 s98, 0x480
	s_cbranch_scc0 .Lcv316_s1
	s_mul_hi_i32 s10, s98, 0x38e38e39
	s_lshr_b32 s11, s10, 31
	s_ashr_i32 s10, s10, 8
	s_add_i32 s10, s10, s11
	s_mulk_i32 s10, 0x480
	s_sub_i32 s10, s98, s10
	s_sext_i32_i16 s11, s10
	s_bfe_u32 s11, s11, 0x4001b
	s_add_i32 s11, s10, s11
	s_sext_i32_i16 s19, s11
	s_and_b32 s11, s11, 0xfff0
	s_lshl_b32 s19, s19, 2
	s_sub_i32 s10, s10, s11
	s_and_b32 s11, s19, 0xffffffc0
	s_sext_i32_i16 s10, s10
	s_lshl_b32 s10, s10, 6
	v_or_b32_e32 v56, s11, v2
	v_mov_b64_e32 v[54:55], s[6:7]
	v_ashrrev_i32_e32 v57, 31, v56
	v_add_u32_e32 v58, s10, v3
	v_add_u32_e32 v53, s10, v5
	v_add_u32_e32 v64, s10, v6
	v_add_u32_e32 v66, s10, v7
	v_add_u32_e32 v68, s10, v8
	v_add_u32_e32 v70, s10, v9
	v_add_u32_e32 v72, s10, v10
	v_add_u32_e32 v74, s10, v11
	v_mad_i64_i32 v[60:61], s[20:21], v58, s94, v[54:55]
	v_lshlrev_b64 v[56:57], 2, v[56:57]
	v_mad_i64_i32 v[62:63], s[20:21], v53, s94, v[54:55]
	v_mad_i64_i32 v[64:65], s[20:21], v64, s94, v[54:55]
	v_mad_i64_i32 v[66:67], s[20:21], v66, s94, v[54:55]
	v_mad_i64_i32 v[68:69], s[20:21], v68, s94, v[54:55]
	v_mad_i64_i32 v[70:71], s[20:21], v70, s94, v[54:55]
	v_mad_i64_i32 v[72:73], s[20:21], v72, s94, v[54:55]
	v_mad_i64_i32 v[54:55], s[20:21], v74, s94, v[54:55]
	v_lshl_add_u64 v[60:61], v[60:61], 0, v[56:57]
	v_lshl_add_u64 v[62:63], v[62:63], 0, v[56:57]
	v_lshl_add_u64 v[64:65], v[64:65], 0, v[56:57]
	v_lshl_add_u64 v[66:67], v[66:67], 0, v[56:57]
	v_lshl_add_u64 v[68:69], v[68:69], 0, v[56:57]
	v_lshl_add_u64 v[70:71], v[70:71], 0, v[56:57]
	v_lshl_add_u64 v[72:73], v[72:73], 0, v[56:57]
	v_lshl_add_u64 v[54:55], v[54:55], 0, v[56:57]
	v_add_co_u32_e32 v56, vcc, s78, v60
	v_ashrrev_i32_e32 v59, 31, v58
	s_nop 0
	v_addc_co_u32_e32 v57, vcc, 0, v61, vcc
	v_add_co_u32_e32 v60, vcc, s78, v62
	v_lshl_add_u64 v[58:59], v[58:59], 2, s[8:9]
	s_nop 0
	v_addc_co_u32_e32 v61, vcc, 0, v63, vcc
	v_add_co_u32_e32 v62, vcc, s78, v64
	s_nop 1
	v_addc_co_u32_e32 v63, vcc, 0, v65, vcc
	v_add_co_u32_e32 v64, vcc, s78, v66
	s_nop 0
	v_addc_co_u32_e32 v65, vcc, 0, v67, vcc
	v_add_co_u32_e32 v66, vcc, s78, v68
	s_nop 1
	v_addc_co_u32_e32 v67, vcc, 0, v69, vcc
	v_add_co_u32_e32 v68, vcc, s78, v70
	s_nop 0
	v_addc_co_u32_e32 v69, vcc, 0, v71, vcc
	v_add_co_u32_e32 v70, vcc, s78, v72
	s_nop 1
	v_addc_co_u32_e32 v71, vcc, 0, v73, vcc
	v_add_co_u32_e32 v54, vcc, s78, v54
	global_load_dword v53, v[58:59], off
	global_load_dword v72, v[58:59], off offset:32
	global_load_dword v73, v[58:59], off offset:64
	global_load_dword v74, v[58:59], off offset:96
	global_load_dword v75, v[58:59], off offset:128
	global_load_dword v76, v[58:59], off offset:160
	global_load_dword v77, v[58:59], off offset:192
	global_load_dword v78, v[58:59], off offset:224
	v_addc_co_u32_e32 v55, vcc, 0, v55, vcc
	global_load_dword v79, v[56:57], off offset:2048
	global_load_dword v80, v[60:61], off offset:2048
	global_load_dword v81, v[62:63], off offset:2048
	global_load_dword v82, v[64:65], off offset:2048
	global_load_dword v83, v[66:67], off offset:2048
	global_load_dword v84, v[68:69], off offset:2048
	global_load_dword v85, v[70:71], off offset:2048
	global_load_dword v86, v[54:55], off offset:2048
	v_add_u32_e32 v54, s11, v3
	v_add_u32_e32 v56, s11, v5
	v_add_u32_e32 v58, s11, v6
	v_add_u32_e32 v60, s11, v7
	v_add_u32_e32 v62, s11, v8
	v_add_u32_e32 v64, s11, v9
	v_add_u32_e32 v66, s11, v10
	v_add_u32_e32 v68, s11, v11
	s_ashr_i32 s11, s10, 31
	v_ashrrev_i32_e32 v55, 31, v54
	v_ashrrev_i32_e32 v57, 31, v56
	v_ashrrev_i32_e32 v59, 31, v58
	v_ashrrev_i32_e32 v61, 31, v60
	v_ashrrev_i32_e32 v63, 31, v62
	v_ashrrev_i32_e32 v65, 31, v64
	v_ashrrev_i32_e32 v67, 31, v66
	v_ashrrev_i32_e32 v69, 31, v68
	v_lshl_add_u64 v[70:71], s[10:11], 1, v[0:1]
	v_lshlrev_b64 v[54:55], 11, v[54:55]
	v_lshlrev_b64 v[56:57], 11, v[56:57]
	v_lshlrev_b64 v[58:59], 11, v[58:59]
	v_lshlrev_b64 v[60:61], 11, v[60:61]
	v_lshlrev_b64 v[62:63], 11, v[62:63]
	v_lshlrev_b64 v[64:65], 11, v[64:65]
	v_lshlrev_b64 v[66:67], 11, v[66:67]
	v_lshlrev_b64 v[68:69], 11, v[68:69]
	v_lshl_add_u64 v[54:55], v[70:71], 0, v[54:55]
	v_lshl_add_u64 v[56:57], v[70:71], 0, v[56:57]
	v_lshl_add_u64 v[58:59], v[70:71], 0, v[58:59]
	v_lshl_add_u64 v[60:61], v[70:71], 0, v[60:61]
	v_lshl_add_u64 v[62:63], v[70:71], 0, v[62:63]
	v_lshl_add_u64 v[64:65], v[70:71], 0, v[64:65]
	v_lshl_add_u64 v[66:67], v[70:71], 0, v[66:67]
	v_lshl_add_u64 v[68:69], v[70:71], 0, v[68:69]
	s_branch .Lcv316_n1

;     ...
;     for (int t_ = first; t_ < ntile * ((REP & 1) + 1); t_ += gridDim.x) { const int t = t_ % ntile;
.Lcv316_n1:
	s_add_i32 s18, s18, s5
	s_cmp_lt_i32 s18, 0x480
	s_cbranch_scc1 .Lcv316_top

; __device__ __forceinline__ bf16_t f2bf(float f) { unsigned u = __float_as_uint(f); u += 0x7FFFu + ((u >> 16) & 1u); return (bf16_t)(u >> 16); }
;     ...
;     for (int t_ = first; t_ < ntile * ((REP & 1) + 1); t_ += gridDim.x) { const int t = t_ % ntile;
;         const int r0 = (t / nkt) * 64, k0 = (t % nkt) * 64;
;         __syncthreads();
; #pragma unroll
;         for (int i = 0; i < 8; ++i) { const int kk = i * 8 + w; tile[kk * 65 + lane] = src(k0 + kk, r0 + lane); }
;         __syncthreads();
; #pragma unroll
;         for (int i = 0; i < 8; ++i) { const int j = i * 8 + w; Bt[(size_t)(r0 + j) * ld + k0 + lane] = f2bf(tile[lane * 65 + j]); }
;     }
; __device__ void convert_phase(unsigned char* smem, const Params& p, int l) {
;     ...
;     { const float* wgt = ((const float*)ldp(26)) + (size_t)l * DM * 3072; const float* gn = ((const float*)ldp(5)) + l * DM; conv_tiles(tile, wt + W_GATE, 3072, 1024, 151, [=](int k, int r) { return gn[k] * wgt[(size_t)k * 3072 + r]; }); }
.LBB0_319:
	s_mov_b32 s98, s17
	s_mul_hi_i32 s10, s98, 0x2aaaaaab
	s_lshr_b32 s11, s10, 31
	s_lshr_b32 s10, s10, 7
	s_add_i32 s10, s10, s11
	s_mulk_i32 s10, 0x300
	s_sub_i32 s10, s98, s10
	s_sext_i32_i16 s11, s10
	s_bfe_u32 s11, s11, 0x4001b
	s_add_i32 s11, s10, s11
	s_sext_i32_i16 s18, s11
	s_and_b32 s11, s11, 0xfff0
	s_sub_i32 s10, s10, s11
	s_lshl_b32 s18, s18, 2
	s_sext_i32_i16 s10, s10
	s_and_b32 s11, s18, 0xffffffc0
	s_lshl_b32 s10, s10, 6
	v_or_b32_e32 v14, s11, v2
	v_add_u32_e32 v16, s10, v3
	v_ashrrev_i32_e32 v15, 31, v14
	v_ashrrev_i32_e32 v17, 31, v16
	v_add_u32_e32 v13, s10, v5
	v_add_u32_e32 v22, s10, v6
	v_add_u32_e32 v24, s10, v7
	v_add_u32_e32 v26, s10, v8
	v_add_u32_e32 v28, s10, v9
	v_add_u32_e32 v30, s10, v10
	v_add_u32_e32 v32, s10, v11
	v_lshl_add_u64 v[14:15], v[14:15], 2, s[6:7]
	v_lshl_add_u64 v[18:19], v[16:17], 2, s[8:9]
	v_mad_i64_i32 v[16:17], s[18:19], v16, s79, v[14:15]
	v_mad_i64_i32 v[20:21], s[18:19], v13, s79, v[14:15]
	v_mad_i64_i32 v[22:23], s[18:19], v22, s79, v[14:15]
	v_mad_i64_i32 v[24:25], s[18:19], v24, s79, v[14:15]
	v_mad_i64_i32 v[26:27], s[18:19], v26, s79, v[14:15]
	v_mad_i64_i32 v[28:29], s[18:19], v28, s79, v[14:15]
	v_mad_i64_i32 v[30:31], s[18:19], v30, s79, v[14:15]
	v_mad_i64_i32 v[14:15], s[18:19], v32, s79, v[14:15]
	global_load_dword v13, v[18:19], off
	global_load_dword v32, v[18:19], off offset:32
	global_load_dword v33, v[18:19], off offset:64
	global_load_dword v34, v[18:19], off offset:96
	global_load_dword v35, v[18:19], off offset:128
	global_load_dword v36, v[18:19], off offset:160
	global_load_dword v37, v[18:19], off offset:192
	global_load_dword v38, v[18:19], off offset:224
	global_load_dword v39, v[16:17], off
	global_load_dword v40, v[20:21], off
	global_load_dword v41, v[22:23], off
	global_load_dword v42, v[24:25], off
	global_load_dword v43, v[26:27], off
	global_load_dword v44, v[28:29], off
	global_load_dword v45, v[30:31], off
	global_load_dword v46, v[14:15], off
	v_add_u32_e32 v14, s11, v3
	v_add_u32_e32 v16, s11, v5
	v_add_u32_e32 v18, s11, v6
	v_add_u32_e32 v20, s11, v7
	v_add_u32_e32 v22, s11, v8
	v_add_u32_e32 v24, s11, v9
	v_add_u32_e32 v26, s11, v10
	v_add_u32_e32 v28, s11, v11
	s_ashr_i32 s11, s10, 31
	v_ashrrev_i32_e32 v15, 31, v14
	v_ashrrev_i32_e32 v17, 31, v16
	v_ashrrev_i32_e32 v19, 31, v18
	v_ashrrev_i32_e32 v21, 31, v20
	v_ashrrev_i32_e32 v23, 31, v22
	v_ashrrev_i32_e32 v25, 31, v24
	v_ashrrev_i32_e32 v27, 31, v26
	v_ashrrev_i32_e32 v29, 31, v28
	v_lshl_add_u64 v[30:31], s[10:11], 1, v[0:1]
	v_lshlrev_b64 v[14:15], 11, v[14:15]
	v_lshlrev_b64 v[16:17], 11, v[16:17]
	v_lshlrev_b64 v[18:19], 11, v[18:19]
	v_lshlrev_b64 v[20:21], 11, v[20:21]
	v_lshlrev_b64 v[22:23], 11, v[22:23]
	v_lshlrev_b64 v[24:25], 11, v[24:25]
	v_lshlrev_b64 v[26:27], 11, v[26:27]
	v_lshlrev_b64 v[28:29], 11, v[28:29]
	v_lshl_add_u64 v[14:15], v[30:31], 0, v[14:15]
	v_lshl_add_u64 v[16:17], v[30:31], 0, v[16:17]
	v_lshl_add_u64 v[18:19], v[30:31], 0, v[18:19]
	v_lshl_add_u64 v[20:21], v[30:31], 0, v[20:21]
	v_lshl_add_u64 v[22:23], v[30:31], 0, v[22:23]
	v_lshl_add_u64 v[24:25], v[30:31], 0, v[24:25]
	v_lshl_add_u64 v[26:27], v[30:31], 0, v[26:27]
	v_lshl_add_u64 v[28:29], v[30:31], 0, v[28:29]
	s_add_i32 s98, s17, s5
	s_cmp_lt_i32 s98, 0x300
	s_cbranch_scc0 .Lcv319_p1skip
	s_mul_hi_i32 s10, s98, 0x2aaaaaab
	s_lshr_b32 s11, s10, 31
	s_lshr_b32 s10, s10, 7
	s_add_i32 s10, s10, s11
	s_mulk_i32 s10, 0x300
	s_sub_i32 s10, s98, s10
	s_sext_i32_i16 s11, s10
	s_bfe_u32 s11, s11, 0x4001b
	s_add_i32 s11, s10, s11
	s_sext_i32_i16 s18, s11
	s_and_b32 s11, s11, 0xfff0
	s_sub_i32 s10, s10, s11
	s_lshl_b32 s18, s18, 2
	s_sext_i32_i16 s10, s10
	s_and_b32 s11, s18, 0xffffffc0
	s_lshl_b32 s10, s10, 6
	v_or_b32_e32 v54, s11, v2
	v_add_u32_e32 v56, s10, v3
	v_ashrrev_i32_e32 v55, 31, v54
	v_ashrrev_i32_e32 v57, 31, v56
	v_add_u32_e32 v53, s10, v5
	v_add_u32_e32 v62, s10, v6
	v_add_u32_e32 v64, s10, v7
	v_add_u32_e32 v66, s10, v8
	v_add_u32_e32 v68, s10, v9
	v_add_u32_e32 v70, s10, v10
	v_add_u32_e32 v72, s10, v11
	v_lshl_add_u64 v[54:55], v[54:55], 2, s[6:7]
	v_lshl_add_u64 v[58:59], v[56:57], 2, s[8:9]
	v_mad_i64_i32 v[56:57], s[18:19], v56, s79, v[54:55]
	v_mad_i64_i32 v[60:61], s[18:19], v53, s79, v[54:55]
	v_mad_i64_i32 v[62:63], s[18:19], v62, s79, v[54:55]
	v_mad_i64_i32 v[64:65], s[18:19], v64, s79, v[54:55]
	v_mad_i64_i32 v[66:67], s[18:19], v66, s79, v[54:55]
	v_mad_i64_i32 v[68:69], s[18:19], v68, s79, v[54:55]
	v_mad_i64_i32 v[70:71], s[18:19], v70, s79, v[54:55]
	v_mad_i64_i32 v[54:55], s[18:19], v72, s79, v[54:55]
	global_load_dword v53, v[58:59], off
	global_load_dword v72, v[58:59], off offset:32
	global_load_dword v73, v[58:59], off offset:64
	global_load_dword v74, v[58:59], off offset:96
	global_load_dword v75, v[58:59], off offset:128
	global_load_dword v76, v[58:59], off offset:160
	global_load_dword v77, v[58:59], off offset:192
	global_load_dword v78, v[58:59], off offset:224
	global_load_dword v79, v[56:57], off
	global_load_dword v80, v[60:61], off
	global_load_dword v81, v[62:63], off
	global_load_dword v82, v[64:65], off
	global_load_dword v83, v[66:67], off
	global_load_dword v84, v[68:69], off
	global_load_dword v85, v[70:71], off
	global_load_dword v86, v[54:55], off
	v_add_u32_e32 v54, s11, v3
	v_add_u32_e32 v56, s11, v5
	v_add_u32_e32 v58, s11, v6
	v_add_u32_e32 v60, s11, v7
	v_add_u32_e32 v62, s11, v8
	v_add_u32_e32 v64, s11, v9
	v_add_u32_e32 v66, s11, v10
	v_add_u32_e32 v68, s11, v11
	s_ashr_i32 s11, s10, 31
	v_ashrrev_i32_e32 v55, 31, v54
	v_ashrrev_i32_e32 v57, 31, v56
	v_ashrrev_i32_e32 v59, 31, v58
	v_ashrrev_i32_e32 v61, 31, v60
	v_ashrrev_i32_e32 v63, 31, v62
	v_ashrrev_i32_e32 v65, 31, v64
	v_ashrrev_i32_e32 v67, 31, v66
	v_ashrrev_i32_e32 v69, 31, v68
	v_lshl_add_u64 v[70:71], s[10:11], 1, v[0:1]
	v_lshlrev_b64 v[54:55], 11, v[54:55]
	v_lshlrev_b64 v[56:57], 11, v[56:57]
	v_lshlrev_b64 v[58:59], 11, v[58:59]
	v_lshlrev_b64 v[60:61], 11, v[60:61]
	v_lshlrev_b64 v[62:63], 11, v[62:63]
	v_lshlrev_b64 v[64:65], 11, v[64:65]
	v_lshlrev_b64 v[66:67], 11, v[66:67]
	v_lshlrev_b64 v[68:69], 11, v[68:69]
	v_lshl_add_u64 v[54:55], v[70:71], 0, v[54:55]
	v_lshl_add_u64 v[56:57], v[70:71], 0, v[56:57]
	v_lshl_add_u64 v[58:59], v[70:71], 0, v[58:59]
	v_lshl_add_u64 v[60:61], v[70:71], 0, v[60:61]
	v_lshl_add_u64 v[62:63], v[70:71], 0, v[62:63]
	v_lshl_add_u64 v[64:65], v[70:71], 0, v[64:65]
	v_lshl_add_u64 v[66:67], v[70:71], 0, v[66:67]
	v_lshl_add_u64 v[68:69], v[70:71], 0, v[68:69]
	s_waitcnt vmcnt(16)
	s_branch .Lcv319_top

; __device__ __forceinline__ bf16_t f2bf(float f) { unsigned u = __float_as_uint(f); u += 0x7FFFu + ((u >> 16) & 1u); return (bf16_t)(u >> 16); }
;     ...
;     for (int t_ = first; t_ < ntile * ((REP & 1) + 1); t_ += gridDim.x) { const int t = t_ % ntile;
;         const int r0 = (t / nkt) * 64, k0 = (t % nkt) * 64;
;         __syncthreads();
; #pragma unroll
;         for (int i = 0; i < 8; ++i) { const int kk = i * 8 + w; tile[kk * 65 + lane] = src(k0 + kk, r0 + lane); }
;         __syncthreads();
; #pragma unroll
;         for (int i = 0; i < 8; ++i) { const int j = i * 8 + w; Bt[(size_t)(r0 + j) * ld + k0 + lane] = f2bf(tile[lane * 65 + j]); }
; __device__ void convert_phase(unsigned char* smem, const Params& p, int l) {
;     ...
;     { const float* wgt = ((const float*)ldp(26)) + (size_t)l * DM * 3072; const float* gn = ((const float*)ldp(5)) + l * DM; conv_tiles(tile, wt + W_GATE, 3072, 1024, 151, [=](int k, int r) { return gn[k] * wgt[(size_t)k * 3072 + r]; }); }
.Lcv319_top:
	s_barrier
	s_waitcnt vmcnt(31)
	v_mul_f32_e32 v13, v13, v39
	s_waitcnt vmcnt(30)
	v_mul_f32_e32 v30, v32, v40
	s_waitcnt vmcnt(29)
	v_mul_f32_e32 v31, v33, v41
	s_waitcnt vmcnt(28)
	v_mul_f32_e32 v32, v34, v42
	s_waitcnt vmcnt(27)
	v_mul_f32_e32 v33, v35, v43
	s_waitcnt vmcnt(26)
	v_mul_f32_e32 v34, v36, v44
	s_waitcnt vmcnt(25)
	v_mul_f32_e32 v35, v37, v45
	s_waitcnt vmcnt(24)
	v_mul_f32_e32 v36, v38, v46
	ds_write_b32 v12, v13
	ds_write_b32 v12, v30 offset:2080
	ds_write_b32 v12, v31 offset:4160
	ds_write_b32 v12, v32 offset:6240
	ds_write_b32 v12, v33 offset:8320
	ds_write_b32 v12, v34 offset:10400
	ds_write_b32 v12, v35 offset:12480
	ds_write_b32 v12, v36 offset:14560
	s_waitcnt lgkmcnt(0)
	s_barrier
	ds_read2_b32 v[30:31], v4 offset1:8
	ds_read2_b32 v[32:33], v4 offset0:16 offset1:24
	ds_read2_b32 v[34:35], v4 offset0:32 offset1:40
	ds_read2_b32 v[36:37], v4 offset0:48 offset1:56
	s_waitcnt lgkmcnt(3)
	v_bfe_u32 v13, v30, 16, 1
	v_bfe_u32 v38, v31, 16, 1
	s_waitcnt lgkmcnt(2)
	v_bfe_u32 v39, v32, 16, 1
	v_bfe_u32 v40, v33, 16, 1
	s_waitcnt lgkmcnt(1)
	v_bfe_u32 v41, v34, 16, 1
	v_bfe_u32 v42, v35, 16, 1
	s_waitcnt lgkmcnt(0)
	v_bfe_u32 v43, v36, 16, 1
	v_bfe_u32 v44, v37, 16, 1
	v_add3_u32 v13, v30, v13, s88
	v_add3_u32 v30, v31, v38, s88
	v_add3_u32 v31, v32, v39, s88
	v_add3_u32 v32, v33, v40, s88
	v_add3_u32 v33, v34, v41, s88
	v_add3_u32 v34, v35, v42, s88
	v_add3_u32 v35, v36, v43, s88
	v_add3_u32 v36, v37, v44, s88
	global_store_short_d16_hi v[14:15], v13, off
	global_store_short_d16_hi v[16:17], v30, off
	global_store_short_d16_hi v[18:19], v31, off
	global_store_short_d16_hi v[20:21], v32, off
	global_store_short_d16_hi v[22:23], v33, off
	global_store_short_d16_hi v[24:25], v34, off
	global_store_short_d16_hi v[26:27], v35, off
	global_store_short_d16_hi v[28:29], v36, off
	s_lshl_b32 s98, s5, 1
	s_add_i32 s98, s98, s17
	s_cmp_lt_i32 s98, 0x300
	s_cbranch_scc0 .Lcv319_s0
	s_mul_hi_i32 s10, s98, 0x2aaaaaab
	s_lshr_b32 s11, s10, 31
	s_lshr_b32 s10, s10, 7
	s_add_i32 s10, s10, s11
	s_mulk_i32 s10, 0x300
	s_sub_i32 s10, s98, s10
	s_sext_i32_i16 s11, s10
	s_bfe_u32 s11, s11, 0x4001b
	s_add_i32 s11, s10, s11
	s_sext_i32_i16 s18, s11
	s_and_b32 s11, s11, 0xfff0
	s_sub_i32 s10, s10, s11
	s_lshl_b32 s18, s18, 2
	s_sext_i32_i16 s10, s10
	s_and_b32 s11, s18, 0xffffffc0
	s_lshl_b32 s10, s10, 6
	v_or_b32_e32 v14, s11, v2
	v_add_u32_e32 v16, s10, v3
	v_ashrrev_i32_e32 v15, 31, v14
	v_ashrrev_i32_e32 v17, 31, v16
	v_add_u32_e32 v13, s10, v5
	v_add_u32_e32 v22, s10, v6
	v_add_u32_e32 v24, s10, v7
	v_add_u32_e32 v26, s10, v8
	v_add_u32_e32 v28, s10, v9
	v_add_u32_e32 v30, s10, v10
	v_add_u32_e32 v32, s10, v11
	v_lshl_add_u64 v[14:15], v[14:15], 2, s[6:7]
	v_lshl_add_u64 v[18:19], v[16:17], 2, s[8:9]
	v_mad_i64_i32 v[16:17], s[18:19], v16, s79, v[14:15]
	v_mad_i64_i32 v[20:21], s[18:19], v13, s79, v[14:15]
	v_mad_i64_i32 v[22:23], s[18:19], v22, s79, v[14:15]
	v_mad_i64_i32 v[24:25], s[18:19], v24, s79, v[14:15]
	v_mad_i64_i32 v[26:27], s[18:19], v26, s79, v[14:15]
	v_mad_i64_i32 v[28:29], s[18:19], v28, s79, v[14:15]
	v_mad_i64_i32 v[30:31], s[18:19], v30, s79, v[14:15]
	v_mad_i64_i32 v[14:15], s[18:19], v32, s79, v[14:15]
	global_load_dword v13, v[18:19], off
	global_load_dword v32, v[18:19], off offset:32
	global_load_dword v33, v[18:19], off offset:64
	global_load_dword v34, v[18:19], off offset:96
	global_load_dword v35, v[18:19], off offset:128
	global_load_dword v36, v[18:19], off offset:160
	global_load_dword v37, v[18:19], off offset:192
	global_load_dword v38, v[18:19], off offset:224
	global_load_dword v39, v[16:17], off
	global_load_dword v40, v[20:21], off
	global_load_dword v41, v[22:23], off
	global_load_dword v42, v[24:25], off
	global_load_dword v43, v[26:27], off
	global_load_dword v44, v[28:29], off
	global_load_dword v45, v[30:31], off
	global_load_dword v46, v[14:15], off
	v_add_u32_e32 v14, s11, v3
	v_add_u32_e32 v16, s11, v5
	v_add_u32_e32 v18, s11, v6
	v_add_u32_e32 v20, s11, v7
	v_add_u32_e32 v22, s11, v8
	v_add_u32_e32 v24, s11, v9
	v_add_u32_e32 v26, s11, v10
	v_add_u32_e32 v28, s11, v11
	s_ashr_i32 s11, s10, 31
	v_ashrrev_i32_e32 v15, 31, v14
	v_ashrrev_i32_e32 v17, 31, v16
	v_ashrrev_i32_e32 v19, 31, v18
	v_ashrrev_i32_e32 v21, 31, v20
	v_ashrrev_i32_e32 v23, 31, v22
	v_ashrrev_i32_e32 v25, 31, v24
	v_ashrrev_i32_e32 v27, 31, v26
	v_ashrrev_i32_e32 v29, 31, v28
	v_lshl_add_u64 v[30:31], s[10:11], 1, v[0:1]
	v_lshlrev_b64 v[14:15], 11, v[14:15]
	v_lshlrev_b64 v[16:17], 11, v[16:17]
	v_lshlrev_b64 v[18:19], 11, v[18:19]
	v_lshlrev_b64 v[20:21], 11, v[20:21]
	v_lshlrev_b64 v[22:23], 11, v[22:23]
	v_lshlrev_b64 v[24:25], 11, v[24:25]
	v_lshlrev_b64 v[26:27], 11, v[26:27]
	v_lshlrev_b64 v[28:29], 11, v[28:29]
	v_lshl_add_u64 v[14:15], v[30:31], 0, v[14:15]
	v_lshl_add_u64 v[16:17], v[30:31], 0, v[16:17]
	v_lshl_add_u64 v[18:19], v[30:31], 0, v[18:19]
	v_lshl_add_u64 v[20:21], v[30:31], 0, v[20:21]
	v_lshl_add_u64 v[22:23], v[30:31], 0, v[22:23]
	v_lshl_add_u64 v[24:25], v[30:31], 0, v[24:25]
	v_lshl_add_u64 v[26:27], v[30:31], 0, v[26:27]
	v_lshl_add_u64 v[28:29], v[30:31], 0, v[28:29]
	s_branch .Lcv319_n0

; __device__ __forceinline__ bf16_t f2bf(float f) { unsigned u = __float_as_uint(f); u += 0x7FFFu + ((u >> 16) & 1u); return (bf16_t)(u >> 16); }
;     ...
;     for (int t_ = first; t_ < ntile * ((REP & 1) + 1); t_ += gridDim.x) { const int t = t_ % ntile;
;         const int r0 = (t / nkt) * 64, k0 = (t % nkt) * 64;
;         __syncthreads();
; #pragma unroll
;         for (int i = 0; i < 8; ++i) { const int kk = i * 8 + w; tile[kk * 65 + lane] = src(k0 + kk, r0 + lane); }
;         __syncthreads();
; #pragma unroll
;         for (int i = 0; i < 8; ++i) { const int j = i * 8 + w; Bt[(size_t)(r0 + j) * ld + k0 + lane] = f2bf(tile[lane * 65 + j]); }
; __device__ void convert_phase(unsigned char* smem, const Params& p, int l) {
;     ...
;     { const float* wgt = ((const float*)ldp(26)) + (size_t)l * DM * 3072; const float* gn = ((const float*)ldp(5)) + l * DM; conv_tiles(tile, wt + W_GATE, 3072, 1024, 151, [=](int k, int r) { return gn[k] * wgt[(size_t)k * 3072 + r]; }); }
.Lcv319_n0:
	s_add_i32 s17, s17, s5
	s_cmp_lt_i32 s17, 0x300
	s_cbranch_scc0 .LBB0_320
	s_barrier
	s_waitcnt vmcnt(31)
	v_mul_f32_e32 v53, v53, v79
	s_waitcnt vmcnt(30)
	v_mul_f32_e32 v70, v72, v80
	s_waitcnt vmcnt(29)
	v_mul_f32_e32 v71, v73, v81
	s_waitcnt vmcnt(28)
	v_mul_f32_e32 v72, v74, v82
	s_waitcnt vmcnt(27)
	v_mul_f32_e32 v73, v75, v83
	s_waitcnt vmcnt(26)
	v_mul_f32_e32 v74, v76, v84
	s_waitcnt vmcnt(25)
	v_mul_f32_e32 v75, v77, v85
	s_waitcnt vmcnt(24)
	v_mul_f32_e32 v76, v78, v86
	ds_write_b32 v12, v53
	ds_write_b32 v12, v70 offset:2080
	ds_write_b32 v12, v71 offset:4160
	ds_write_b32 v12, v72 offset:6240
	ds_write_b32 v12, v73 offset:8320
	ds_write_b32 v12, v74 offset:10400
	ds_write_b32 v12, v75 offset:12480
	ds_write_b32 v12, v76 offset:14560
	s_waitcnt lgkmcnt(0)
	s_barrier
	ds_read2_b32 v[70:71], v4 offset1:8
	ds_read2_b32 v[72:73], v4 offset0:16 offset1:24
	ds_read2_b32 v[74:75], v4 offset0:32 offset1:40
	ds_read2_b32 v[76:77], v4 offset0:48 offset1:56
	s_waitcnt lgkmcnt(3)
	v_bfe_u32 v53, v70, 16, 1
	v_bfe_u32 v78, v71, 16, 1
	s_waitcnt lgkmcnt(2)
	v_bfe_u32 v79, v72, 16, 1
	v_bfe_u32 v80, v73, 16, 1
	s_waitcnt lgkmcnt(1)
	v_bfe_u32 v81, v74, 16, 1
	v_bfe_u32 v82, v75, 16, 1
	s_waitcnt lgkmcnt(0)
	v_bfe_u32 v83, v76, 16, 1
	v_bfe_u32 v84, v77, 16, 1
	v_add3_u32 v53, v70, v53, s88
	v_add3_u32 v70, v71, v78, s88
	v_add3_u32 v71, v72, v79, s88
	v_add3_u32 v72, v73, v80, s88
	v_add3_u32 v73, v74, v81, s88
	v_add3_u32 v74, v75, v82, s88
	v_add3_u32 v75, v76, v83, s88
	v_add3_u32 v76, v77, v84, s88
	global_store_short_d16_hi v[54:55], v53, off
	global_store_short_d16_hi v[56:57], v70, off
	global_store_short_d16_hi v[58:59], v71, off
	global_store_short_d16_hi v[60:61], v72, off
	global_store_short_d16_hi v[62:63], v73, off
	global_store_short_d16_hi v[64:65], v74, off
	global_store_short_d16_hi v[66:67], v75, off
	global_store_short_d16_hi v[68:69], v76, off
	s_lshl_b32 s98, s5, 1
	s_add_i32 s98, s98, s17
	s_cmp_lt_i32 s98, 0x300
	s_cbranch_scc0 .Lcv319_s1
	s_mul_hi_i32 s10, s98, 0x2aaaaaab
	s_lshr_b32 s11, s10, 31
	s_lshr_b32 s10, s10, 7
	s_add_i32 s10, s10, s11
	s_mulk_i32 s10, 0x300
	s_sub_i32 s10, s98, s10
	s_sext_i32_i16 s11, s10
	s_bfe_u32 s11, s11, 0x4001b
	s_add_i32 s11, s10, s11
	s_sext_i32_i16 s18, s11
	s_and_b32 s11, s11, 0xfff0
	s_sub_i32 s10, s10, s11
	s_lshl_b32 s18, s18, 2
	s_sext_i32_i16 s10, s10
	s_and_b32 s11, s18, 0xffffffc0
	s_lshl_b32 s10, s10, 6
	v_or_b32_e32 v54, s11, v2
	v_add_u32_e32 v56, s10, v3
	v_ashrrev_i32_e32 v55, 31, v54
	v_ashrrev_i32_e32 v57, 31, v56
	v_add_u32_e32 v53, s10, v5
	v_add_u32_e32 v62, s10, v6
	v_add_u32_e32 v64, s10, v7
	v_add_u32_e32 v66, s10, v8
	v_add_u32_e32 v68, s10, v9
	v_add_u32_e32 v70, s10, v10
	v_add_u32_e32 v72, s10, v11
	v_lshl_add_u64 v[54:55], v[54:55], 2, s[6:7]
	v_lshl_add_u64 v[58:59], v[56:57], 2, s[8:9]
	v_mad_i64_i32 v[56:57], s[18:19], v56, s79, v[54:55]
	v_mad_i64_i32 v[60:61], s[18:19], v53, s79, v[54:55]
	v_mad_i64_i32 v[62:63], s[18:19], v62, s79, v[54:55]
	v_mad_i64_i32 v[64:65], s[18:19], v64, s79, v[54:55]
	v_mad_i64_i32 v[66:67], s[18:19], v66, s79, v[54:55]
	v_mad_i64_i32 v[68:69], s[18:19], v68, s79, v[54:55]
	v_mad_i64_i32 v[70:71], s[18:19], v70, s79, v[54:55]
	v_mad_i64_i32 v[54:55], s[18:19], v72, s79, v[54:55]
	global_load_dword v53, v[58:59], off
	global_load_dword v72, v[58:59], off offset:32
	global_load_dword v73, v[58:59], off offset:64
	global_load_dword v74, v[58:59], off offset:96
	global_load_dword v75, v[58:59], off offset:128
	global_load_dword v76, v[58:59], off offset:160
	global_load_dword v77, v[58:59], off offset:192
	global_load_dword v78, v[58:59], off offset:224
	global_load_dword v79, v[56:57], off
	global_load_dword v80, v[60:61], off
	global_load_dword v81, v[62:63], off
	global_load_dword v82, v[64:65], off
	global_load_dword v83, v[66:67], off
	global_load_dword v84, v[68:69], off
	global_load_dword v85, v[70:71], off
	global_load_dword v86, v[54:55], off
	v_add_u32_e32 v54, s11, v3
	v_add_u32_e32 v56, s11, v5
	v_add_u32_e32 v58, s11, v6
	v_add_u32_e32 v60, s11, v7
	v_add_u32_e32 v62, s11, v8
	v_add_u32_e32 v64, s11, v9
	v_add_u32_e32 v66, s11, v10
	v_add_u32_e32 v68, s11, v11
	s_ashr_i32 s11, s10, 31
	v_ashrrev_i32_e32 v55, 31, v54
	v_ashrrev_i32_e32 v57, 31, v56
	v_ashrrev_i32_e32 v59, 31, v58
	v_ashrrev_i32_e32 v61, 31, v60
	v_ashrrev_i32_e32 v63, 31, v62
	v_ashrrev_i32_e32 v65, 31, v64
	v_ashrrev_i32_e32 v67, 31, v66
	v_ashrrev_i32_e32 v69, 31, v68
	v_lshl_add_u64 v[70:71], s[10:11], 1, v[0:1]
	v_lshlrev_b64 v[54:55], 11, v[54:55]
	v_lshlrev_b64 v[56:57], 11, v[56:57]
	v_lshlrev_b64 v[58:59], 11, v[58:59]
	v_lshlrev_b64 v[60:61], 11, v[60:61]
	v_lshlrev_b64 v[62:63], 11, v[62:63]
	v_lshlrev_b64 v[64:65], 11, v[64:65]
	v_lshlrev_b64 v[66:67], 11, v[66:67]
	v_lshlrev_b64 v[68:69], 11, v[68:69]
	v_lshl_add_u64 v[54:55], v[70:71], 0, v[54:55]
	v_lshl_add_u64 v[56:57], v[70:71], 0, v[56:57]
	v_lshl_add_u64 v[58:59], v[70:71], 0, v[58:59]
	v_lshl_add_u64 v[60:61], v[70:71], 0, v[60:61]
	v_lshl_add_u64 v[62:63], v[70:71], 0, v[62:63]
	v_lshl_add_u64 v[64:65], v[70:71], 0, v[64:65]
	v_lshl_add_u64 v[66:67], v[70:71], 0, v[66:67]
	v_lshl_add_u64 v[68:69], v[70:71], 0, v[68:69]
	s_branch .Lcv319_n1

;     ...
;     for (int t_ = first; t_ < ntile * ((REP & 1) + 1); t_ += gridDim.x) { const int t = t_ % ntile;
.Lcv319_n1:
	s_add_i32 s17, s17, s5
	s_cmp_lt_i32 s17, 0x300
	s_cbranch_scc1 .Lcv319_top

; __device__ __forceinline__ bf16_t f2bf(float f) { unsigned u = __float_as_uint(f); u += 0x7FFFu + ((u >> 16) & 1u); return (bf16_t)(u >> 16); }
;     ...
;     for (int t_ = first; t_ < ntile * ((REP & 1) + 1); t_ += gridDim.x) { const int t = t_ % ntile;
;         const int r0 = (t / nkt) * 64, k0 = (t % nkt) * 64;
;         __syncthreads();
; #pragma unroll
;         for (int i = 0; i < 8; ++i) { const int kk = i * 8 + w; tile[kk * 65 + lane] = src(k0 + kk, r0 + lane); }
;         __syncthreads();
; #pragma unroll
;         for (int i = 0; i < 8; ++i) { const int j = i * 8 + w; Bt[(size_t)(r0 + j) * ld + k0 + lane] = f2bf(tile[lane * 65 + j]); }
;     }
; __device__ void convert_phase(unsigned char* smem, const Params& p, int l) {
;     ...
;       conv_tiles(tile, wt + W_UP2, 5632, 1024, 53, [=](int k, int r) { const int col = (r >> 5) * 16 + (r & 15); return gn[k] * (((r >> 4) & 1) ? wu[(size_t)k * DFF + col] : wg[(size_t)k * DFF + col]); }); }
.LBB0_334:
	s_mov_b32 s98, s10
	s_mul_hi_i32 s8, s98, 0x2e8ba2e9
	s_lshr_b32 s9, s8, 31
	s_ashr_i32 s8, s8, 8
	s_add_i32 s8, s8, s9
	s_mulk_i32 s8, 0x580
	s_sub_i32 s8, s98, s8
	s_sext_i32_i16 s9, s8
	s_bfe_u32 s9, s9, 0x4001b
	s_add_i32 s9, s8, s9
	s_sext_i32_i16 s11, s9
	s_lshl_b32 s11, s11, 2
	s_and_b32 s9, s9, 0xfff0
	s_andn2_b32 s11, s11, 63
	s_sub_i32 s8, s8, s9
	v_or_b32_e32 v16, s11, v4
	s_sext_i32_i16 s8, s8
	v_ashrrev_i32_e32 v17, 1, v16
	s_lshl_b32 s8, s8, 6
	v_and_or_b32 v18, v17, -16, v6
	v_add_u32_e32 v16, s8, v5
	v_ashrrev_i32_e32 v19, 31, v18
	v_ashrrev_i32_e32 v17, 31, v16
	v_lshl_add_u64 v[18:19], v[18:19], 2, v[0:1]
	v_add_u32_e32 v22, s8, v8
	v_add_u32_e32 v23, s8, v9
	v_add_u32_e32 v24, s8, v10
	v_add_u32_e32 v26, s8, v11
	v_add_u32_e32 v28, s8, v12
	v_add_u32_e32 v30, s8, v13
	v_add_u32_e32 v32, s8, v14
	v_lshl_add_u64 v[20:21], v[16:17], 2, s[6:7]
	v_mad_i64_i32 v[16:17], s[16:17], v16, s33, v[18:19]
	global_load_dword v34, v[20:21], off
	global_load_dword v35, v[20:21], off offset:32
	global_load_dword v36, v[20:21], off offset:64
	global_load_dword v37, v[20:21], off offset:96
	global_load_dword v38, v[20:21], off offset:128
	global_load_dword v39, v[20:21], off offset:160
	global_load_dword v40, v[20:21], off offset:192
	global_load_dword v41, v[20:21], off offset:224
	v_mad_i64_i32 v[20:21], s[16:17], v22, s33, v[18:19]
	v_mad_i64_i32 v[22:23], s[16:17], v23, s33, v[18:19]
	v_mad_i64_i32 v[24:25], s[16:17], v24, s33, v[18:19]
	v_mad_i64_i32 v[26:27], s[16:17], v26, s33, v[18:19]
	v_mad_i64_i32 v[28:29], s[16:17], v28, s33, v[18:19]
	v_mad_i64_i32 v[30:31], s[16:17], v30, s33, v[18:19]
	v_mad_i64_i32 v[18:19], s[16:17], v32, s33, v[18:19]
	global_load_dword v42, v[16:17], off
	global_load_dword v43, v[20:21], off
	global_load_dword v44, v[22:23], off
	global_load_dword v45, v[24:25], off
	global_load_dword v46, v[26:27], off
	global_load_dword v47, v[28:29], off
	global_load_dword v48, v[30:31], off
	global_load_dword v49, v[18:19], off
	v_add_u32_e32 v16, s11, v5
	v_add_u32_e32 v18, s11, v8
	v_add_u32_e32 v20, s11, v9
	v_add_u32_e32 v22, s11, v10
	v_add_u32_e32 v24, s11, v11
	v_add_u32_e32 v26, s11, v12
	v_add_u32_e32 v28, s11, v13
	v_add_u32_e32 v30, s11, v14
	s_ashr_i32 s9, s8, 31
	v_ashrrev_i32_e32 v17, 31, v16
	v_ashrrev_i32_e32 v19, 31, v18
	v_ashrrev_i32_e32 v21, 31, v20
	v_ashrrev_i32_e32 v23, 31, v22
	v_ashrrev_i32_e32 v25, 31, v24
	v_ashrrev_i32_e32 v27, 31, v26
	v_ashrrev_i32_e32 v29, 31, v28
	v_ashrrev_i32_e32 v31, 31, v30
	v_lshl_add_u64 v[32:33], s[8:9], 1, v[2:3]
	v_lshlrev_b64 v[16:17], 11, v[16:17]
	v_lshlrev_b64 v[18:19], 11, v[18:19]
	v_lshlrev_b64 v[20:21], 11, v[20:21]
	v_lshlrev_b64 v[22:23], 11, v[22:23]
	v_lshlrev_b64 v[24:25], 11, v[24:25]
	v_lshlrev_b64 v[26:27], 11, v[26:27]
	v_lshlrev_b64 v[28:29], 11, v[28:29]
	v_lshlrev_b64 v[30:31], 11, v[30:31]
	v_lshl_add_u64 v[16:17], v[32:33], 0, v[16:17]
	v_lshl_add_u64 v[18:19], v[32:33], 0, v[18:19]
	v_lshl_add_u64 v[20:21], v[32:33], 0, v[20:21]
	v_lshl_add_u64 v[22:23], v[32:33], 0, v[22:23]
	v_lshl_add_u64 v[24:25], v[32:33], 0, v[24:25]
	v_lshl_add_u64 v[26:27], v[32:33], 0, v[26:27]
	v_lshl_add_u64 v[28:29], v[32:33], 0, v[28:29]
	v_lshl_add_u64 v[30:31], v[32:33], 0, v[30:31]
	s_add_i32 s98, s10, s5
	s_cmp_lt_i32 s98, 0x580
	s_cbranch_scc0 .Lcv334_p1skip
	s_mul_hi_i32 s8, s98, 0x2e8ba2e9
	s_lshr_b32 s9, s8, 31
	s_ashr_i32 s8, s8, 8
	s_add_i32 s8, s8, s9
	s_mulk_i32 s8, 0x580
	s_sub_i32 s8, s98, s8
	s_sext_i32_i16 s9, s8
	s_bfe_u32 s9, s9, 0x4001b
	s_add_i32 s9, s8, s9
	s_sext_i32_i16 s11, s9
	s_lshl_b32 s11, s11, 2
	s_and_b32 s9, s9, 0xfff0
	s_andn2_b32 s11, s11, 63
	s_sub_i32 s8, s8, s9
	v_or_b32_e32 v56, s11, v4
	s_sext_i32_i16 s8, s8
	v_ashrrev_i32_e32 v57, 1, v56
	s_lshl_b32 s8, s8, 6
	v_and_or_b32 v58, v57, -16, v6
	v_add_u32_e32 v56, s8, v5
	v_ashrrev_i32_e32 v59, 31, v58
	v_ashrrev_i32_e32 v57, 31, v56
	v_lshl_add_u64 v[58:59], v[58:59], 2, v[0:1]
	v_add_u32_e32 v62, s8, v8
	v_add_u32_e32 v63, s8, v9
	v_add_u32_e32 v64, s8, v10
	v_add_u32_e32 v66, s8, v11
	v_add_u32_e32 v68, s8, v12
	v_add_u32_e32 v70, s8, v13
	v_add_u32_e32 v72, s8, v14
	v_lshl_add_u64 v[60:61], v[56:57], 2, s[6:7]
	v_mad_i64_i32 v[56:57], s[16:17], v56, s33, v[58:59]
	global_load_dword v74, v[60:61], off
	global_load_dword v75, v[60:61], off offset:32
	global_load_dword v76, v[60:61], off offset:64
	global_load_dword v77, v[60:61], off offset:96
	global_load_dword v78, v[60:61], off offset:128
	global_load_dword v79, v[60:61], off offset:160
	global_load_dword v80, v[60:61], off offset:192
	global_load_dword v81, v[60:61], off offset:224
	v_mad_i64_i32 v[60:61], s[16:17], v62, s33, v[58:59]
	v_mad_i64_i32 v[62:63], s[16:17], v63, s33, v[58:59]
	v_mad_i64_i32 v[64:65], s[16:17], v64, s33, v[58:59]
	v_mad_i64_i32 v[66:67], s[16:17], v66, s33, v[58:59]
	v_mad_i64_i32 v[68:69], s[16:17], v68, s33, v[58:59]
	v_mad_i64_i32 v[70:71], s[16:17], v70, s33, v[58:59]
	v_mad_i64_i32 v[58:59], s[16:17], v72, s33, v[58:59]
	global_load_dword v82, v[56:57], off
	global_load_dword v83, v[60:61], off
	global_load_dword v84, v[62:63], off
	global_load_dword v85, v[64:65], off
	global_load_dword v86, v[66:67], off
	global_load_dword v87, v[68:69], off
	global_load_dword v88, v[70:71], off
	global_load_dword v89, v[58:59], off
	v_add_u32_e32 v56, s11, v5
	v_add_u32_e32 v58, s11, v8
	v_add_u32_e32 v60, s11, v9
	v_add_u32_e32 v62, s11, v10
	v_add_u32_e32 v64, s11, v11
	v_add_u32_e32 v66, s11, v12
	v_add_u32_e32 v68, s11, v13
	v_add_u32_e32 v70, s11, v14
	s_ashr_i32 s9, s8, 31
	v_ashrrev_i32_e32 v57, 31, v56
	v_ashrrev_i32_e32 v59, 31, v58
	v_ashrrev_i32_e32 v61, 31, v60
	v_ashrrev_i32_e32 v63, 31, v62
	v_ashrrev_i32_e32 v65, 31, v64
	v_ashrrev_i32_e32 v67, 31, v66
	v_ashrrev_i32_e32 v69, 31, v68
	v_ashrrev_i32_e32 v71, 31, v70
	v_lshl_add_u64 v[72:73], s[8:9], 1, v[2:3]
	v_lshlrev_b64 v[56:57], 11, v[56:57]
	v_lshlrev_b64 v[58:59], 11, v[58:59]
	v_lshlrev_b64 v[60:61], 11, v[60:61]
	v_lshlrev_b64 v[62:63], 11, v[62:63]
	v_lshlrev_b64 v[64:65], 11, v[64:65]
	v_lshlrev_b64 v[66:67], 11, v[66:67]
	v_lshlrev_b64 v[68:69], 11, v[68:69]
	v_lshlrev_b64 v[70:71], 11, v[70:71]
	v_lshl_add_u64 v[56:57], v[72:73], 0, v[56:57]
	v_lshl_add_u64 v[58:59], v[72:73], 0, v[58:59]
	v_lshl_add_u64 v[60:61], v[72:73], 0, v[60:61]
	v_lshl_add_u64 v[62:63], v[72:73], 0, v[62:63]
	v_lshl_add_u64 v[64:65], v[72:73], 0, v[64:65]
	v_lshl_add_u64 v[66:67], v[72:73], 0, v[66:67]
	v_lshl_add_u64 v[68:69], v[72:73], 0, v[68:69]
	v_lshl_add_u64 v[70:71], v[72:73], 0, v[70:71]
	s_waitcnt vmcnt(16)
	s_branch .Lcv334_top

; __device__ __forceinline__ bf16_t f2bf(float f) { unsigned u = __float_as_uint(f); u += 0x7FFFu + ((u >> 16) & 1u); return (bf16_t)(u >> 16); }
;     ...
;     for (int t_ = first; t_ < ntile * ((REP & 1) + 1); t_ += gridDim.x) { const int t = t_ % ntile;
;         const int r0 = (t / nkt) * 64, k0 = (t % nkt) * 64;
;         __syncthreads();
; #pragma unroll
;         for (int i = 0; i < 8; ++i) { const int kk = i * 8 + w; tile[kk * 65 + lane] = src(k0 + kk, r0 + lane); }
;         __syncthreads();
; #pragma unroll
;         for (int i = 0; i < 8; ++i) { const int j = i * 8 + w; Bt[(size_t)(r0 + j) * ld + k0 + lane] = f2bf(tile[lane * 65 + j]); }
; __device__ void convert_phase(unsigned char* smem, const Params& p, int l) {
;     ...
;       conv_tiles(tile, wt + W_UP2, 5632, 1024, 53, [=](int k, int r) { const int col = (r >> 5) * 16 + (r & 15); return gn[k] * (((r >> 4) & 1) ? wu[(size_t)k * DFF + col] : wg[(size_t)k * DFF + col]); }); }
.Lcv334_top:
	s_barrier
	s_waitcnt vmcnt(31)
	v_mul_f32_e32 v32, v34, v42
	s_waitcnt vmcnt(30)
	v_mul_f32_e32 v33, v35, v43
	s_waitcnt vmcnt(29)
	v_mul_f32_e32 v34, v36, v44
	s_waitcnt vmcnt(28)
	v_mul_f32_e32 v35, v37, v45
	s_waitcnt vmcnt(27)
	v_mul_f32_e32 v36, v38, v46
	s_waitcnt vmcnt(26)
	v_mul_f32_e32 v37, v39, v47
	s_waitcnt vmcnt(25)
	v_mul_f32_e32 v38, v40, v48
	s_waitcnt vmcnt(24)
	v_mul_f32_e32 v39, v41, v49
	ds_write_b32 v15, v32
	ds_write_b32 v15, v33 offset:2080
	ds_write_b32 v15, v34 offset:4160
	ds_write_b32 v15, v35 offset:6240
	ds_write_b32 v15, v36 offset:8320
	ds_write_b32 v15, v37 offset:10400
	ds_write_b32 v15, v38 offset:12480
	ds_write_b32 v15, v39 offset:14560
	s_waitcnt lgkmcnt(0)
	s_barrier
	ds_read2_b32 v[32:33], v7 offset1:8
	ds_read2_b32 v[34:35], v7 offset0:16 offset1:24
	ds_read2_b32 v[36:37], v7 offset0:32 offset1:40
	ds_read2_b32 v[38:39], v7 offset0:48 offset1:56
	s_waitcnt lgkmcnt(3)
	v_bfe_u32 v40, v32, 16, 1
	v_bfe_u32 v41, v33, 16, 1
	s_waitcnt lgkmcnt(2)
	v_bfe_u32 v42, v34, 16, 1
	v_bfe_u32 v43, v35, 16, 1
	s_waitcnt lgkmcnt(1)
	v_bfe_u32 v44, v36, 16, 1
	v_bfe_u32 v45, v37, 16, 1
	s_waitcnt lgkmcnt(0)
	v_bfe_u32 v46, v38, 16, 1
	v_bfe_u32 v47, v39, 16, 1
	v_add3_u32 v32, v32, v40, s88
	v_add3_u32 v33, v33, v41, s88
	v_add3_u32 v34, v34, v42, s88
	v_add3_u32 v35, v35, v43, s88
	v_add3_u32 v36, v36, v44, s88
	v_add3_u32 v37, v37, v45, s88
	v_add3_u32 v38, v38, v46, s88
	v_add3_u32 v39, v39, v47, s88
	global_store_short_d16_hi v[16:17], v32, off
	global_store_short_d16_hi v[18:19], v33, off
	global_store_short_d16_hi v[20:21], v34, off
	global_store_short_d16_hi v[22:23], v35, off
	global_store_short_d16_hi v[24:25], v36, off
	global_store_short_d16_hi v[26:27], v37, off
	global_store_short_d16_hi v[28:29], v38, off
	global_store_short_d16_hi v[30:31], v39, off
	s_lshl_b32 s98, s5, 1
	s_add_i32 s98, s98, s10
	s_cmp_lt_i32 s98, 0x580
	s_cbranch_scc0 .Lcv334_s0
	s_mul_hi_i32 s8, s98, 0x2e8ba2e9
	s_lshr_b32 s9, s8, 31
	s_ashr_i32 s8, s8, 8
	s_add_i32 s8, s8, s9
	s_mulk_i32 s8, 0x580
	s_sub_i32 s8, s98, s8
	s_sext_i32_i16 s9, s8
	s_bfe_u32 s9, s9, 0x4001b
	s_add_i32 s9, s8, s9
	s_sext_i32_i16 s11, s9
	s_lshl_b32 s11, s11, 2
	s_and_b32 s9, s9, 0xfff0
	s_andn2_b32 s11, s11, 63
	s_sub_i32 s8, s8, s9
	v_or_b32_e32 v16, s11, v4
	s_sext_i32_i16 s8, s8
	v_ashrrev_i32_e32 v17, 1, v16
	s_lshl_b32 s8, s8, 6
	v_and_or_b32 v18, v17, -16, v6
	v_add_u32_e32 v16, s8, v5
	v_ashrrev_i32_e32 v19, 31, v18
	v_ashrrev_i32_e32 v17, 31, v16
	v_lshl_add_u64 v[18:19], v[18:19], 2, v[0:1]
	v_add_u32_e32 v22, s8, v8
	v_add_u32_e32 v23, s8, v9
	v_add_u32_e32 v24, s8, v10
	v_add_u32_e32 v26, s8, v11
	v_add_u32_e32 v28, s8, v12
	v_add_u32_e32 v30, s8, v13
	v_add_u32_e32 v32, s8, v14
	v_lshl_add_u64 v[20:21], v[16:17], 2, s[6:7]
	v_mad_i64_i32 v[16:17], s[16:17], v16, s33, v[18:19]
	global_load_dword v34, v[20:21], off
	global_load_dword v35, v[20:21], off offset:32
	global_load_dword v36, v[20:21], off offset:64
	global_load_dword v37, v[20:21], off offset:96
	global_load_dword v38, v[20:21], off offset:128
	global_load_dword v39, v[20:21], off offset:160
	global_load_dword v40, v[20:21], off offset:192
	global_load_dword v41, v[20:21], off offset:224
	v_mad_i64_i32 v[20:21], s[16:17], v22, s33, v[18:19]
	v_mad_i64_i32 v[22:23], s[16:17], v23, s33, v[18:19]
	v_mad_i64_i32 v[24:25], s[16:17], v24, s33, v[18:19]
	v_mad_i64_i32 v[26:27], s[16:17], v26, s33, v[18:19]
	v_mad_i64_i32 v[28:29], s[16:17], v28, s33, v[18:19]
	v_mad_i64_i32 v[30:31], s[16:17], v30, s33, v[18:19]
	v_mad_i64_i32 v[18:19], s[16:17], v32, s33, v[18:19]
	global_load_dword v42, v[16:17], off
	global_load_dword v43, v[20:21], off
	global_load_dword v44, v[22:23], off
	global_load_dword v45, v[24:25], off
	global_load_dword v46, v[26:27], off
	global_load_dword v47, v[28:29], off
	global_load_dword v48, v[30:31], off
	global_load_dword v49, v[18:19], off
	v_add_u32_e32 v16, s11, v5
	v_add_u32_e32 v18, s11, v8
	v_add_u32_e32 v20, s11, v9
	v_add_u32_e32 v22, s11, v10
	v_add_u32_e32 v24, s11, v11
	v_add_u32_e32 v26, s11, v12
	v_add_u32_e32 v28, s11, v13
	v_add_u32_e32 v30, s11, v14
	s_ashr_i32 s9, s8, 31
	v_ashrrev_i32_e32 v17, 31, v16
	v_ashrrev_i32_e32 v19, 31, v18
	v_ashrrev_i32_e32 v21, 31, v20
	v_ashrrev_i32_e32 v23, 31, v22
	v_ashrrev_i32_e32 v25, 31, v24
	v_ashrrev_i32_e32 v27, 31, v26
	v_ashrrev_i32_e32 v29, 31, v28
	v_ashrrev_i32_e32 v31, 31, v30
	v_lshl_add_u64 v[32:33], s[8:9], 1, v[2:3]
	v_lshlrev_b64 v[16:17], 11, v[16:17]
	v_lshlrev_b64 v[18:19], 11, v[18:19]
	v_lshlrev_b64 v[20:21], 11, v[20:21]
	v_lshlrev_b64 v[22:23], 11, v[22:23]
	v_lshlrev_b64 v[24:25], 11, v[24:25]
	v_lshlrev_b64 v[26:27], 11, v[26:27]
	v_lshlrev_b64 v[28:29], 11, v[28:29]
	v_lshlrev_b64 v[30:31], 11, v[30:31]
	v_lshl_add_u64 v[16:17], v[32:33], 0, v[16:17]
	v_lshl_add_u64 v[18:19], v[32:33], 0, v[18:19]
	v_lshl_add_u64 v[20:21], v[32:33], 0, v[20:21]
	v_lshl_add_u64 v[22:23], v[32:33], 0, v[22:23]
	v_lshl_add_u64 v[24:25], v[32:33], 0, v[24:25]
	v_lshl_add_u64 v[26:27], v[32:33], 0, v[26:27]
	v_lshl_add_u64 v[28:29], v[32:33], 0, v[28:29]
	v_lshl_add_u64 v[30:31], v[32:33], 0, v[30:31]
	s_branch .Lcv334_n0

; __device__ __forceinline__ bf16_t f2bf(float f) { unsigned u = __float_as_uint(f); u += 0x7FFFu + ((u >> 16) & 1u); return (bf16_t)(u >> 16); }
;     ...
;     for (int t_ = first; t_ < ntile * ((REP & 1) + 1); t_ += gridDim.x) { const int t = t_ % ntile;
;         const int r0 = (t / nkt) * 64, k0 = (t % nkt) * 64;
;         __syncthreads();
; #pragma unroll
;         for (int i = 0; i < 8; ++i) { const int kk = i * 8 + w; tile[kk * 65 + lane] = src(k0 + kk, r0 + lane); }
;         __syncthreads();
; #pragma unroll
;         for (int i = 0; i < 8; ++i) { const int j = i * 8 + w; Bt[(size_t)(r0 + j) * ld + k0 + lane] = f2bf(tile[lane * 65 + j]); }
; __device__ void convert_phase(unsigned char* smem, const Params& p, int l) {
;     ...
;       conv_tiles(tile, wt + W_UP2, 5632, 1024, 53, [=](int k, int r) { const int col = (r >> 5) * 16 + (r & 15); return gn[k] * (((r >> 4) & 1) ? wu[(size_t)k * DFF + col] : wg[(size_t)k * DFF + col]); }); }
.Lcv334_n0:
	s_add_i32 s10, s10, s5
	s_cmp_lt_i32 s10, 0x580
	s_cbranch_scc0 .LBB0_335
	s_barrier
	s_waitcnt vmcnt(31)
	v_mul_f32_e32 v72, v74, v82
	s_waitcnt vmcnt(30)
	v_mul_f32_e32 v73, v75, v83
	s_waitcnt vmcnt(29)
	v_mul_f32_e32 v74, v76, v84
	s_waitcnt vmcnt(28)
	v_mul_f32_e32 v75, v77, v85
	s_waitcnt vmcnt(27)
	v_mul_f32_e32 v76, v78, v86
	s_waitcnt vmcnt(26)
	v_mul_f32_e32 v77, v79, v87
	s_waitcnt vmcnt(25)
	v_mul_f32_e32 v78, v80, v88
	s_waitcnt vmcnt(24)
	v_mul_f32_e32 v79, v81, v89
	ds_write_b32 v15, v72
	ds_write_b32 v15, v73 offset:2080
	ds_write_b32 v15, v74 offset:4160
	ds_write_b32 v15, v75 offset:6240
	ds_write_b32 v15, v76 offset:8320
	ds_write_b32 v15, v77 offset:10400
	ds_write_b32 v15, v78 offset:12480
	ds_write_b32 v15, v79 offset:14560
	s_waitcnt lgkmcnt(0)
	s_barrier
	ds_read2_b32 v[72:73], v7 offset1:8
	ds_read2_b32 v[74:75], v7 offset0:16 offset1:24
	ds_read2_b32 v[76:77], v7 offset0:32 offset1:40
	ds_read2_b32 v[78:79], v7 offset0:48 offset1:56
	s_waitcnt lgkmcnt(3)
	v_bfe_u32 v80, v72, 16, 1
	v_bfe_u32 v81, v73, 16, 1
	s_waitcnt lgkmcnt(2)
	v_bfe_u32 v82, v74, 16, 1
	v_bfe_u32 v83, v75, 16, 1
	s_waitcnt lgkmcnt(1)
	v_bfe_u32 v84, v76, 16, 1
	v_bfe_u32 v85, v77, 16, 1
	s_waitcnt lgkmcnt(0)
	v_bfe_u32 v86, v78, 16, 1
	v_bfe_u32 v87, v79, 16, 1
	v_add3_u32 v72, v72, v80, s88
	v_add3_u32 v73, v73, v81, s88
	v_add3_u32 v74, v74, v82, s88
	v_add3_u32 v75, v75, v83, s88
	v_add3_u32 v76, v76, v84, s88
	v_add3_u32 v77, v77, v85, s88
	v_add3_u32 v78, v78, v86, s88
	v_add3_u32 v79, v79, v87, s88
	global_store_short_d16_hi v[56:57], v72, off
	global_store_short_d16_hi v[58:59], v73, off
	global_store_short_d16_hi v[60:61], v74, off
	global_store_short_d16_hi v[62:63], v75, off
	global_store_short_d16_hi v[64:65], v76, off
	global_store_short_d16_hi v[66:67], v77, off
	global_store_short_d16_hi v[68:69], v78, off
	global_store_short_d16_hi v[70:71], v79, off
	s_lshl_b32 s98, s5, 1
	s_add_i32 s98, s98, s10
	s_cmp_lt_i32 s98, 0x580
	s_cbranch_scc0 .Lcv334_s1
	s_mul_hi_i32 s8, s98, 0x2e8ba2e9
	s_lshr_b32 s9, s8, 31
	s_ashr_i32 s8, s8, 8
	s_add_i32 s8, s8, s9
	s_mulk_i32 s8, 0x580
	s_sub_i32 s8, s98, s8
	s_sext_i32_i16 s9, s8
	s_bfe_u32 s9, s9, 0x4001b
	s_add_i32 s9, s8, s9
	s_sext_i32_i16 s11, s9
	s_lshl_b32 s11, s11, 2
	s_and_b32 s9, s9, 0xfff0
	s_andn2_b32 s11, s11, 63
	s_sub_i32 s8, s8, s9
	v_or_b32_e32 v56, s11, v4
	s_sext_i32_i16 s8, s8
	v_ashrrev_i32_e32 v57, 1, v56
	s_lshl_b32 s8, s8, 6
	v_and_or_b32 v58, v57, -16, v6
	v_add_u32_e32 v56, s8, v5
	v_ashrrev_i32_e32 v59, 31, v58
	v_ashrrev_i32_e32 v57, 31, v56
	v_lshl_add_u64 v[58:59], v[58:59], 2, v[0:1]
	v_add_u32_e32 v62, s8, v8
	v_add_u32_e32 v63, s8, v9
	v_add_u32_e32 v64, s8, v10
	v_add_u32_e32 v66, s8, v11
	v_add_u32_e32 v68, s8, v12
	v_add_u32_e32 v70, s8, v13
	v_add_u32_e32 v72, s8, v14
	v_lshl_add_u64 v[60:61], v[56:57], 2, s[6:7]
	v_mad_i64_i32 v[56:57], s[16:17], v56, s33, v[58:59]
	global_load_dword v74, v[60:61], off
	global_load_dword v75, v[60:61], off offset:32
	global_load_dword v76, v[60:61], off offset:64
	global_load_dword v77, v[60:61], off offset:96
	global_load_dword v78, v[60:61], off offset:128
	global_load_dword v79, v[60:61], off offset:160
	global_load_dword v80, v[60:61], off offset:192
	global_load_dword v81, v[60:61], off offset:224
	v_mad_i64_i32 v[60:61], s[16:17], v62, s33, v[58:59]
	v_mad_i64_i32 v[62:63], s[16:17], v63, s33, v[58:59]
	v_mad_i64_i32 v[64:65], s[16:17], v64, s33, v[58:59]
	v_mad_i64_i32 v[66:67], s[16:17], v66, s33, v[58:59]
	v_mad_i64_i32 v[68:69], s[16:17], v68, s33, v[58:59]
	v_mad_i64_i32 v[70:71], s[16:17], v70, s33, v[58:59]
	v_mad_i64_i32 v[58:59], s[16:17], v72, s33, v[58:59]
	global_load_dword v82, v[56:57], off
	global_load_dword v83, v[60:61], off
	global_load_dword v84, v[62:63], off
	global_load_dword v85, v[64:65], off
	global_load_dword v86, v[66:67], off
	global_load_dword v87, v[68:69], off
	global_load_dword v88, v[70:71], off
	global_load_dword v89, v[58:59], off
	v_add_u32_e32 v56, s11, v5
	v_add_u32_e32 v58, s11, v8
	v_add_u32_e32 v60, s11, v9
	v_add_u32_e32 v62, s11, v10
	v_add_u32_e32 v64, s11, v11
	v_add_u32_e32 v66, s11, v12
	v_add_u32_e32 v68, s11, v13
	v_add_u32_e32 v70, s11, v14
	s_ashr_i32 s9, s8, 31
	v_ashrrev_i32_e32 v57, 31, v56
	v_ashrrev_i32_e32 v59, 31, v58
	v_ashrrev_i32_e32 v61, 31, v60
	v_ashrrev_i32_e32 v63, 31, v62
	v_ashrrev_i32_e32 v65, 31, v64
	v_ashrrev_i32_e32 v67, 31, v66
	v_ashrrev_i32_e32 v69, 31, v68
	v_ashrrev_i32_e32 v71, 31, v70
	v_lshl_add_u64 v[72:73], s[8:9], 1, v[2:3]
	v_lshlrev_b64 v[56:57], 11, v[56:57]
	v_lshlrev_b64 v[58:59], 11, v[58:59]
	v_lshlrev_b64 v[60:61], 11, v[60:61]
	v_lshlrev_b64 v[62:63], 11, v[62:63]
	v_lshlrev_b64 v[64:65], 11, v[64:65]
	v_lshlrev_b64 v[66:67], 11, v[66:67]
	v_lshlrev_b64 v[68:69], 11, v[68:69]
	v_lshlrev_b64 v[70:71], 11, v[70:71]
	v_lshl_add_u64 v[56:57], v[72:73], 0, v[56:57]
	v_lshl_add_u64 v[58:59], v[72:73], 0, v[58:59]
	v_lshl_add_u64 v[60:61], v[72:73], 0, v[60:61]
	v_lshl_add_u64 v[62:63], v[72:73], 0, v[62:63]
	v_lshl_add_u64 v[64:65], v[72:73], 0, v[64:65]
	v_lshl_add_u64 v[66:67], v[72:73], 0, v[66:67]
	v_lshl_add_u64 v[68:69], v[72:73], 0, v[68:69]
	v_lshl_add_u64 v[70:71], v[72:73], 0, v[70:71]
	s_branch .Lcv334_n1

;     ...
;     for (int t_ = first; t_ < ntile * ((REP & 1) + 1); t_ += gridDim.x) { const int t = t_ % ntile;
.Lcv334_n1:
	s_add_i32 s10, s10, s5
	s_cmp_lt_i32 s10, 0x580
	s_cbranch_scc1 .Lcv334_top

; __device__ __forceinline__ bf16_t f2bf(float f) { unsigned u = __float_as_uint(f); u += 0x7FFFu + ((u >> 16) & 1u); return (bf16_t)(u >> 16); }
;     ...
;     for (int t_ = first; t_ < ntile * ((REP & 1) + 1); t_ += gridDim.x) { const int t = t_ % ntile;
;         const int r0 = (t / nkt) * 64, k0 = (t % nkt) * 64;
;         __syncthreads();
; #pragma unroll
;         for (int i = 0; i < 8; ++i) { const int kk = i * 8 + w; tile[kk * 65 + lane] = src(k0 + kk, r0 + lane); }
;         __syncthreads();
; #pragma unroll
;         for (int i = 0; i < 8; ++i) { const int j = i * 8 + w; Bt[(size_t)(r0 + j) * ld + k0 + lane] = f2bf(tile[lane * 65 + j]); }
;     }
; __device__ void convert_phase(unsigned char* smem, const Params& p, int l) {
;     ...
;     { const float* wd = ((const float*)ldp(35)) + uo; conv_tiles(tile, wt + W_DN2, 1024, 2816, 97, [=](int k, int r) { return wd[(size_t)k * DM + r]; }); }
.LBB0_337:
	s_mov_b32 s98, s10
	s_mul_hi_i32 s8, s98, 0x2e8ba2e9
	s_lshr_b32 s9, s8, 31
	s_ashr_i32 s8, s8, 7
	s_add_i32 s8, s8, s9
	s_mulk_i32 s8, 0x2c0
	s_sub_i32 s8, s98, s8
	s_sext_i32_i16 s9, s8
	s_mulk_i32 s9, 0xba3
	s_lshr_b32 s11, s9, 31
	s_ashr_i32 s9, s9, 17
	s_add_i32 s9, s9, s11
	s_sext_i32_i16 s11, s9
	s_mul_i32 s9, s9, 44
	s_sub_i32 s8, s8, s9
	s_sext_i32_i16 s8, s8
	s_lshl_b32 s11, s11, 6
	s_lshl_b32 s8, s8, 6
	v_or_b32_e32 v14, s11, v2
	v_add_u32_e32 v16, s8, v3
	v_ashrrev_i32_e32 v15, 31, v14
	v_add_u32_e32 v18, s8, v5
	v_add_u32_e32 v20, s8, v6
	v_add_u32_e32 v22, s8, v7
	v_add_u32_e32 v24, s8, v8
	v_add_u32_e32 v26, s8, v9
	v_add_u32_e32 v28, s8, v10
	v_add_u32_e32 v30, s8, v11
	v_ashrrev_i32_e32 v17, 31, v16
	v_lshl_add_u64 v[14:15], v[14:15], 2, s[6:7]
	v_ashrrev_i32_e32 v19, 31, v18
	v_ashrrev_i32_e32 v21, 31, v20
	v_ashrrev_i32_e32 v23, 31, v22
	v_ashrrev_i32_e32 v25, 31, v24
	v_ashrrev_i32_e32 v27, 31, v26
	v_ashrrev_i32_e32 v29, 31, v28
	v_ashrrev_i32_e32 v31, 31, v30
	v_lshlrev_b64 v[16:17], 12, v[16:17]
	v_lshlrev_b64 v[18:19], 12, v[18:19]
	v_lshlrev_b64 v[20:21], 12, v[20:21]
	v_lshlrev_b64 v[22:23], 12, v[22:23]
	v_lshlrev_b64 v[24:25], 12, v[24:25]
	v_lshlrev_b64 v[26:27], 12, v[26:27]
	v_lshlrev_b64 v[28:29], 12, v[28:29]
	v_lshlrev_b64 v[30:31], 12, v[30:31]
	v_lshl_add_u64 v[16:17], v[14:15], 0, v[16:17]
	v_lshl_add_u64 v[18:19], v[14:15], 0, v[18:19]
	v_lshl_add_u64 v[20:21], v[14:15], 0, v[20:21]
	v_lshl_add_u64 v[22:23], v[14:15], 0, v[22:23]
	v_lshl_add_u64 v[24:25], v[14:15], 0, v[24:25]
	v_lshl_add_u64 v[26:27], v[14:15], 0, v[26:27]
	v_lshl_add_u64 v[28:29], v[14:15], 0, v[28:29]
	v_lshl_add_u64 v[14:15], v[14:15], 0, v[30:31]
	global_load_dword v13, v[16:17], off
	global_load_dword v30, v[18:19], off
	global_load_dword v31, v[20:21], off
	global_load_dword v32, v[22:23], off
	global_load_dword v33, v[24:25], off
	global_load_dword v34, v[26:27], off
	global_load_dword v35, v[28:29], off
	global_load_dword v36, v[14:15], off
	s_ashr_i32 s9, s8, 31
	v_add_u32_e32 v16, s11, v3
	v_add_u32_e32 v18, s11, v5
	v_add_u32_e32 v20, s11, v6
	v_add_u32_e32 v22, s11, v7
	v_add_u32_e32 v24, s11, v8
	v_add_u32_e32 v26, s11, v9
	v_add_u32_e32 v28, s11, v10
	v_add_u32_e32 v37, s11, v11
	v_lshl_add_u64 v[14:15], s[8:9], 1, v[0:1]
	v_mad_i64_i32 v[16:17], s[8:9], v16, s54, v[14:15]
	v_mad_i64_i32 v[18:19], s[8:9], v18, s54, v[14:15]
	v_mad_i64_i32 v[20:21], s[8:9], v20, s54, v[14:15]
	v_mad_i64_i32 v[22:23], s[8:9], v22, s54, v[14:15]
	v_mad_i64_i32 v[24:25], s[8:9], v24, s54, v[14:15]
	v_mad_i64_i32 v[26:27], s[8:9], v26, s54, v[14:15]
	v_mad_i64_i32 v[28:29], s[8:9], v28, s54, v[14:15]
	v_mad_i64_i32 v[14:15], s[8:9], v37, s54, v[14:15]
	s_add_i32 s98, s10, s5
	s_cmp_lt_i32 s98, 0x2c0
	s_cbranch_scc0 .Lcv337_p1skip
	s_mul_hi_i32 s8, s98, 0x2e8ba2e9
	s_lshr_b32 s9, s8, 31
	s_ashr_i32 s8, s8, 7
	s_add_i32 s8, s8, s9
	s_mulk_i32 s8, 0x2c0
	s_sub_i32 s8, s98, s8
	s_sext_i32_i16 s9, s8
	s_mulk_i32 s9, 0xba3
	s_lshr_b32 s11, s9, 31
	s_ashr_i32 s9, s9, 17
	s_add_i32 s9, s9, s11
	s_sext_i32_i16 s11, s9
	s_mul_i32 s9, s9, 44
	s_sub_i32 s8, s8, s9
	s_sext_i32_i16 s8, s8
	s_lshl_b32 s11, s11, 6
	s_lshl_b32 s8, s8, 6
	v_or_b32_e32 v54, s11, v2
	v_add_u32_e32 v56, s8, v3
	v_ashrrev_i32_e32 v55, 31, v54
	v_add_u32_e32 v58, s8, v5
	v_add_u32_e32 v60, s8, v6
	v_add_u32_e32 v62, s8, v7
	v_add_u32_e32 v64, s8, v8
	v_add_u32_e32 v66, s8, v9
	v_add_u32_e32 v68, s8, v10
	v_add_u32_e32 v70, s8, v11
	v_ashrrev_i32_e32 v57, 31, v56
	v_lshl_add_u64 v[54:55], v[54:55], 2, s[6:7]
	v_ashrrev_i32_e32 v59, 31, v58
	v_ashrrev_i32_e32 v61, 31, v60
	v_ashrrev_i32_e32 v63, 31, v62
	v_ashrrev_i32_e32 v65, 31, v64
	v_ashrrev_i32_e32 v67, 31, v66
	v_ashrrev_i32_e32 v69, 31, v68
	v_ashrrev_i32_e32 v71, 31, v70
	v_lshlrev_b64 v[56:57], 12, v[56:57]
	v_lshlrev_b64 v[58:59], 12, v[58:59]
	v_lshlrev_b64 v[60:61], 12, v[60:61]
	v_lshlrev_b64 v[62:63], 12, v[62:63]
	v_lshlrev_b64 v[64:65], 12, v[64:65]
	v_lshlrev_b64 v[66:67], 12, v[66:67]
	v_lshlrev_b64 v[68:69], 12, v[68:69]
	v_lshlrev_b64 v[70:71], 12, v[70:71]
	v_lshl_add_u64 v[56:57], v[54:55], 0, v[56:57]
	v_lshl_add_u64 v[58:59], v[54:55], 0, v[58:59]
	v_lshl_add_u64 v[60:61], v[54:55], 0, v[60:61]
	v_lshl_add_u64 v[62:63], v[54:55], 0, v[62:63]
	v_lshl_add_u64 v[64:65], v[54:55], 0, v[64:65]
	v_lshl_add_u64 v[66:67], v[54:55], 0, v[66:67]
	v_lshl_add_u64 v[68:69], v[54:55], 0, v[68:69]
	v_lshl_add_u64 v[54:55], v[54:55], 0, v[70:71]
	global_load_dword v53, v[56:57], off
	global_load_dword v70, v[58:59], off
	global_load_dword v71, v[60:61], off
	global_load_dword v72, v[62:63], off
	global_load_dword v73, v[64:65], off
	global_load_dword v74, v[66:67], off
	global_load_dword v75, v[68:69], off
	global_load_dword v76, v[54:55], off
	s_ashr_i32 s9, s8, 31
	v_add_u32_e32 v56, s11, v3
	v_add_u32_e32 v58, s11, v5
	v_add_u32_e32 v60, s11, v6
	v_add_u32_e32 v62, s11, v7
	v_add_u32_e32 v64, s11, v8
	v_add_u32_e32 v66, s11, v9
	v_add_u32_e32 v68, s11, v10
	v_add_u32_e32 v77, s11, v11
	v_lshl_add_u64 v[54:55], s[8:9], 1, v[0:1]
	v_mad_i64_i32 v[56:57], s[8:9], v56, s54, v[54:55]
	v_mad_i64_i32 v[58:59], s[8:9], v58, s54, v[54:55]
	v_mad_i64_i32 v[60:61], s[8:9], v60, s54, v[54:55]
	v_mad_i64_i32 v[62:63], s[8:9], v62, s54, v[54:55]
	v_mad_i64_i32 v[64:65], s[8:9], v64, s54, v[54:55]
	v_mad_i64_i32 v[66:67], s[8:9], v66, s54, v[54:55]
	v_mad_i64_i32 v[68:69], s[8:9], v68, s54, v[54:55]
	v_mad_i64_i32 v[54:55], s[8:9], v77, s54, v[54:55]
	s_waitcnt vmcnt(8)
	s_branch .Lcv337_top

; __device__ __forceinline__ bf16_t f2bf(float f) { unsigned u = __float_as_uint(f); u += 0x7FFFu + ((u >> 16) & 1u); return (bf16_t)(u >> 16); }
;     ...
;     for (int t_ = first; t_ < ntile * ((REP & 1) + 1); t_ += gridDim.x) { const int t = t_ % ntile;
;         const int r0 = (t / nkt) * 64, k0 = (t % nkt) * 64;
;         __syncthreads();
; #pragma unroll
;         for (int i = 0; i < 8; ++i) { const int kk = i * 8 + w; tile[kk * 65 + lane] = src(k0 + kk, r0 + lane); }
;         __syncthreads();
; #pragma unroll
;         for (int i = 0; i < 8; ++i) { const int j = i * 8 + w; Bt[(size_t)(r0 + j) * ld + k0 + lane] = f2bf(tile[lane * 65 + j]); }
; __device__ void convert_phase(unsigned char* smem, const Params& p, int l) {
;     ...
;     { const float* wd = ((const float*)ldp(35)) + uo; conv_tiles(tile, wt + W_DN2, 1024, 2816, 97, [=](int k, int r) { return wd[(size_t)k * DM + r]; }); }
.Lcv337_top:
	s_barrier
	s_waitcnt vmcnt(23)
	ds_write_b32 v12, v13
	s_waitcnt vmcnt(22)
	ds_write_b32 v12, v30 offset:2080
	s_waitcnt vmcnt(21)
	ds_write_b32 v12, v31 offset:4160
	s_waitcnt vmcnt(20)
	ds_write_b32 v12, v32 offset:6240
	s_waitcnt vmcnt(19)
	ds_write_b32 v12, v33 offset:8320
	s_waitcnt vmcnt(18)
	ds_write_b32 v12, v34 offset:10400
	s_waitcnt vmcnt(17)
	ds_write_b32 v12, v35 offset:12480
	s_waitcnt vmcnt(16)
	ds_write_b32 v12, v36 offset:14560
	s_waitcnt lgkmcnt(0)
	s_barrier
	ds_read2_b32 v[30:31], v4 offset1:8
	ds_read2_b32 v[32:33], v4 offset0:16 offset1:24
	ds_read2_b32 v[34:35], v4 offset0:32 offset1:40
	ds_read2_b32 v[36:37], v4 offset0:48 offset1:56
	s_waitcnt lgkmcnt(3)
	v_bfe_u32 v13, v30, 16, 1
	v_bfe_u32 v38, v31, 16, 1
	s_waitcnt lgkmcnt(2)
	v_bfe_u32 v39, v32, 16, 1
	v_bfe_u32 v40, v33, 16, 1
	s_waitcnt lgkmcnt(1)
	v_bfe_u32 v41, v34, 16, 1
	v_bfe_u32 v42, v35, 16, 1
	s_waitcnt lgkmcnt(0)
	v_bfe_u32 v43, v36, 16, 1
	v_bfe_u32 v44, v37, 16, 1
	v_add3_u32 v13, v30, v13, s88
	v_add3_u32 v30, v31, v38, s88
	v_add3_u32 v31, v32, v39, s88
	v_add3_u32 v32, v33, v40, s88
	v_add3_u32 v33, v34, v41, s88
	v_add3_u32 v34, v35, v42, s88
	v_add3_u32 v35, v36, v43, s88
	v_add3_u32 v36, v37, v44, s88
	global_store_short_d16_hi v[16:17], v13, off
	global_store_short_d16_hi v[18:19], v30, off
	global_store_short_d16_hi v[20:21], v31, off
	global_store_short_d16_hi v[22:23], v32, off
	global_store_short_d16_hi v[24:25], v33, off
	global_store_short_d16_hi v[26:27], v34, off
	global_store_short_d16_hi v[28:29], v35, off
	global_store_short_d16_hi v[14:15], v36, off
	s_lshl_b32 s98, s5, 1
	s_add_i32 s98, s98, s10
	s_cmp_lt_i32 s98, 0x2c0
	s_cbranch_scc0 .Lcv337_s0
	s_mul_hi_i32 s8, s98, 0x2e8ba2e9
	s_lshr_b32 s9, s8, 31
	s_ashr_i32 s8, s8, 7
	s_add_i32 s8, s8, s9
	s_mulk_i32 s8, 0x2c0
	s_sub_i32 s8, s98, s8
	s_sext_i32_i16 s9, s8
	s_mulk_i32 s9, 0xba3
	s_lshr_b32 s11, s9, 31
	s_ashr_i32 s9, s9, 17
	s_add_i32 s9, s9, s11
	s_sext_i32_i16 s11, s9
	s_mul_i32 s9, s9, 44
	s_sub_i32 s8, s8, s9
	s_sext_i32_i16 s8, s8
	s_lshl_b32 s11, s11, 6
	s_lshl_b32 s8, s8, 6
	v_or_b32_e32 v14, s11, v2
	v_add_u32_e32 v16, s8, v3
	v_ashrrev_i32_e32 v15, 31, v14
	v_add_u32_e32 v18, s8, v5
	v_add_u32_e32 v20, s8, v6
	v_add_u32_e32 v22, s8, v7
	v_add_u32_e32 v24, s8, v8
	v_add_u32_e32 v26, s8, v9
	v_add_u32_e32 v28, s8, v10
	v_add_u32_e32 v30, s8, v11
	v_ashrrev_i32_e32 v17, 31, v16
	v_lshl_add_u64 v[14:15], v[14:15], 2, s[6:7]
	v_ashrrev_i32_e32 v19, 31, v18
	v_ashrrev_i32_e32 v21, 31, v20
	v_ashrrev_i32_e32 v23, 31, v22
	v_ashrrev_i32_e32 v25, 31, v24
	v_ashrrev_i32_e32 v27, 31, v26
	v_ashrrev_i32_e32 v29, 31, v28
	v_ashrrev_i32_e32 v31, 31, v30
	v_lshlrev_b64 v[16:17], 12, v[16:17]
	v_lshlrev_b64 v[18:19], 12, v[18:19]
	v_lshlrev_b64 v[20:21], 12, v[20:21]
	v_lshlrev_b64 v[22:23], 12, v[22:23]
	v_lshlrev_b64 v[24:25], 12, v[24:25]
	v_lshlrev_b64 v[26:27], 12, v[26:27]
	v_lshlrev_b64 v[28:29], 12, v[28:29]
	v_lshlrev_b64 v[30:31], 12, v[30:31]
	v_lshl_add_u64 v[16:17], v[14:15], 0, v[16:17]
	v_lshl_add_u64 v[18:19], v[14:15], 0, v[18:19]
	v_lshl_add_u64 v[20:21], v[14:15], 0, v[20:21]
	v_lshl_add_u64 v[22:23], v[14:15], 0, v[22:23]
	v_lshl_add_u64 v[24:25], v[14:15], 0, v[24:25]
	v_lshl_add_u64 v[26:27], v[14:15], 0, v[26:27]
	v_lshl_add_u64 v[28:29], v[14:15], 0, v[28:29]
	v_lshl_add_u64 v[14:15], v[14:15], 0, v[30:31]
	global_load_dword v13, v[16:17], off
	global_load_dword v30, v[18:19], off
	global_load_dword v31, v[20:21], off
	global_load_dword v32, v[22:23], off
	global_load_dword v33, v[24:25], off
	global_load_dword v34, v[26:27], off
	global_load_dword v35, v[28:29], off
	global_load_dword v36, v[14:15], off
	s_ashr_i32 s9, s8, 31
	v_add_u32_e32 v16, s11, v3
	v_add_u32_e32 v18, s11, v5
	v_add_u32_e32 v20, s11, v6
	v_add_u32_e32 v22, s11, v7
	v_add_u32_e32 v24, s11, v8
	v_add_u32_e32 v26, s11, v9
	v_add_u32_e32 v28, s11, v10
	v_add_u32_e32 v37, s11, v11
	v_lshl_add_u64 v[14:15], s[8:9], 1, v[0:1]
	v_mad_i64_i32 v[16:17], s[8:9], v16, s54, v[14:15]
	v_mad_i64_i32 v[18:19], s[8:9], v18, s54, v[14:15]
	v_mad_i64_i32 v[20:21], s[8:9], v20, s54, v[14:15]
	v_mad_i64_i32 v[22:23], s[8:9], v22, s54, v[14:15]
	v_mad_i64_i32 v[24:25], s[8:9], v24, s54, v[14:15]
	v_mad_i64_i32 v[26:27], s[8:9], v26, s54, v[14:15]
	v_mad_i64_i32 v[28:29], s[8:9], v28, s54, v[14:15]
	v_mad_i64_i32 v[14:15], s[8:9], v37, s54, v[14:15]
	s_branch .Lcv337_n0

; __device__ __forceinline__ bf16_t f2bf(float f) { unsigned u = __float_as_uint(f); u += 0x7FFFu + ((u >> 16) & 1u); return (bf16_t)(u >> 16); }
;     ...
;     for (int t_ = first; t_ < ntile * ((REP & 1) + 1); t_ += gridDim.x) { const int t = t_ % ntile;
;         const int r0 = (t / nkt) * 64, k0 = (t % nkt) * 64;
;         __syncthreads();
; #pragma unroll
;         for (int i = 0; i < 8; ++i) { const int kk = i * 8 + w; tile[kk * 65 + lane] = src(k0 + kk, r0 + lane); }
;         __syncthreads();
; #pragma unroll
;         for (int i = 0; i < 8; ++i) { const int j = i * 8 + w; Bt[(size_t)(r0 + j) * ld + k0 + lane] = f2bf(tile[lane * 65 + j]); }
; __device__ void convert_phase(unsigned char* smem, const Params& p, int l) {
;     ...
;     { const float* wd = ((const float*)ldp(35)) + uo; conv_tiles(tile, wt + W_DN2, 1024, 2816, 97, [=](int k, int r) { return wd[(size_t)k * DM + r]; }); }
.Lcv337_n0:
	s_add_i32 s10, s10, s5
	s_cmp_lt_i32 s10, 0x2c0
	s_cbranch_scc0 .LBB0_338
	s_barrier
	s_waitcnt vmcnt(23)
	ds_write_b32 v12, v53
	s_waitcnt vmcnt(22)
	ds_write_b32 v12, v70 offset:2080
	s_waitcnt vmcnt(21)
	ds_write_b32 v12, v71 offset:4160
	s_waitcnt vmcnt(20)
	ds_write_b32 v12, v72 offset:6240
	s_waitcnt vmcnt(19)
	ds_write_b32 v12, v73 offset:8320
	s_waitcnt vmcnt(18)
	ds_write_b32 v12, v74 offset:10400
	s_waitcnt vmcnt(17)
	ds_write_b32 v12, v75 offset:12480
	s_waitcnt vmcnt(16)
	ds_write_b32 v12, v76 offset:14560
	s_waitcnt lgkmcnt(0)
	s_barrier
	ds_read2_b32 v[70:71], v4 offset1:8
	ds_read2_b32 v[72:73], v4 offset0:16 offset1:24
	ds_read2_b32 v[74:75], v4 offset0:32 offset1:40
	ds_read2_b32 v[76:77], v4 offset0:48 offset1:56
	s_waitcnt lgkmcnt(3)
	v_bfe_u32 v53, v70, 16, 1
	v_bfe_u32 v78, v71, 16, 1
	s_waitcnt lgkmcnt(2)
	v_bfe_u32 v79, v72, 16, 1
	v_bfe_u32 v80, v73, 16, 1
	s_waitcnt lgkmcnt(1)
	v_bfe_u32 v81, v74, 16, 1
	v_bfe_u32 v82, v75, 16, 1
	s_waitcnt lgkmcnt(0)
	v_bfe_u32 v83, v76, 16, 1
	v_bfe_u32 v84, v77, 16, 1
	v_add3_u32 v53, v70, v53, s88
	v_add3_u32 v70, v71, v78, s88
	v_add3_u32 v71, v72, v79, s88
	v_add3_u32 v72, v73, v80, s88
	v_add3_u32 v73, v74, v81, s88
	v_add3_u32 v74, v75, v82, s88
	v_add3_u32 v75, v76, v83, s88
	v_add3_u32 v76, v77, v84, s88
	global_store_short_d16_hi v[56:57], v53, off
	global_store_short_d16_hi v[58:59], v70, off
	global_store_short_d16_hi v[60:61], v71, off
	global_store_short_d16_hi v[62:63], v72, off
	global_store_short_d16_hi v[64:65], v73, off
	global_store_short_d16_hi v[66:67], v74, off
	global_store_short_d16_hi v[68:69], v75, off
	global_store_short_d16_hi v[54:55], v76, off
	s_lshl_b32 s98, s5, 1
	s_add_i32 s98, s98, s10
	s_cmp_lt_i32 s98, 0x2c0
	s_cbranch_scc0 .Lcv337_s1
	s_mul_hi_i32 s8, s98, 0x2e8ba2e9
	s_lshr_b32 s9, s8, 31
	s_ashr_i32 s8, s8, 7
	s_add_i32 s8, s8, s9
	s_mulk_i32 s8, 0x2c0
	s_sub_i32 s8, s98, s8
	s_sext_i32_i16 s9, s8
	s_mulk_i32 s9, 0xba3
	s_lshr_b32 s11, s9, 31
	s_ashr_i32 s9, s9, 17
	s_add_i32 s9, s9, s11
	s_sext_i32_i16 s11, s9
	s_mul_i32 s9, s9, 44
	s_sub_i32 s8, s8, s9
	s_sext_i32_i16 s8, s8
	s_lshl_b32 s11, s11, 6
	s_lshl_b32 s8, s8, 6
	v_or_b32_e32 v54, s11, v2
	v_add_u32_e32 v56, s8, v3
	v_ashrrev_i32_e32 v55, 31, v54
	v_add_u32_e32 v58, s8, v5
	v_add_u32_e32 v60, s8, v6
	v_add_u32_e32 v62, s8, v7
	v_add_u32_e32 v64, s8, v8
	v_add_u32_e32 v66, s8, v9
	v_add_u32_e32 v68, s8, v10
	v_add_u32_e32 v70, s8, v11
	v_ashrrev_i32_e32 v57, 31, v56
	v_lshl_add_u64 v[54:55], v[54:55], 2, s[6:7]
	v_ashrrev_i32_e32 v59, 31, v58
	v_ashrrev_i32_e32 v61, 31, v60
	v_ashrrev_i32_e32 v63, 31, v62
	v_ashrrev_i32_e32 v65, 31, v64
	v_ashrrev_i32_e32 v67, 31, v66
	v_ashrrev_i32_e32 v69, 31, v68
	v_ashrrev_i32_e32 v71, 31, v70
	v_lshlrev_b64 v[56:57], 12, v[56:57]
	v_lshlrev_b64 v[58:59], 12, v[58:59]
	v_lshlrev_b64 v[60:61], 12, v[60:61]
	v_lshlrev_b64 v[62:63], 12, v[62:63]
	v_lshlrev_b64 v[64:65], 12, v[64:65]
	v_lshlrev_b64 v[66:67], 12, v[66:67]
	v_lshlrev_b64 v[68:69], 12, v[68:69]
	v_lshlrev_b64 v[70:71], 12, v[70:71]
	v_lshl_add_u64 v[56:57], v[54:55], 0, v[56:57]
	v_lshl_add_u64 v[58:59], v[54:55], 0, v[58:59]
	v_lshl_add_u64 v[60:61], v[54:55], 0, v[60:61]
	v_lshl_add_u64 v[62:63], v[54:55], 0, v[62:63]
	v_lshl_add_u64 v[64:65], v[54:55], 0, v[64:65]
	v_lshl_add_u64 v[66:67], v[54:55], 0, v[66:67]
	v_lshl_add_u64 v[68:69], v[54:55], 0, v[68:69]
	v_lshl_add_u64 v[54:55], v[54:55], 0, v[70:71]
	global_load_dword v53, v[56:57], off
	global_load_dword v70, v[58:59], off
	global_load_dword v71, v[60:61], off
	global_load_dword v72, v[62:63], off
	global_load_dword v73, v[64:65], off
	global_load_dword v74, v[66:67], off
	global_load_dword v75, v[68:69], off
	global_load_dword v76, v[54:55], off
	s_ashr_i32 s9, s8, 31
	v_add_u32_e32 v56, s11, v3
	v_add_u32_e32 v58, s11, v5
	v_add_u32_e32 v60, s11, v6
	v_add_u32_e32 v62, s11, v7
	v_add_u32_e32 v64, s11, v8
	v_add_u32_e32 v66, s11, v9
	v_add_u32_e32 v68, s11, v10
	v_add_u32_e32 v77, s11, v11
	v_lshl_add_u64 v[54:55], s[8:9], 1, v[0:1]
	v_mad_i64_i32 v[56:57], s[8:9], v56, s54, v[54:55]
	v_mad_i64_i32 v[58:59], s[8:9], v58, s54, v[54:55]
	v_mad_i64_i32 v[60:61], s[8:9], v60, s54, v[54:55]
	v_mad_i64_i32 v[62:63], s[8:9], v62, s54, v[54:55]
	v_mad_i64_i32 v[64:65], s[8:9], v64, s54, v[54:55]
	v_mad_i64_i32 v[66:67], s[8:9], v66, s54, v[54:55]
	v_mad_i64_i32 v[68:69], s[8:9], v68, s54, v[54:55]
	v_mad_i64_i32 v[54:55], s[8:9], v77, s54, v[54:55]
	s_branch .Lcv337_n1

;     ...
;     for (int t_ = first; t_ < ntile * ((REP & 1) + 1); t_ += gridDim.x) { const int t = t_ % ntile;
.Lcv337_n1:
	s_add_i32 s10, s10, s5
	s_cmp_lt_i32 s10, 0x2c0
	s_cbranch_scc1 .Lcv337_top
